# rmsnorm phases: loop-invariant gain vector loaded once before the row loop (was reloaded per row pair behind vmcnt(0) after each store pair)
# baseline (speedup 1.0000x reference)
; __device__ __forceinline__ unsigned pk2(float lo, float hi) { return f2bf(lo) | (f2bf(hi) << 16); }
; __device__ __forceinline__ void rms_rows2_to_bf16(const float* x0, const float* x1, const float* g, bf16* o0, bf16* o1, int lane) {
;     const f32x4* xr0 = (const f32x4*)x0 + lane; const f32x4* xr1 = (const f32x4*)x1 + lane; const f32x4* gr = (const f32x4*)g + lane;
;     f32x4 v[8], w[8]; float s = 0.f, t = 0.f;
; #pragma unroll
;     for (int j = 0; j < 8; ++j) { v[j] = xr0[64 * j]; w[j] = xr1[64 * j]; }
; #pragma unroll
;     for (int j = 0; j < 8; ++j) { s += (v[j].x * v[j].x + v[j].y * v[j].y) + (v[j].z * v[j].z + v[j].w * v[j].w); t += (w[j].x * w[j].x + w[j].y * w[j].y) + (w[j].z * w[j].z + w[j].w * w[j].w); }
;     const float rs = 1.f / sqrtf(wave_sum(s, lane) * (1.f / D) + NORM_EPS), rt = 1.f / sqrtf(wave_sum(t, lane) * (1.f / D) + NORM_EPS);
;     unsigned long long* p0 = (unsigned long long*)o0 + lane; unsigned long long* p1 = (unsigned long long*)o1 + lane;
; #pragma unroll
;     for (int j = 0; j < 8; ++j) { const f32x4 gg = gr[64 * j];
;         p0[64 * j] = (unsigned long long)pk2(v[j].x * rs * gg.x, v[j].y * rs * gg.y) | ((unsigned long long)pk2(v[j].z * rs * gg.z, v[j].w * rs * gg.w) << 32);
;         p1[64 * j] = (unsigned long long)pk2(w[j].x * rt * gg.x, w[j].y * rt * gg.y) | ((unsigned long long)pk2(w[j].z * rt * gg.z, w[j].w * rt * gg.w) << 32); }
; }
; __global__ void __launch_bounds__(NWAVES * 64, 2) mega_fwd(Args args) {
;     ...
;         for (int m = gw; m < M / 2; m += NGW) rms_rows2_to_bf16(x + (size_t)m * D, x + (size_t)(m + M / 2) * D, ln_mix, XN + (size_t)m * D, XN + (size_t)(m + M / 2) * D, lane);
.LBB0_40:
	s_cmpk_gt_i32 s14, 0x1fff
	s_cbranch_scc1 .LBB0_43
	v_lshlrev_b32_e32 v66, 4, v7
	v_mov_b32_e32 v67, 0
	s_waitcnt lgkmcnt(0)
	v_lshl_add_u64 v[68:69], s[38:39], 0, v[66:67]
	s_mov_b64 s[0:1], 0x1000
	v_lshl_add_u64 v[70:71], v[68:69], 0, s[0:1]
	s_mov_b64 s[0:1], 0x1400
	v_lshl_add_u64 v[72:73], v[68:69], 0, s[0:1]
	s_mov_b64 s[0:1], 0x1800
	v_lshl_add_u64 v[74:75], v[68:69], 0, s[0:1]
	s_mov_b64 s[0:1], 0x1c00
	v_lshl_add_u64 v[76:77], v[68:69], 0, s[0:1]
	s_add_i32 s0, s14, 0x2000
	s_ashr_i32 s1, s0, 31
	s_lshl_b64 s[4:5], s[0:1], 12
	s_add_u32 s24, s54, s4
	s_addc_u32 s25, s55, s5
	s_ashr_i32 s35, s34, 31
	s_lshl_b64 s[26:27], s[34:35], 12
	s_lshl_b64 s[0:1], s[0:1], 13
	s_add_u32 s28, s36, s0
	s_addc_u32 s29, s37, s1
	s_ashr_i32 s15, s14, 31
	s_lshl_b64 s[42:43], s[34:35], 13
	s_lshl_b64 s[0:1], s[14:15], 13
	s_add_u32 s46, s36, s0
	s_addc_u32 s47, s37, s1
	s_lshl_b64 s[0:1], s[14:15], 12
	v_lshlrev_b32_e32 v2, 2, v7
	s_add_u32 s48, s54, s0
	v_xor_b32_e32 v1, 4, v2
	v_xor_b32_e32 v84, 8, v2
	v_xor_b32_e32 v85, 16, v2
	v_xor_b32_e32 v86, 32, v2
	v_xor_b32_e32 v87, 64, v2
	v_xor_b32_e32 v88, 0x80, v2
	v_lshlrev_b32_e32 v78, 3, v7
	v_mov_b32_e32 v79, v67
	s_addc_u32 s49, s55, s1
	s_movk_i32 s3, 0x1000
	v_mov_b32_e32 v89, 0x358637bd
	s_mov_b32 s15, 0xf800000
	v_mov_b32_e32 v90, 0x260
	s_movk_i32 s33, 0x7fff
	s_mov_b32 s35, 0xffff0000
	s_brev_b32 s60, 48
	global_load_dwordx4 v[200:203], v[68:69], off
	global_load_dwordx4 v[204:207], v[68:69], off offset:1024
	global_load_dwordx4 v[208:211], v[68:69], off offset:2048
	global_load_dwordx4 v[212:215], v[68:69], off offset:3072
	global_load_dwordx4 v[216:219], v[70:71], off
	global_load_dwordx4 v[220:223], v[72:73], off
	global_load_dwordx4 v[224:227], v[74:75], off
	global_load_dwordx4 v[228:231], v[76:77], off
	s_waitcnt vmcnt(0)
.LBB0_42:
	v_lshl_add_u64 v[2:3], s[46:47], 0, v[66:67]
	v_lshl_add_u64 v[6:7], s[28:29], 0, v[66:67]
	v_lshl_add_u64 v[4:5], s[48:49], 0, v[78:79]
	s_nop 1
	v_mov_b32_e32 v18, v200
	v_mov_b32_e32 v19, v201
	v_mov_b32_e32 v20, v202
	v_mov_b32_e32 v21, v203
	global_load_dwordx4 v[94:97], v[2:3], off
	global_load_dwordx4 v[34:37], v[6:7], off
	global_load_dwordx4 v[62:65], v[2:3], off offset:1024
	global_load_dwordx4 v[30:33], v[6:7], off offset:1024
	global_load_dwordx4 v[58:61], v[2:3], off offset:2048
	global_load_dwordx4 v[26:29], v[6:7], off offset:2048
	global_load_dwordx4 v[50:53], v[2:3], off offset:3072
	global_load_dwordx4 v[22:25], v[6:7], off offset:3072
	v_add_co_u32_e32 v2, vcc, s3, v2
	v_add_co_u32_e64 v80, s[0:1], s60, v4
	s_nop 0
	v_addc_co_u32_e32 v3, vcc, 0, v3, vcc
	v_lshl_add_u64 v[8:9], s[24:25], 0, v[78:79]
	v_addc_co_u32_e64 v81, s[0:1], 0, v5, s[0:1]
	v_add_co_u32_e32 v6, vcc, s3, v6
	v_add_co_u32_e64 v82, s[0:1], s60, v8
	global_load_dwordx4 v[54:57], v[2:3], off
	global_load_dwordx4 v[46:49], v[2:3], off offset:1024
	global_load_dwordx4 v[14:17], v[2:3], off offset:2048
	s_nop 0
	global_load_dwordx4 v[2:5], v[2:3], off offset:3072
	v_addc_co_u32_e32 v7, vcc, 0, v7, vcc
	v_addc_co_u32_e64 v83, s[0:1], 0, v9, s[0:1]
	global_load_dwordx4 v[42:45], v[6:7], off
	global_load_dwordx4 v[38:41], v[6:7], off offset:1024
	global_load_dwordx4 v[10:13], v[6:7], off offset:2048
	s_nop 0
	global_load_dwordx4 v[6:9], v[6:7], off offset:3072
	s_add_i32 s14, s14, s34
	s_add_u32 s24, s24, s26
	s_addc_u32 s25, s25, s27
	s_add_u32 s28, s28, s42
	s_addc_u32 s29, s29, s43
	s_add_u32 s46, s46, s42
	s_addc_u32 s47, s47, s43
	s_add_u32 s48, s48, s26
	s_addc_u32 s49, s49, s27
	s_cmpk_gt_i32 s14, 0x1fff
	s_waitcnt vmcnt(15)
	v_mul_f32_e32 v91, v95, v95
	v_mul_f32_e32 v92, v97, v97
	s_waitcnt vmcnt(14)
	v_mul_f32_e32 v93, v35, v35
	v_mul_f32_e32 v98, v37, v37
	s_waitcnt vmcnt(13)
	v_mul_f32_e32 v99, v63, v63
	v_mul_f32_e32 v100, v65, v65
	s_waitcnt vmcnt(12)
	v_mul_f32_e32 v101, v31, v31
	v_mul_f32_e32 v102, v33, v33
	s_waitcnt vmcnt(11)
	v_mul_f32_e32 v103, v59, v59
	v_mul_f32_e32 v104, v61, v61
	v_fmac_f32_e32 v91, v94, v94
	v_fmac_f32_e32 v92, v96, v96
	v_fmac_f32_e32 v93, v34, v34
	v_fmac_f32_e32 v98, v36, v36
	v_fmac_f32_e32 v99, v62, v62
	v_fmac_f32_e32 v100, v64, v64
	s_waitcnt vmcnt(10)
	v_mul_f32_e32 v105, v27, v27
	v_mul_f32_e32 v106, v29, v29
	s_waitcnt vmcnt(9)
	v_mul_f32_e32 v107, v51, v51
	v_mul_f32_e32 v108, v53, v53
	v_fmac_f32_e32 v101, v30, v30
	v_fmac_f32_e32 v102, v32, v32
	v_fmac_f32_e32 v103, v58, v58
	v_fmac_f32_e32 v104, v60, v60
	v_add_f32_e32 v91, v91, v92
	v_add_f32_e32 v92, v93, v98
	v_add_f32_e32 v93, v99, v100
	s_waitcnt vmcnt(8)
	v_mul_f32_e32 v109, v23, v23
	v_mul_f32_e32 v110, v25, v25
	v_fmac_f32_e32 v105, v26, v26
	v_fmac_f32_e32 v106, v28, v28
	v_fmac_f32_e32 v107, v50, v50
	v_fmac_f32_e32 v108, v52, v52
	v_add_f32_e32 v98, v101, v102
	v_add_f32_e32 v99, v103, v104
	s_waitcnt vmcnt(7)
	v_mul_f32_e32 v103, v55, v55
	v_mul_f32_e32 v104, v57, v57
	v_add_f32_e32 v91, v91, v93
	v_fmac_f32_e32 v109, v22, v22
	v_fmac_f32_e32 v110, v24, v24
	v_add_f32_e32 v100, v105, v106
	v_add_f32_e32 v101, v107, v108
	s_waitcnt vmcnt(6)
	v_mul_f32_e32 v105, v47, v47
	v_mul_f32_e32 v106, v49, v49
	v_add_f32_e32 v92, v92, v98
	v_fmac_f32_e32 v103, v54, v54
	v_fmac_f32_e32 v104, v56, v56
	s_waitcnt vmcnt(3)
	v_mul_f32_e32 v93, v43, v43
	v_mul_f32_e32 v98, v45, v45
	v_add_f32_e32 v91, v91, v99
	v_add_f32_e32 v102, v109, v110
	v_mul_f32_e32 v107, v15, v15
	v_mul_f32_e32 v108, v17, v17
	v_fmac_f32_e32 v105, v46, v46
	v_fmac_f32_e32 v106, v48, v48
	s_waitcnt vmcnt(2)
	v_mul_f32_e32 v111, v39, v39
	v_mul_f32_e32 v112, v41, v41
	v_add_f32_e32 v92, v92, v100
	v_add_f32_e32 v99, v103, v104
	v_fmac_f32_e32 v93, v42, v42
	v_fmac_f32_e32 v98, v44, v44
	v_add_f32_e32 v91, v91, v101
	v_mul_f32_e32 v109, v3, v3
	v_mul_f32_e32 v110, v5, v5
	v_fmac_f32_e32 v107, v14, v14
	v_fmac_f32_e32 v108, v16, v16
	s_waitcnt vmcnt(1)
; __device__ __forceinline__ unsigned pk2(float lo, float hi) { return f2bf(lo) | (f2bf(hi) << 16); }
; __device__ __forceinline__ void rms_rows2_to_bf16(const float* x0, const float* x1, const float* g, bf16* o0, bf16* o1, int lane) {
;     ...
;     const float rs = 1.f / sqrtf(wave_sum(s, lane) * (1.f / D) + NORM_EPS), rt = 1.f / sqrtf(wave_sum(t, lane) * (1.f / D) + NORM_EPS);
;     unsigned long long* p0 = (unsigned long long*)o0 + lane; unsigned long long* p1 = (unsigned long long*)o1 + lane;
; #pragma unroll
;     for (int j = 0; j < 8; ++j) { const f32x4 gg = gr[64 * j];
;         p0[64 * j] = (unsigned long long)pk2(v[j].x * rs * gg.x, v[j].y * rs * gg.y) | ((unsigned long long)pk2(v[j].z * rs * gg.z, v[j].w * rs * gg.w) << 32);
;         p1[64 * j] = (unsigned long long)pk2(w[j].x * rt * gg.x, w[j].y * rt * gg.y) | ((unsigned long long)pk2(w[j].z * rt * gg.z, w[j].w * rt * gg.w) << 32); }
	v_mul_f32_e32 v113, v11, v11
	v_mul_f32_e32 v114, v13, v13
	v_add_f32_e32 v100, v105, v106
	v_fmac_f32_e32 v111, v38, v38
	v_fmac_f32_e32 v112, v40, v40
	v_add_f32_e32 v92, v92, v102
	v_add_f32_e32 v93, v93, v98
	v_add_f32_e32 v91, v91, v99
	v_fmac_f32_e32 v109, v2, v2
	v_fmac_f32_e32 v110, v4, v4
	s_waitcnt vmcnt(0)
	v_mul_f32_e32 v115, v7, v7
	v_mul_f32_e32 v116, v9, v9
	v_add_f32_e32 v103, v107, v108
	v_fmac_f32_e32 v113, v10, v10
	v_fmac_f32_e32 v114, v12, v12
	v_add_f32_e32 v98, v111, v112
	v_add_f32_e32 v92, v92, v93
	v_add_f32_e32 v91, v91, v100
	v_add_f32_e32 v104, v109, v110
	v_fmac_f32_e32 v115, v6, v6
	v_fmac_f32_e32 v116, v8, v8
	v_add_f32_e32 v101, v113, v114
	v_add_f32_e32 v92, v92, v98
	v_add_f32_e32 v91, v91, v103
	v_add_f32_e32 v102, v115, v116
	v_add_f32_e32 v92, v92, v101
	v_add_f32_e32 v91, v91, v104
	v_add_f32_e32 v92, v92, v102
	ds_bpermute_b32 v93, v1, v91
	ds_bpermute_b32 v98, v1, v92
	s_waitcnt lgkmcnt(1)
	v_add_f32_e32 v91, v91, v93
	s_waitcnt lgkmcnt(0)
	v_add_f32_e32 v92, v92, v98
	ds_bpermute_b32 v93, v84, v91
	ds_bpermute_b32 v98, v84, v92
	s_waitcnt lgkmcnt(1)
	v_add_f32_e32 v91, v91, v93
	s_waitcnt lgkmcnt(0)
	v_add_f32_e32 v92, v92, v98
	ds_bpermute_b32 v93, v85, v91
	ds_bpermute_b32 v98, v85, v92
	s_waitcnt lgkmcnt(1)
	v_add_f32_e32 v91, v91, v93
	s_waitcnt lgkmcnt(0)
	v_add_f32_e32 v92, v92, v98
	ds_bpermute_b32 v93, v86, v91
	ds_bpermute_b32 v98, v86, v92
	s_waitcnt lgkmcnt(1)
	v_add_f32_e32 v91, v91, v93
	s_waitcnt lgkmcnt(0)
	v_add_f32_e32 v92, v92, v98
	ds_bpermute_b32 v93, v87, v91
	ds_bpermute_b32 v98, v87, v92
	s_waitcnt lgkmcnt(1)
	v_add_f32_e32 v91, v91, v93
	s_waitcnt lgkmcnt(0)
	v_add_f32_e32 v92, v92, v98
	ds_bpermute_b32 v93, v88, v91
	ds_bpermute_b32 v98, v88, v92
	s_waitcnt lgkmcnt(1)
	v_add_f32_e32 v91, v91, v93
	s_waitcnt lgkmcnt(0)
	v_add_f32_e32 v92, v92, v98
	v_fmamk_f32 v91, v91, 0x3a000000, v89
	v_fmamk_f32 v92, v92, 0x3a000000, v89
	v_mul_f32_e32 v93, 0x4f800000, v91
	v_cmp_gt_f32_e64 s[0:1], s15, v91
	v_mul_f32_e32 v98, 0x4f800000, v92
	v_cmp_gt_f32_e32 vcc, s15, v92
	v_cndmask_b32_e64 v91, v91, v93, s[0:1]
	v_sqrt_f32_e32 v93, v91
	v_cndmask_b32_e32 v92, v92, v98, vcc
	v_sqrt_f32_e32 v98, v92
	v_add_u32_e32 v99, -1, v93
	v_add_u32_e32 v100, 1, v93
	v_add_u32_e32 v101, -1, v98
	v_fma_f32 v103, -v99, v93, v91
	v_add_u32_e32 v102, 1, v98
	v_fma_f32 v104, -v100, v93, v91
	v_fma_f32 v105, -v101, v98, v92
	v_cmp_ge_f32_e64 s[4:5], 0, v103
	v_fma_f32 v106, -v102, v98, v92
	v_cmp_lt_f32_e64 s[6:7], 0, v104
	v_cndmask_b32_e64 v93, v93, v99, s[4:5]
	v_cmp_ge_f32_e64 s[4:5], 0, v105
	v_cndmask_b32_e64 v93, v93, v100, s[6:7]
	v_mul_f32_e32 v99, 0x37800000, v93
	v_cndmask_b32_e64 v98, v98, v101, s[4:5]
	v_cmp_lt_f32_e64 s[4:5], 0, v106
	v_cndmask_b32_e64 v93, v93, v99, s[0:1]
	v_cmp_class_f32_e64 s[0:1], v91, v90
	v_cndmask_b32_e64 v98, v98, v102, s[4:5]
	v_mul_f32_e32 v100, 0x37800000, v98
	v_cndmask_b32_e32 v98, v98, v100, vcc
	v_cmp_class_f32_e32 vcc, v92, v90
	v_cndmask_b32_e64 v91, v93, v91, s[0:1]
	s_nop 0
	v_cndmask_b32_e32 v93, v98, v92, vcc
	v_div_scale_f32 v92, s[0:1], v91, v91, 1.0
	v_div_scale_f32 v99, s[0:1], v93, v93, 1.0
	v_rcp_f32_e32 v101, v92
	v_rcp_f32_e32 v102, v99
	v_div_scale_f32 v98, vcc, 1.0, v91, 1.0
	v_fma_f32 v103, -v92, v101, 1.0
	v_fma_f32 v104, -v99, v102, 1.0
	v_fmac_f32_e32 v101, v103, v101
	v_div_scale_f32 v100, s[0:1], 1.0, v93, 1.0
	v_fmac_f32_e32 v102, v104, v102
	v_mul_f32_e32 v103, v98, v101
	v_mul_f32_e32 v104, v100, v102
	v_fma_f32 v105, -v92, v103, v98
	v_fma_f32 v106, -v99, v104, v100
	v_fmac_f32_e32 v103, v105, v101
	v_fmac_f32_e32 v104, v106, v102
	v_fma_f32 v92, -v92, v103, v98
	v_fma_f32 v98, -v99, v104, v100
	v_div_fmas_f32 v92, v92, v101, v103
	s_mov_b64 vcc, s[0:1]
	v_div_fixup_f32 v92, v92, v91, 1.0
	v_div_fmas_f32 v91, v98, v102, v104
	v_div_fixup_f32 v91, v91, v93, 1.0
	v_mul_f32_e32 v93, v94, v92
	v_mul_f32_e32 v94, v95, v92
	v_mul_f32_e32 v95, v96, v92
	v_mul_f32_e32 v96, v97, v92
	v_mul_f32_e32 v93, v18, v93
	v_mul_f32_e32 v95, v20, v95
	v_mul_f32_e32 v34, v34, v91
	v_mul_f32_e32 v36, v36, v91
	v_mul_f32_e32 v94, v19, v94
	v_mul_f32_e32 v96, v21, v96
	v_mul_f32_e32 v35, v35, v91
	v_mul_f32_e32 v37, v37, v91
	v_bfe_u32 v97, v93, 16, 1
	v_bfe_u32 v99, v95, 16, 1
	v_mul_f32_e32 v18, v18, v34
	v_mul_f32_e32 v20, v20, v36
	v_bfe_u32 v98, v94, 16, 1
	v_bfe_u32 v100, v96, 16, 1
	v_mul_f32_e32 v19, v19, v35
	v_mul_f32_e32 v21, v21, v37
	v_add3_u32 v34, v93, v97, s33
	v_add3_u32 v36, v95, v99, s33
	v_bfe_u32 v93, v18, 16, 1
	v_bfe_u32 v95, v20, 16, 1
	v_add3_u32 v35, v94, v98, s33
	v_add3_u32 v37, v96, v100, s33
	v_bfe_u32 v94, v19, 16, 1
	v_bfe_u32 v96, v21, 16, 1
	v_lshrrev_b32_e32 v34, 16, v34
	v_lshrrev_b32_e32 v36, 16, v36
	v_add3_u32 v93, v18, v93, s33
	v_add3_u32 v20, v20, v95, s33
	v_add3_u32 v94, v19, v94, s33
	v_add3_u32 v21, v21, v96, s33
	v_and_or_b32 v18, v35, s35, v34
	v_and_or_b32 v19, v37, s35, v36
	v_lshrrev_b32_e32 v34, 16, v93
	v_lshrrev_b32_e32 v20, 16, v20
	global_store_dwordx2 v[80:81], v[18:19], off
	v_and_or_b32 v18, v94, s35, v34
	v_and_or_b32 v19, v21, s35, v20
	global_store_dwordx2 v[82:83], v[18:19], off
	s_nop 1
	v_mov_b32_e32 v18, v204
	v_mov_b32_e32 v19, v205
	v_mov_b32_e32 v20, v206
	v_mov_b32_e32 v21, v207
	v_mul_f32_e32 v62, v62, v92
	v_mul_f32_e32 v64, v64, v92
	v_mul_f32_e32 v63, v63, v92
	v_mul_f32_e32 v65, v65, v92
	v_mul_f32_e32 v30, v30, v91
	v_mul_f32_e32 v31, v31, v91
	v_mul_f32_e32 v32, v32, v91
	v_mul_f32_e32 v33, v33, v91
	v_mul_f32_e32 v58, v58, v92
	v_mul_f32_e32 v60, v60, v92
	v_mul_f32_e32 v59, v59, v92
	v_mul_f32_e32 v61, v61, v92
	v_mul_f32_e32 v26, v26, v91
	v_mul_f32_e32 v27, v27, v91
; __device__ __forceinline__ unsigned pk2(float lo, float hi) { return f2bf(lo) | (f2bf(hi) << 16); }
; __device__ __forceinline__ void rms_rows2_to_bf16(const float* x0, const float* x1, const float* g, bf16* o0, bf16* o1, int lane) {
;     ...
;     for (int j = 0; j < 8; ++j) { const f32x4 gg = gr[64 * j];
;         p0[64 * j] = (unsigned long long)pk2(v[j].x * rs * gg.x, v[j].y * rs * gg.y) | ((unsigned long long)pk2(v[j].z * rs * gg.z, v[j].w * rs * gg.w) << 32);
;         p1[64 * j] = (unsigned long long)pk2(w[j].x * rt * gg.x, w[j].y * rt * gg.y) | ((unsigned long long)pk2(w[j].z * rt * gg.z, w[j].w * rt * gg.w) << 32); }
	v_mul_f32_e32 v28, v28, v91
	v_mul_f32_e32 v29, v29, v91
	v_mul_f32_e32 v50, v50, v92
	v_mul_f32_e32 v52, v52, v92
	v_mul_f32_e32 v51, v51, v92
	v_mul_f32_e32 v53, v53, v92
	v_mul_f32_e32 v22, v22, v91
	v_mul_f32_e32 v23, v23, v91
	v_mul_f32_e32 v24, v24, v91
	v_mul_f32_e32 v25, v25, v91
	v_mul_f32_e32 v54, v54, v92
	v_mul_f32_e32 v56, v56, v92
	v_mul_f32_e32 v55, v55, v92
	v_mul_f32_e32 v57, v57, v92
	v_mul_f32_e32 v42, v42, v91
	v_mul_f32_e32 v43, v43, v91
	v_mul_f32_e32 v44, v44, v91
	v_mul_f32_e32 v45, v45, v91
	v_mul_f32_e32 v46, v46, v92
	v_mul_f32_e32 v48, v48, v92
	v_mul_f32_e32 v47, v47, v92
	v_mul_f32_e32 v49, v49, v92
	v_mul_f32_e32 v38, v38, v91
	v_mul_f32_e32 v39, v39, v91
	v_mul_f32_e32 v40, v40, v91
	v_mul_f32_e32 v41, v41, v91
	v_mul_f32_e32 v14, v14, v92
	v_mul_f32_e32 v16, v16, v92
	v_mul_f32_e32 v15, v15, v92
	v_mul_f32_e32 v17, v17, v92
	v_mul_f32_e32 v10, v10, v91
	v_mul_f32_e32 v11, v11, v91
	v_mul_f32_e32 v12, v12, v91
	v_mul_f32_e32 v13, v13, v91
	v_mul_f32_e32 v2, v2, v92
	v_mul_f32_e32 v4, v4, v92
	v_mul_f32_e32 v3, v3, v92
	v_mul_f32_e32 v5, v5, v92
	v_mul_f32_e32 v6, v6, v91
	v_mul_f32_e32 v8, v8, v91
	v_mul_f32_e32 v7, v7, v91
	v_mul_f32_e32 v9, v9, v91
	v_mul_f32_e32 v34, v62, v18
	v_mul_f32_e32 v36, v64, v20
	v_mul_f32_e32 v35, v63, v19
	v_mul_f32_e32 v37, v65, v21
	v_mul_f32_e32 v18, v18, v30
	v_mul_f32_e32 v19, v19, v31
	v_mul_f32_e32 v20, v20, v32
	v_bfe_u32 v30, v34, 16, 1
	v_bfe_u32 v32, v36, 16, 1
	v_mul_f32_e32 v21, v21, v33
	v_bfe_u32 v31, v35, 16, 1
	v_bfe_u32 v33, v37, 16, 1
	v_bfe_u32 v62, v18, 16, 1
	v_bfe_u32 v63, v19, 16, 1
	v_bfe_u32 v64, v20, 16, 1
	v_add3_u32 v30, v34, v30, s33
	v_add3_u32 v32, v36, v32, s33
	v_bfe_u32 v65, v21, 16, 1
	v_add3_u32 v31, v35, v31, s33
	v_add3_u32 v33, v37, v33, s33
	v_add3_u32 v18, v18, v62, s33
	v_add3_u32 v34, v19, v63, s33
	v_add3_u32 v19, v20, v64, s33
	v_lshrrev_b32_e32 v20, 16, v30
	v_lshrrev_b32_e32 v30, 16, v32
	v_add3_u32 v21, v21, v65, s33
	v_lshrrev_b32_e32 v32, 16, v18
	v_lshrrev_b32_e32 v35, 16, v19
	v_and_or_b32 v18, v31, s35, v20
	v_and_or_b32 v19, v33, s35, v30
	v_and_or_b32 v20, v34, s35, v32
	v_and_or_b32 v21, v21, s35, v35
	global_store_dwordx2 v[80:81], v[18:19], off offset:512
	global_store_dwordx2 v[82:83], v[20:21], off offset:512
	s_nop 1
	v_mov_b32_e32 v18, v208
	v_mov_b32_e32 v19, v209
	v_mov_b32_e32 v20, v210
	v_mov_b32_e32 v21, v211
	v_mul_f32_e32 v30, v58, v18
	v_mul_f32_e32 v32, v60, v20
	v_mul_f32_e32 v31, v59, v19
	v_mul_f32_e32 v33, v61, v21
	v_mul_f32_e32 v18, v26, v18
	v_mul_f32_e32 v19, v27, v19
	v_mul_f32_e32 v20, v28, v20
	v_bfe_u32 v26, v30, 16, 1
	v_bfe_u32 v28, v32, 16, 1
	v_mul_f32_e32 v21, v29, v21
	v_bfe_u32 v27, v31, 16, 1
	v_bfe_u32 v29, v33, 16, 1
	v_bfe_u32 v34, v18, 16, 1
	v_bfe_u32 v35, v19, 16, 1
	v_bfe_u32 v36, v20, 16, 1
	v_add3_u32 v26, v30, v26, s33
	v_add3_u32 v28, v32, v28, s33
	v_bfe_u32 v37, v21, 16, 1
	v_add3_u32 v27, v31, v27, s33
	v_add3_u32 v29, v33, v29, s33
	v_add3_u32 v18, v18, v34, s33
	v_add3_u32 v30, v19, v35, s33
	v_add3_u32 v19, v20, v36, s33
	v_lshrrev_b32_e32 v20, 16, v26
	v_lshrrev_b32_e32 v26, 16, v28
	v_add3_u32 v21, v21, v37, s33
	v_lshrrev_b32_e32 v28, 16, v18
	v_lshrrev_b32_e32 v31, 16, v19
	v_and_or_b32 v18, v27, s35, v20
	v_and_or_b32 v19, v29, s35, v26
	v_and_or_b32 v20, v30, s35, v28
	v_and_or_b32 v21, v21, s35, v31
	global_store_dwordx2 v[80:81], v[18:19], off offset:1024
	global_store_dwordx2 v[82:83], v[20:21], off offset:1024
	s_nop 1
	v_mov_b32_e32 v18, v212
	v_mov_b32_e32 v19, v213
	v_mov_b32_e32 v20, v214
	v_mov_b32_e32 v21, v215
	v_mul_f32_e32 v26, v50, v18
	v_mul_f32_e32 v28, v52, v20
	v_mul_f32_e32 v27, v51, v19
	v_mul_f32_e32 v29, v53, v21
	v_mul_f32_e32 v18, v22, v18
	v_mul_f32_e32 v19, v23, v19
	v_mul_f32_e32 v20, v24, v20
	v_bfe_u32 v22, v26, 16, 1
	v_bfe_u32 v24, v28, 16, 1
	v_mul_f32_e32 v21, v25, v21
	v_bfe_u32 v23, v27, 16, 1
	v_bfe_u32 v25, v29, 16, 1
	v_bfe_u32 v30, v18, 16, 1
	v_bfe_u32 v31, v19, 16, 1
	v_bfe_u32 v32, v20, 16, 1
	v_add3_u32 v22, v26, v22, s33
	v_add3_u32 v24, v28, v24, s33
	v_bfe_u32 v33, v21, 16, 1
	v_add3_u32 v23, v27, v23, s33
	v_add3_u32 v25, v29, v25, s33
	v_add3_u32 v18, v18, v30, s33
	v_add3_u32 v26, v19, v31, s33
	v_add3_u32 v19, v20, v32, s33
	v_lshrrev_b32_e32 v20, 16, v22
	v_lshrrev_b32_e32 v22, 16, v24
	v_add3_u32 v21, v21, v33, s33
	v_lshrrev_b32_e32 v24, 16, v18
	v_lshrrev_b32_e32 v27, 16, v19
	v_and_or_b32 v18, v23, s35, v20
	v_and_or_b32 v19, v25, s35, v22
	v_and_or_b32 v20, v26, s35, v24
	v_and_or_b32 v21, v21, s35, v27
	global_store_dwordx2 v[80:81], v[18:19], off offset:1536
	global_store_dwordx2 v[82:83], v[20:21], off offset:1536
	s_nop 1
	v_mov_b32_e32 v18, v216
; __device__ __forceinline__ unsigned pk2(float lo, float hi) { return f2bf(lo) | (f2bf(hi) << 16); }
; __device__ __forceinline__ void rms_rows2_to_bf16(const float* x0, const float* x1, const float* g, bf16* o0, bf16* o1, int lane) {
;     ...
;     for (int j = 0; j < 8; ++j) { const f32x4 gg = gr[64 * j];
;         p0[64 * j] = (unsigned long long)pk2(v[j].x * rs * gg.x, v[j].y * rs * gg.y) | ((unsigned long long)pk2(v[j].z * rs * gg.z, v[j].w * rs * gg.w) << 32);
;         p1[64 * j] = (unsigned long long)pk2(w[j].x * rt * gg.x, w[j].y * rt * gg.y) | ((unsigned long long)pk2(w[j].z * rt * gg.z, w[j].w * rt * gg.w) << 32); }
	v_mov_b32_e32 v19, v217
	v_mov_b32_e32 v20, v218
	v_mov_b32_e32 v21, v219
	v_mul_f32_e32 v22, v54, v18
	v_mul_f32_e32 v24, v56, v20
	v_mul_f32_e32 v23, v55, v19
	v_mul_f32_e32 v25, v57, v21
	v_mul_f32_e32 v18, v42, v18
	v_mul_f32_e32 v19, v43, v19
	v_mul_f32_e32 v20, v44, v20
	v_bfe_u32 v26, v22, 16, 1
	v_bfe_u32 v28, v24, 16, 1
	v_mul_f32_e32 v21, v45, v21
	v_bfe_u32 v27, v23, 16, 1
	v_bfe_u32 v29, v25, 16, 1
	v_bfe_u32 v30, v18, 16, 1
	v_bfe_u32 v31, v19, 16, 1
	v_bfe_u32 v32, v20, 16, 1
	v_add3_u32 v22, v22, v26, s33
	v_add3_u32 v24, v24, v28, s33
	v_bfe_u32 v33, v21, 16, 1
	v_add3_u32 v23, v23, v27, s33
	v_add3_u32 v25, v25, v29, s33
	v_add3_u32 v18, v18, v30, s33
	v_add3_u32 v26, v19, v31, s33
	v_add3_u32 v19, v20, v32, s33
	v_lshrrev_b32_e32 v20, 16, v22
	v_lshrrev_b32_e32 v22, 16, v24
	v_add3_u32 v21, v21, v33, s33
	v_lshrrev_b32_e32 v24, 16, v18
	v_lshrrev_b32_e32 v27, 16, v19
	v_and_or_b32 v18, v23, s35, v20
	v_and_or_b32 v19, v25, s35, v22
	v_and_or_b32 v20, v26, s35, v24
	v_and_or_b32 v21, v21, s35, v27
	global_store_dwordx2 v[80:81], v[18:19], off offset:2048
	global_store_dwordx2 v[82:83], v[20:21], off offset:2048
	s_nop 1
	v_mov_b32_e32 v18, v220
	v_mov_b32_e32 v19, v221
	v_mov_b32_e32 v20, v222
	v_mov_b32_e32 v21, v223
	v_mul_f32_e32 v22, v46, v18
	v_mul_f32_e32 v24, v48, v20
	v_mul_f32_e32 v23, v47, v19
	v_mul_f32_e32 v25, v49, v21
	v_mul_f32_e32 v18, v38, v18
	v_mul_f32_e32 v19, v39, v19
	v_mul_f32_e32 v20, v40, v20
	v_bfe_u32 v26, v22, 16, 1
	v_bfe_u32 v28, v24, 16, 1
	v_mul_f32_e32 v21, v41, v21
	v_bfe_u32 v27, v23, 16, 1
	v_bfe_u32 v29, v25, 16, 1
	v_bfe_u32 v30, v18, 16, 1
	v_bfe_u32 v31, v19, 16, 1
	v_bfe_u32 v32, v20, 16, 1
	v_add3_u32 v22, v22, v26, s33
	v_add3_u32 v24, v24, v28, s33
	v_bfe_u32 v33, v21, 16, 1
	v_add3_u32 v23, v23, v27, s33
	v_add3_u32 v25, v25, v29, s33
	v_add3_u32 v18, v18, v30, s33
	v_add3_u32 v26, v19, v31, s33
	v_add3_u32 v19, v20, v32, s33
	v_lshrrev_b32_e32 v20, 16, v22
	v_lshrrev_b32_e32 v22, 16, v24
	v_add3_u32 v21, v21, v33, s33
	v_lshrrev_b32_e32 v24, 16, v18
	v_lshrrev_b32_e32 v27, 16, v19
	v_and_or_b32 v18, v23, s35, v20
	v_and_or_b32 v19, v25, s35, v22
	v_and_or_b32 v20, v26, s35, v24
	v_and_or_b32 v21, v21, s35, v27
	global_store_dwordx2 v[80:81], v[18:19], off offset:2560
	global_store_dwordx2 v[82:83], v[20:21], off offset:2560
	s_nop 1
	v_mov_b32_e32 v18, v224
	v_mov_b32_e32 v19, v225
	v_mov_b32_e32 v20, v226
	v_mov_b32_e32 v21, v227
	v_mul_f32_e32 v14, v14, v18
	v_mul_f32_e32 v16, v16, v20
	v_mul_f32_e32 v15, v15, v19
	v_mul_f32_e32 v17, v17, v21
	v_mul_f32_e32 v10, v10, v18
	v_mul_f32_e32 v11, v11, v19
	v_mul_f32_e32 v12, v12, v20
	v_bfe_u32 v18, v14, 16, 1
	v_bfe_u32 v20, v16, 16, 1
	v_mul_f32_e32 v13, v13, v21
	v_bfe_u32 v19, v15, 16, 1
	v_bfe_u32 v21, v17, 16, 1
	v_bfe_u32 v22, v10, 16, 1
	v_bfe_u32 v23, v11, 16, 1
	v_bfe_u32 v24, v12, 16, 1
	v_add3_u32 v14, v14, v18, s33
	v_add3_u32 v16, v16, v20, s33
	v_bfe_u32 v25, v13, 16, 1
	v_add3_u32 v15, v15, v19, s33
	v_add3_u32 v17, v17, v21, s33
	v_add3_u32 v10, v10, v22, s33
	v_add3_u32 v18, v11, v23, s33
	v_add3_u32 v11, v12, v24, s33
	v_lshrrev_b32_e32 v12, 16, v14
	v_lshrrev_b32_e32 v14, 16, v16
	v_add3_u32 v13, v13, v25, s33
	v_lshrrev_b32_e32 v16, 16, v10
	v_lshrrev_b32_e32 v19, 16, v11
	v_and_or_b32 v10, v15, s35, v12
	v_and_or_b32 v11, v17, s35, v14
	v_and_or_b32 v12, v18, s35, v16
	v_and_or_b32 v13, v13, s35, v19
	global_store_dwordx2 v[80:81], v[10:11], off offset:3072
	global_store_dwordx2 v[82:83], v[12:13], off offset:3072
	s_nop 1
	v_mov_b32_e32 v10, v228
	v_mov_b32_e32 v11, v229
	v_mov_b32_e32 v12, v230
	v_mov_b32_e32 v13, v231
	v_mul_f32_e32 v2, v2, v10
	v_mul_f32_e32 v4, v4, v12
	v_mul_f32_e32 v3, v3, v11
	v_mul_f32_e32 v5, v5, v13
	v_mul_f32_e32 v6, v6, v10
	v_mul_f32_e32 v8, v8, v12
	v_bfe_u32 v10, v2, 16, 1
	v_bfe_u32 v12, v4, 16, 1
	v_mul_f32_e32 v7, v7, v11
	v_mul_f32_e32 v9, v9, v13
	v_bfe_u32 v11, v3, 16, 1
	v_bfe_u32 v13, v5, 16, 1
	v_bfe_u32 v14, v6, 16, 1
	v_bfe_u32 v16, v8, 16, 1
	v_add3_u32 v2, v2, v10, s33
	v_add3_u32 v4, v4, v12, s33
	v_bfe_u32 v15, v7, 16, 1
	v_bfe_u32 v17, v9, 16, 1
	v_add3_u32 v3, v3, v11, s33
	v_add3_u32 v5, v5, v13, s33
	v_add3_u32 v6, v6, v14, s33
	v_add3_u32 v8, v8, v16, s33
	v_lshrrev_b32_e32 v2, 16, v2
	v_lshrrev_b32_e32 v4, 16, v4
	v_add3_u32 v7, v7, v15, s33
	v_add3_u32 v9, v9, v17, s33
	v_lshrrev_b32_e32 v6, 16, v6
	v_lshrrev_b32_e32 v8, 16, v8
	v_and_or_b32 v2, v3, s35, v2
	v_and_or_b32 v3, v5, s35, v4
	v_and_or_b32 v4, v7, s35, v6
	v_and_or_b32 v5, v9, s35, v8
	global_store_dwordx2 v[80:81], v[2:3], off offset:3584
	global_store_dwordx2 v[82:83], v[4:5], off offset:3584
	s_cbranch_scc0 .LBB0_42

; __device__ __forceinline__ unsigned pk2(float lo, float hi) { return f2bf(lo) | (f2bf(hi) << 16); }
; __device__ __forceinline__ void rms_rows2_b2b(const bf16* x0, const bf16* x1, const float* g, bf16* o0, bf16* o1, int lane) {
;     const v4u* xr0 = (const v4u*)x0 + lane; const v4u* xr1 = (const v4u*)x1 + lane; const f32x4* gr = (const f32x4*)g + 2 * lane;
;     v4u v[4], w[4]; float s = 0.f, t = 0.f;
; #pragma unroll
;     for (int j = 0; j < 4; ++j) { v[j] = xr0[64 * j]; w[j] = xr1[64 * j]; }
; #pragma unroll
;     for (int j = 0; j < 4; ++j) {
;         s += (bflo(v[j].x) * bflo(v[j].x) + bfhi(v[j].x) * bfhi(v[j].x)) + (bflo(v[j].y) * bflo(v[j].y) + bfhi(v[j].y) * bfhi(v[j].y)) + (bflo(v[j].z) * bflo(v[j].z) + bfhi(v[j].z) * bfhi(v[j].z)) + (bflo(v[j].w) * bflo(v[j].w) + bfhi(v[j].w) * bfhi(v[j].w));
;         t += (bflo(w[j].x) * bflo(w[j].x) + bfhi(w[j].x) * bfhi(w[j].x)) + (bflo(w[j].y) * bflo(w[j].y) + bfhi(w[j].y) * bfhi(w[j].y)) + (bflo(w[j].z) * bflo(w[j].z) + bfhi(w[j].z) * bfhi(w[j].z)) + (bflo(w[j].w) * bflo(w[j].w) + bfhi(w[j].w) * bfhi(w[j].w)); }
;     const float rs = 1.f / sqrtf(wave_sum(s, lane) * (1.f / D) + NORM_EPS), rt = 1.f / sqrtf(wave_sum(t, lane) * (1.f / D) + NORM_EPS);
;     v4u* p0 = (v4u*)o0 + lane; v4u* p1 = (v4u*)o1 + lane;
; #pragma unroll
;     for (int j = 0; j < 4; ++j) { const f32x4 ga = gr[128 * j], gb = gr[128 * j + 1];
;         v4u a, b;
;         a.x = pk2(bflo(v[j].x) * rs * ga.x, bfhi(v[j].x) * rs * ga.y); a.y = pk2(bflo(v[j].y) * rs * ga.z, bfhi(v[j].y) * rs * ga.w); a.z = pk2(bflo(v[j].z) * rs * gb.x, bfhi(v[j].z) * rs * gb.y); a.w = pk2(bflo(v[j].w) * rs * gb.z, bfhi(v[j].w) * rs * gb.w);
;         b.x = pk2(bflo(w[j].x) * rt * ga.x, bfhi(w[j].x) * rt * ga.y); b.y = pk2(bflo(w[j].y) * rt * ga.z, bfhi(w[j].y) * rt * ga.w); b.z = pk2(bflo(w[j].z) * rt * gb.x, bfhi(w[j].z) * rt * gb.y); b.w = pk2(bflo(w[j].w) * rt * gb.z, bfhi(w[j].w) * rt * gb.w);
;         p0[64 * j] = a; p1[64 * j] = b; }
.LBB0_304:
	s_or_b64 exec, exec, s[4:5]
	s_waitcnt lgkmcnt(0)
	v_mov_b32_e32 v0, v248
	s_barrier
	s_nop 0
	v_readfirstlane_b32 s0, v0
	s_ashr_i32 s1, s0, 6
	v_readlane_b32 s0, v255, 1
	s_add_i32 s0, s1, s0
	s_cmpk_gt_i32 s0, 0x1fff
	s_cbranch_scc1 .LBB0_307
	v_and_b32_e32 v0, 63, v0
	v_lshlrev_b32_e32 v8, 5, v0
	v_mov_b32_e32 v9, 0
	v_lshl_add_u64 v[10:11], s[40:41], 0, v[8:9]
	s_mov_b64 s[4:5], 0x1000
	v_lshl_add_u64 v[12:13], v[10:11], 0, s[4:5]
	s_mov_b64 s[4:5], 0x1800
	v_lshl_add_u64 v[14:15], v[10:11], 0, s[4:5]
	s_add_i32 s4, s0, 0x2000
	s_ashr_i32 s5, s4, 31
	s_lshl_b64 s[4:5], s[4:5], 12
	s_add_u32 s10, s54, s4
	s_addc_u32 s11, s55, s5
	s_ashr_i32 s35, s34, 31
	v_readlane_b32 s6, v255, 1
	s_lshl_b64 s[14:15], s[34:35], 12
	s_ashr_i32 s7, s1, 31
	s_ashr_i32 s8, s6, 31
	s_add_u32 s6, s1, s6
	s_addc_u32 s7, s7, s8
	s_lshl_b64 s[6:7], s[6:7], 12
	s_add_u32 s36, s52, s6
	s_addc_u32 s37, s53, s7
	s_add_u32 s44, s52, s4
	s_addc_u32 s45, s53, s5
	s_add_u32 s1, s54, s6
	s_addc_u32 s4, s55, s7
	v_lshlrev_b32_e32 v1, 2, v0
	s_add_u32 s48, s1, 0xc000800
	v_xor_b32_e32 v70, 4, v1
	v_xor_b32_e32 v71, 8, v1
	v_xor_b32_e32 v72, 16, v1
	v_xor_b32_e32 v73, 32, v1
	v_xor_b32_e32 v74, 64, v1
	v_xor_b32_e32 v75, 0x80, v1
	v_lshlrev_b32_e32 v8, 4, v0
	s_addc_u32 s49, s4, 0
	s_mov_b32 s1, 0xffff0000
	v_mov_b32_e32 v76, 0x358637bd
	s_mov_b32 s24, 0xf800000
	v_mov_b32_e32 v77, 0x260
	s_movk_i32 s25, 0x7fff
	s_brev_b32 s33, 48
	global_load_dwordx4 v[200:203], v[10:11], off offset:16
	global_load_dwordx4 v[204:207], v[10:11], off
	global_load_dwordx4 v[208:211], v[10:11], off offset:2048
	global_load_dwordx4 v[212:215], v[10:11], off offset:2064
	global_load_dwordx4 v[216:219], v[12:13], off
	global_load_dwordx4 v[220:223], v[12:13], off offset:16
	global_load_dwordx4 v[224:227], v[14:15], off
	global_load_dwordx4 v[228:231], v[14:15], off offset:16
	s_waitcnt vmcnt(0)
.LBB0_306:
	v_lshl_add_u64 v[18:19], s[36:37], 0, v[8:9]
	s_nop 1
	v_mov_b32_e32 v0, v200
	v_mov_b32_e32 v1, v201
	v_mov_b32_e32 v2, v202
	v_mov_b32_e32 v3, v203
	s_nop 1
	v_mov_b32_e32 v4, v204
	v_mov_b32_e32 v5, v205
	v_mov_b32_e32 v6, v206
	v_mov_b32_e32 v7, v207
	v_lshl_add_u64 v[20:21], s[44:45], 0, v[8:9]
	global_load_dwordx4 v[24:27], v[18:19], off offset:1024
	global_load_dwordx4 v[28:31], v[20:21], off offset:1024
	global_load_dwordx4 v[36:39], v[18:19], off offset:2048
	global_load_dwordx4 v[42:45], v[20:21], off offset:2048
	global_load_dwordx4 v[78:81], v[18:19], off offset:3072
	global_load_dwordx4 v[82:85], v[20:21], off offset:3072
	global_load_dwordx4 v[32:35], v[18:19], off
	global_load_dwordx4 v[86:89], v[20:21], off
	v_lshl_add_u64 v[22:23], s[10:11], 0, v[8:9]
	v_add_co_u32_e32 v18, vcc, s33, v22
	v_lshl_add_u64 v[16:17], s[48:49], 0, v[8:9]
	s_nop 0
	v_addc_co_u32_e32 v19, vcc, 0, v23, vcc
	s_add_i32 s0, s0, s34
	s_add_u32 s10, s10, s14
	s_addc_u32 s11, s11, s15
	s_add_u32 s36, s36, s14
	s_addc_u32 s37, s37, s15
	s_add_u32 s44, s44, s14
	s_addc_u32 s45, s45, s15
	s_add_u32 s48, s48, s14
	s_addc_u32 s49, s49, s15
	s_cmpk_gt_i32 s0, 0x1fff
	s_waitcnt vmcnt(7)
	v_and_b32_e32 v63, 0xffff0000, v25
	v_and_b32_e32 v62, 0xffff0000, v24
	s_waitcnt vmcnt(5)
	v_and_b32_e32 v91, 0xffff0000, v36
	v_lshlrev_b32_e32 v92, 16, v37
	v_and_b32_e32 v93, 0xffff0000, v37
	s_waitcnt vmcnt(4)
	v_and_b32_e32 v95, 0xffff0000, v42
	s_waitcnt vmcnt(1)
	v_and_b32_e32 v98, 0xffff0000, v32
	v_and_b32_e32 v102, 0xffff0000, v34
	v_and_b32_e32 v65, 0xffff0000, v43
	v_lshlrev_b32_e32 v97, 16, v33
	v_lshlrev_b32_e32 v96, 16, v32
	v_and_b32_e32 v99, 0xffff0000, v33
	v_lshlrev_b32_e32 v101, 16, v35
	v_lshlrev_b32_e32 v100, 16, v34
	v_and_b32_e32 v103, 0xffff0000, v35
	v_lshlrev_b32_e32 v35, 16, v78
	v_and_b32_e32 v37, 0xffff0000, v78
	v_pk_mov_b32 v[46:47], v[38:39], v[80:81] op_sel:[1,0]
	v_lshlrev_b32_e32 v33, 16, v80
	s_waitcnt vmcnt(0)
	v_lshlrev_b32_e32 v78, 16, v86
	v_and_b32_e32 v80, 0xffff0000, v86
	v_lshlrev_b32_e32 v86, 16, v88
	v_and_b32_e32 v88, 0xffff0000, v88
	v_mov_b32_e32 v114, v102
	v_mov_b32_e32 v115, v98
	v_mov_b32_e32 v48, v4
	v_mov_b32_e32 v49, v6
	v_mov_b32_e32 v6, v5
	v_mov_b32_e32 v50, v0
	v_mov_b32_e32 v51, v2
	v_mov_b32_e32 v2, v1
	v_lshlrev_b32_e32 v61, 16, v25
	v_lshlrev_b32_e32 v60, 16, v24
	v_lshlrev_b32_e32 v67, 16, v27
	v_lshlrev_b32_e32 v66, 16, v26
	v_and_b32_e32 v69, 0xffff0000, v27
	v_and_b32_e32 v68, 0xffff0000, v26
	v_lshlrev_b32_e32 v53, 16, v29
	v_lshlrev_b32_e32 v52, 16, v28
	v_and_b32_e32 v55, 0xffff0000, v29
	v_and_b32_e32 v54, 0xffff0000, v28
	v_lshlrev_b32_e32 v57, 16, v31
	v_and_b32_e32 v59, 0xffff0000, v31
	v_lshlrev_b32_e32 v90, 16, v36
	v_lshlrev_b32_e32 v94, 16, v42
	v_lshlrev_b32_e32 v64, 16, v43
	v_lshlrev_b32_e32 v31, 16, v79
	v_and_b32_e32 v29, 0xffff0000, v79
	v_lshlrev_b32_e32 v27, 16, v81
	v_and_b32_e32 v25, 0xffff0000, v81
	v_lshlrev_b32_e32 v23, 16, v83
	v_and_b32_e32 v21, 0xffff0000, v83
	v_lshlrev_b32_e32 v5, 16, v85
	v_and_b32_e32 v1, 0xffff0000, v85
	v_lshlrev_b32_e32 v32, 16, v39
	v_lshlrev_b32_e32 v79, 16, v87
	v_and_b32_e32 v81, 0xffff0000, v87
	v_lshlrev_b32_e32 v41, 16, v82
	v_and_b32_e32 v43, 0xffff0000, v82
	v_pk_mov_b32 v[82:83], v[44:45], v[84:85] op_sel:[1,0]
	v_lshlrev_b32_e32 v39, 16, v84
	v_pk_mul_f32 v[84:85], v[62:63], v[62:63]
	v_mov_b32_e32 v110, v97
	v_mov_b32_e32 v111, v99
	v_mul_f32_e32 v0, v99, v99
	v_mov_b32_e32 v112, v100
	v_mov_b32_e32 v113, v96
	v_mul_f32_e32 v4, v91, v91
	v_mul_f32_e32 v20, v93, v93
	v_mov_b32_e32 v126, v88
	v_mov_b32_e32 v127, v80
	v_mul_f32_e32 v26, v95, v95
	v_mul_f32_e32 v28, v65, v65
	v_pk_mul_f32 v[114:115], v[114:115], v[114:115]
	v_and_b32_e32 v36, 0xffff0000, v38
	v_pk_mul_f32 v[104:105], v[68:69], v[68:69]
; __device__ __forceinline__ void rms_rows2_b2b(const bf16* x0, const bf16* x1, const float* g, bf16* o0, bf16* o1, int lane) {
;     ...
;     for (int j = 0; j < 4; ++j) { v[j] = xr0[64 * j]; w[j] = xr1[64 * j]; }
; #pragma unroll
;     for (int j = 0; j < 4; ++j) {
;         s += (bflo(v[j].x) * bflo(v[j].x) + bfhi(v[j].x) * bfhi(v[j].x)) + (bflo(v[j].y) * bflo(v[j].y) + bfhi(v[j].y) * bfhi(v[j].y)) + (bflo(v[j].z) * bflo(v[j].z) + bfhi(v[j].z) * bfhi(v[j].z)) + (bflo(v[j].w) * bflo(v[j].w) + bfhi(v[j].w) * bfhi(v[j].w));
;         t += (bflo(w[j].x) * bflo(w[j].x) + bfhi(w[j].x) * bfhi(w[j].x)) + (bflo(w[j].y) * bflo(w[j].y) + bfhi(w[j].y) * bfhi(w[j].y)) + (bflo(w[j].z) * bflo(w[j].z) + bfhi(w[j].z) * bfhi(w[j].z)) + (bflo(w[j].w) * bflo(w[j].w) + bfhi(w[j].w) * bfhi(w[j].w)); }
;     const float rs = 1.f / sqrtf(wave_sum(s, lane) * (1.f / D) + NORM_EPS), rt = 1.f / sqrtf(wave_sum(t, lane) * (1.f / D) + NORM_EPS);
	v_mul_f32_e32 v120, v31, v31
	v_mul_f32_e32 v156, v29, v29
	v_mov_b32_e32 v122, v79
	v_mov_b32_e32 v123, v81
	v_mul_f32_e32 v24, v81, v81
	v_mov_b32_e32 v124, v86
	v_mov_b32_e32 v125, v78
	v_mov_b32_e32 v138, v94
	v_mov_b32_e32 v139, v64
	v_pk_fma_f32 v[84:85], v[60:61], v[60:61], v[84:85]
	v_pk_fma_f32 v[110:111], v[110:111], v[110:111], v[0:1] op_sel_hi:[1,1,0]
	v_pk_fma_f32 v[144:145], v[90:91], v[90:91], v[4:5] op_sel_hi:[1,1,0]
	v_pk_fma_f32 v[146:147], v[92:93], v[92:93], v[20:21] op_sel_hi:[1,1,0]
	v_pk_mul_f32 v[126:127], v[126:127], v[126:127]
	v_pk_fma_f32 v[150:151], v[94:95], v[94:95], v[26:27] op_sel_hi:[1,1,0]
	v_pk_fma_f32 v[152:153], v[64:65], v[64:65], v[28:29] op_sel_hi:[1,1,0]
	v_mov_b32_e32 v64, v95
	v_pk_fma_f32 v[94:95], v[112:113], v[112:113], v[114:115]
	v_and_b32_e32 v58, 0xffff0000, v30
	v_lshlrev_b32_e32 v34, 16, v38
	v_lshlrev_b32_e32 v87, 16, v89
	v_and_b32_e32 v89, 0xffff0000, v89
	v_lshlrev_b32_e32 v40, 16, v44
	v_and_b32_e32 v42, 0xffff0000, v44
	v_lshlrev_b32_e32 v38, 16, v45
	v_pk_mul_f32 v[106:107], v[54:55], v[54:55]
	v_mov_b32_e32 v116, v101
	v_mov_b32_e32 v117, v103
	v_pk_mul_f32 v[118:119], v[36:37], v[36:37]
	v_and_b32_e32 v45, 0xffff0000, v47
	v_and_b32_e32 v44, 0xffff0000, v46
	v_mul_f32_e32 v22, v103, v103
	v_pk_fma_f32 v[104:105], v[66:67], v[66:67], v[104:105]
	v_pk_fma_f32 v[122:123], v[122:123], v[122:123], v[24:25] op_sel_hi:[1,1,0]
	v_pk_add_f32 v[84:85], v[84:85], v[84:85] op_sel:[0,1] op_sel_hi:[1,0]
	v_mov_b32_e32 v145, v120
	v_mov_b32_e32 v147, v156
	v_pk_fma_f32 v[112:113], v[124:125], v[124:125], v[126:127]
	v_pk_add_f32 v[110:111], v[94:95], v[110:111] op_sel:[1,0] op_sel_hi:[0,1]
	v_lshlrev_b32_e32 v56, 16, v30
	v_pk_mul_f32 v[108:109], v[58:59], v[58:59]
	v_mov_b32_e32 v128, v87
	v_mov_b32_e32 v129, v89
	v_mul_f32_e32 v30, v89, v89
	v_pk_fma_f32 v[106:107], v[52:53], v[52:53], v[106:107]
	v_pk_fma_f32 v[118:119], v[34:35], v[34:35], v[118:119]
	v_pk_mul_f32 v[148:149], v[44:45], v[44:45]
	v_pk_fma_f32 v[116:117], v[116:117], v[116:117], v[22:23] op_sel_hi:[1,1,0]
	v_pk_add_f32 v[84:85], v[104:105], v[84:85]
	v_pk_add_f32 v[124:125], v[144:145], v[146:147]
	v_pk_add_f32 v[122:123], v[112:113], v[122:123] op_sel:[1,0] op_sel_hi:[0,1]
	v_pk_add_f32 v[94:95], v[94:95], v[110:111]
	v_mul_f32_e32 v158, v23, v23
	v_mul_f32_e32 v159, v21, v21
	v_mov_b32_e32 v121, v27
	v_mov_b32_e32 v132, v90
	v_mov_b32_e32 v133, v92
	v_pk_fma_f32 v[108:109], v[56:57], v[56:57], v[108:109]
	v_pk_fma_f32 v[128:129], v[128:129], v[128:129], v[30:31] op_sel_hi:[1,1,0]
	v_mov_b32_e32 v92, v91
	v_pk_add_f32 v[90:91], v[106:107], v[106:107] op_sel:[0,1] op_sel_hi:[1,0]
	v_pk_fma_f32 v[106:107], v[32:33], v[32:33], v[148:149]
	v_mov_b32_e32 v26, v116
	v_pk_add_f32 v[110:111], v[118:119], v[124:125]
	v_pk_add_f32 v[84:85], v[104:105], v[84:85] op_sel:[1,0] op_sel_hi:[0,1]
	v_pk_add_f32 v[104:105], v[112:113], v[122:123]
	v_mov_b32_e32 v120, v94
	v_mul_f32_e32 v157, v25, v25
	v_pk_mul_f32 v[130:131], v[42:43], v[42:43]
	v_and_b32_e32 v47, 0xffff0000, v83
	v_and_b32_e32 v46, 0xffff0000, v82
	v_mov_b32_e32 v83, v5
	v_mov_b32_e32 v151, v158
	v_mov_b32_e32 v153, v159
	v_mov_b32_e32 v4, v128
	v_pk_add_f32 v[90:91], v[108:109], v[90:91]
	v_pk_add_f32 v[106:107], v[106:107], v[110:111]
	v_pk_add_f32 v[94:95], v[116:117], v[94:95]
	v_mov_b32_e32 v82, v104
	v_pk_mul_f32 v[110:111], v[26:27], v[120:121]
	v_mul_f32_e32 v160, v1, v1
	v_pk_fma_f32 v[130:131], v[40:41], v[40:41], v[130:131]
	v_pk_mul_f32 v[154:155], v[46:47], v[46:47]
	v_pk_add_f32 v[126:127], v[150:151], v[152:153]
	v_pk_add_f32 v[90:91], v[108:109], v[90:91] op_sel:[1,0] op_sel_hi:[0,1]
	v_mov_b32_e32 v85, v157
	v_pk_add_f32 v[104:105], v[128:129], v[104:105]
	v_pk_mul_f32 v[82:83], v[4:5], v[82:83]
	v_mov_b32_e32 v95, v111
	v_pk_fma_f32 v[114:115], v[38:39], v[38:39], v[154:155]
	v_pk_add_f32 v[112:113], v[130:131], v[126:127]
	v_mov_b32_e32 v91, v160
	v_mov_b32_e32 v105, v83
	v_pk_add_f32 v[82:83], v[94:95], v[84:85]
	v_pk_add_f32 v[108:109], v[114:115], v[112:113]
	v_pk_add_f32 v[84:85], v[104:105], v[90:91]
	v_pk_add_f32 v[82:83], v[82:83], v[106:107]
	v_pk_add_f32 v[84:85], v[84:85], v[108:109]
	v_add_f32_e32 v0, v82, v83
	v_add_f32_e32 v4, v84, v85
	ds_bpermute_b32 v20, v70, v0
	ds_bpermute_b32 v22, v70, v4
	v_mov_b32_e32 v135, v32
	v_mov_b32_e32 v134, v34
	v_mov_b32_e32 v136, v36
	s_waitcnt lgkmcnt(1)
	v_add_f32_e32 v0, v0, v20
	s_waitcnt lgkmcnt(0)
	v_add_f32_e32 v4, v4, v22
	ds_bpermute_b32 v20, v71, v0
	ds_bpermute_b32 v22, v71, v4
	v_mov_b32_e32 v141, v38
	v_mov_b32_e32 v140, v40
	v_mov_b32_e32 v142, v42
	s_waitcnt lgkmcnt(1)
	v_add_f32_e32 v0, v0, v20
	s_waitcnt lgkmcnt(0)
	v_add_f32_e32 v4, v4, v22
	ds_bpermute_b32 v20, v72, v0
	ds_bpermute_b32 v22, v72, v4
	v_mov_b32_e32 v137, v44
	v_mov_b32_e32 v143, v46
	s_waitcnt lgkmcnt(1)
	v_add_f32_e32 v0, v0, v20
	s_waitcnt lgkmcnt(0)
	v_add_f32_e32 v4, v4, v22
	ds_bpermute_b32 v20, v73, v0
	ds_bpermute_b32 v22, v73, v4
	s_waitcnt lgkmcnt(1)
	v_add_f32_e32 v0, v0, v20
	s_waitcnt lgkmcnt(0)
	v_add_f32_e32 v4, v4, v22
	ds_bpermute_b32 v20, v74, v0
	ds_bpermute_b32 v22, v74, v4
	s_waitcnt lgkmcnt(1)
	v_add_f32_e32 v0, v0, v20
	s_waitcnt lgkmcnt(0)
	v_add_f32_e32 v4, v4, v22
	ds_bpermute_b32 v20, v75, v0
	ds_bpermute_b32 v22, v75, v4
	s_waitcnt lgkmcnt(1)
	v_add_f32_e32 v0, v0, v20
	s_waitcnt lgkmcnt(0)
; __device__ __forceinline__ unsigned pk2(float lo, float hi) { return f2bf(lo) | (f2bf(hi) << 16); }
; __device__ __forceinline__ void rms_rows2_b2b(const bf16* x0, const bf16* x1, const float* g, bf16* o0, bf16* o1, int lane) {
;     ...
;     const float rs = 1.f / sqrtf(wave_sum(s, lane) * (1.f / D) + NORM_EPS), rt = 1.f / sqrtf(wave_sum(t, lane) * (1.f / D) + NORM_EPS);
;     v4u* p0 = (v4u*)o0 + lane; v4u* p1 = (v4u*)o1 + lane;
; #pragma unroll
;     for (int j = 0; j < 4; ++j) { const f32x4 ga = gr[128 * j], gb = gr[128 * j + 1];
;         v4u a, b;
;         a.x = pk2(bflo(v[j].x) * rs * ga.x, bfhi(v[j].x) * rs * ga.y); a.y = pk2(bflo(v[j].y) * rs * ga.z, bfhi(v[j].y) * rs * ga.w); a.z = pk2(bflo(v[j].z) * rs * gb.x, bfhi(v[j].z) * rs * gb.y); a.w = pk2(bflo(v[j].w) * rs * gb.z, bfhi(v[j].w) * rs * gb.w);
;         b.x = pk2(bflo(w[j].x) * rt * ga.x, bfhi(w[j].x) * rt * ga.y); b.y = pk2(bflo(w[j].y) * rt * ga.z, bfhi(w[j].y) * rt * ga.w); b.z = pk2(bflo(w[j].z) * rt * gb.x, bfhi(w[j].z) * rt * gb.y); b.w = pk2(bflo(w[j].w) * rt * gb.z, bfhi(w[j].w) * rt * gb.w);
;         p0[64 * j] = a; p1[64 * j] = b; }
	v_add_f32_e32 v4, v4, v22
	v_fmamk_f32 v0, v0, 0x3a000000, v76
	v_fmamk_f32 v4, v4, 0x3a000000, v76
	v_mul_f32_e32 v20, 0x4f800000, v0
	v_cmp_gt_f32_e64 s[4:5], s24, v0
	v_mul_f32_e32 v22, 0x4f800000, v4
	v_cmp_gt_f32_e32 vcc, s24, v4
	v_cndmask_b32_e64 v0, v0, v20, s[4:5]
	v_sqrt_f32_e32 v20, v0
	v_cndmask_b32_e32 v4, v4, v22, vcc
	v_sqrt_f32_e32 v22, v4
	v_add_u32_e32 v24, -1, v20
	v_add_u32_e32 v26, 1, v20
	v_add_u32_e32 v28, -1, v22
	v_fma_f32 v32, -v24, v20, v0
	v_add_u32_e32 v30, 1, v22
	v_fma_f32 v34, -v26, v20, v0
	v_fma_f32 v36, -v28, v22, v4
	v_cmp_ge_f32_e64 s[6:7], 0, v32
	v_fma_f32 v38, -v30, v22, v4
	v_cmp_lt_f32_e64 s[8:9], 0, v34
	v_cndmask_b32_e64 v20, v20, v24, s[6:7]
	v_cmp_ge_f32_e64 s[6:7], 0, v36
	v_cndmask_b32_e64 v20, v20, v26, s[8:9]
	v_mul_f32_e32 v24, 0x37800000, v20
	v_cndmask_b32_e64 v22, v22, v28, s[6:7]
	v_cmp_lt_f32_e64 s[6:7], 0, v38
	v_cndmask_b32_e64 v20, v20, v24, s[4:5]
	v_cmp_class_f32_e64 s[4:5], v0, v77
	v_cndmask_b32_e64 v22, v22, v30, s[6:7]
	v_mul_f32_e32 v26, 0x37800000, v22
	v_cndmask_b32_e32 v22, v22, v26, vcc
	v_cmp_class_f32_e32 vcc, v4, v77
	v_cndmask_b32_e64 v0, v20, v0, s[4:5]
	v_div_scale_f32 v20, s[4:5], v0, v0, 1.0
	v_cndmask_b32_e32 v4, v22, v4, vcc
	v_div_scale_f32 v24, s[4:5], v4, v4, 1.0
	v_rcp_f32_e32 v28, v20
	v_rcp_f32_e32 v30, v24
	v_div_scale_f32 v22, vcc, 1.0, v0, 1.0
	v_fma_f32 v32, -v20, v28, 1.0
	v_fma_f32 v34, -v24, v30, 1.0
	v_fmac_f32_e32 v28, v32, v28
	v_div_scale_f32 v26, s[4:5], 1.0, v4, 1.0
	v_fmac_f32_e32 v30, v34, v30
	v_mul_f32_e32 v32, v22, v28
	v_mul_f32_e32 v34, v26, v30
	v_fma_f32 v36, -v20, v32, v22
	v_fma_f32 v38, -v24, v34, v26
	v_fmac_f32_e32 v32, v36, v28
	v_fmac_f32_e32 v34, v38, v30
	v_fma_f32 v20, -v20, v32, v22
	v_fma_f32 v22, -v24, v34, v26
	v_div_fmas_f32 v20, v20, v28, v32
	s_mov_b64 vcc, s[4:5]
	v_div_fixup_f32 v32, v20, v0, 1.0
	v_div_fmas_f32 v0, v22, v30, v34
	v_pk_mul_f32 v[82:83], v[32:33], v[96:97] op_sel_hi:[0,1]
	v_pk_mul_f32 v[90:91], v[32:33], v[100:101] op_sel_hi:[0,1]
	v_div_fixup_f32 v34, v0, v4, 1.0
	v_pk_mul_f32 v[84:85], v[32:33], v[98:99] op_sel_hi:[0,1]
	v_pk_mul_f32 v[94:95], v[32:33], v[102:103] op_sel_hi:[0,1]
	v_pk_mul_f32 v[82:83], v[48:49], v[82:83]
	v_pk_mul_f32 v[90:91], v[50:51], v[90:91]
	v_pk_mul_f32 v[78:79], v[34:35], v[78:79] op_sel_hi:[0,1]
	v_pk_mul_f32 v[80:81], v[34:35], v[80:81] op_sel_hi:[0,1]
	v_pk_mul_f32 v[86:87], v[34:35], v[86:87] op_sel_hi:[0,1]
	v_pk_mul_f32 v[88:89], v[34:35], v[88:89] op_sel_hi:[0,1]
	v_pk_mul_f32 v[84:85], v[6:7], v[84:85]
	v_pk_mul_f32 v[94:95], v[2:3], v[94:95]
	v_bfe_u32 v24, v82, 16, 1
	v_bfe_u32 v26, v83, 16, 1
	v_bfe_u32 v28, v90, 16, 1
	v_bfe_u32 v30, v91, 16, 1
	v_pk_mul_f32 v[48:49], v[48:49], v[78:79]
	v_pk_mul_f32 v[6:7], v[6:7], v[80:81]
	v_pk_mul_f32 v[50:51], v[50:51], v[86:87]
	v_pk_mul_f32 v[2:3], v[2:3], v[88:89]
	v_pk_mul_f32 v[102:103], v[34:35], v[52:53] op_sel_hi:[0,1]
	v_bfe_u32 v0, v95, 16, 1
	v_bfe_u32 v4, v94, 16, 1
	v_bfe_u32 v20, v85, 16, 1
	v_bfe_u32 v22, v84, 16, 1
	v_add3_u32 v30, v91, v30, s25
	v_add3_u32 v28, v90, v28, s25
	v_add3_u32 v26, v83, v26, s25
	v_add3_u32 v24, v82, v24, s25
	v_bfe_u32 v36, v3, 16, 1
	v_bfe_u32 v38, v2, 16, 1
	v_bfe_u32 v40, v7, 16, 1
	v_bfe_u32 v42, v6, 16, 1
	v_bfe_u32 v44, v48, 16, 1
	v_bfe_u32 v46, v49, 16, 1
	v_bfe_u32 v52, v50, 16, 1
	v_bfe_u32 v53, v51, 16, 1
	v_add3_u32 v22, v84, v22, s25
	v_add3_u32 v20, v85, v20, s25
	v_add3_u32 v4, v94, v4, s25
	v_add3_u32 v0, v95, v0, s25
	v_lshrrev_b32_e32 v24, 16, v24
	v_lshrrev_b32_e32 v26, 16, v26
	v_lshrrev_b32_e32 v28, 16, v28
	v_lshrrev_b32_e32 v30, 16, v30
	v_add3_u32 v6, v6, v42, s25
	v_add3_u32 v7, v7, v40, s25
	v_add3_u32 v2, v2, v38, s25
	v_add3_u32 v3, v3, v36, s25
	v_add3_u32 v36, v51, v53, s25
	v_add3_u32 v38, v50, v52, s25
	v_add3_u32 v40, v49, v46, s25
	v_add3_u32 v42, v48, v44, s25
	v_and_or_b32 v51, v0, s1, v30
	v_and_or_b32 v50, v4, s1, v28
	v_and_or_b32 v49, v20, s1, v26
	v_and_or_b32 v48, v22, s1, v24
	v_lshrrev_b32_e32 v0, 16, v42
	v_lshrrev_b32_e32 v4, 16, v40
	v_lshrrev_b32_e32 v20, 16, v38
	v_lshrrev_b32_e32 v22, 16, v36
	v_pk_mul_f32 v[104:105], v[34:35], v[54:55] op_sel_hi:[0,1]
	v_and_or_b32 v55, v3, s1, v22
	v_and_or_b32 v54, v2, s1, v20
	v_and_or_b32 v53, v7, s1, v4
	v_and_or_b32 v52, v6, s1, v0
	global_store_dwordx4 v[16:17], v[48:51], off offset:-2048
	global_store_dwordx4 v[18:19], v[52:55], off
	s_nop 1
	v_mov_b32_e32 v48, v208
	v_mov_b32_e32 v49, v209
	v_mov_b32_e32 v50, v210
	v_mov_b32_e32 v51, v211
	s_nop 0
	s_nop 1
	v_mov_b32_e32 v52, v212
	v_mov_b32_e32 v53, v213
	v_mov_b32_e32 v54, v214
	v_mov_b32_e32 v55, v215
	v_pk_mul_f32 v[60:61], v[32:33], v[60:61] op_sel_hi:[0,1]
	v_pk_mul_f32 v[66:67], v[32:33], v[66:67] op_sel_hi:[0,1]
	v_pk_mul_f32 v[62:63], v[32:33], v[62:63] op_sel_hi:[0,1]
	v_pk_mul_f32 v[68:69], v[32:33], v[68:69] op_sel_hi:[0,1]
	v_pk_mul_f32 v[56:57], v[34:35], v[56:57] op_sel_hi:[0,1]
	v_pk_mul_f32 v[58:59], v[34:35], v[58:59] op_sel_hi:[0,1]
	v_pk_mul_f32 v[96:97], v[32:33], v[132:133] op_sel_hi:[0,1]
	v_pk_mul_f32 v[98:99], v[32:33], v[134:135] op_sel_hi:[0,1]
	v_pk_mul_f32 v[92:93], v[32:33], v[92:93] op_sel_hi:[0,1]
	v_pk_mul_f32 v[100:101], v[32:33], v[136:137] op_sel_hi:[0,1]
	v_pk_mul_f32 v[106:107], v[34:35], v[138:139] op_sel_hi:[0,1]
	v_pk_mul_f32 v[108:109], v[34:35], v[140:141] op_sel_hi:[0,1]
	v_pk_mul_f32 v[64:65], v[34:35], v[64:65] op_sel_hi:[0,1]
	v_pk_mul_f32 v[110:111], v[34:35], v[142:143] op_sel_hi:[0,1]
	v_mov_b32_e32 v2, v48
	v_mov_b32_e32 v3, v50
	v_mov_b32_e32 v6, v52
	v_mov_b32_e32 v7, v54
	v_mov_b32_e32 v50, v49
	v_mov_b32_e32 v54, v53
	v_pk_mul_f32 v[48:49], v[2:3], v[60:61]
; __device__ __forceinline__ unsigned pk2(float lo, float hi) { return f2bf(lo) | (f2bf(hi) << 16); }
; __device__ __forceinline__ void rms_rows2_b2b(const bf16* x0, const bf16* x1, const float* g, bf16* o0, bf16* o1, int lane) {
;     ...
;     for (int j = 0; j < 4; ++j) { const f32x4 ga = gr[128 * j], gb = gr[128 * j + 1];
;         v4u a, b;
;         a.x = pk2(bflo(v[j].x) * rs * ga.x, bfhi(v[j].x) * rs * ga.y); a.y = pk2(bflo(v[j].y) * rs * ga.z, bfhi(v[j].y) * rs * ga.w); a.z = pk2(bflo(v[j].z) * rs * gb.x, bfhi(v[j].z) * rs * gb.y); a.w = pk2(bflo(v[j].w) * rs * gb.z, bfhi(v[j].w) * rs * gb.w);
;         b.x = pk2(bflo(w[j].x) * rt * ga.x, bfhi(w[j].x) * rt * ga.y); b.y = pk2(bflo(w[j].y) * rt * ga.z, bfhi(w[j].y) * rt * ga.w); b.z = pk2(bflo(w[j].z) * rt * gb.x, bfhi(w[j].z) * rt * gb.y); b.w = pk2(bflo(w[j].w) * rt * gb.z, bfhi(w[j].w) * rt * gb.w);
;         p0[64 * j] = a; p1[64 * j] = b; }
	v_pk_mul_f32 v[60:61], v[66:67], v[6:7]
	v_pk_mul_f32 v[52:53], v[50:51], v[62:63]
	v_pk_mul_f32 v[62:63], v[68:69], v[54:55]
	v_pk_mul_f32 v[2:3], v[2:3], v[102:103]
	v_pk_mul_f32 v[6:7], v[6:7], v[56:57]
	v_bfe_u32 v24, v48, 16, 1
	v_bfe_u32 v26, v49, 16, 1
	v_bfe_u32 v28, v60, 16, 1
	v_bfe_u32 v30, v61, 16, 1
	v_pk_mul_f32 v[50:51], v[50:51], v[104:105]
	v_pk_mul_f32 v[54:55], v[54:55], v[58:59]
	v_bfe_u32 v0, v63, 16, 1
	v_bfe_u32 v4, v62, 16, 1
	v_bfe_u32 v20, v53, 16, 1
	v_bfe_u32 v22, v52, 16, 1
	v_bfe_u32 v44, v2, 16, 1
	v_bfe_u32 v46, v3, 16, 1
	v_bfe_u32 v56, v6, 16, 1
	v_bfe_u32 v57, v7, 16, 1
	v_add3_u32 v30, v61, v30, s25
	v_add3_u32 v28, v60, v28, s25
	v_add3_u32 v26, v49, v26, s25
	v_add3_u32 v24, v48, v24, s25
	v_bfe_u32 v36, v55, 16, 1
	v_bfe_u32 v38, v54, 16, 1
	v_bfe_u32 v40, v51, 16, 1
	v_bfe_u32 v42, v50, 16, 1
	v_add3_u32 v22, v52, v22, s25
	v_add3_u32 v20, v53, v20, s25
	v_add3_u32 v4, v62, v4, s25
	v_add3_u32 v0, v63, v0, s25
	v_add3_u32 v7, v7, v57, s25
	v_add3_u32 v6, v6, v56, s25
	v_add3_u32 v3, v3, v46, s25
	v_add3_u32 v2, v2, v44, s25
	v_lshrrev_b32_e32 v24, 16, v24
	v_lshrrev_b32_e32 v26, 16, v26
	v_lshrrev_b32_e32 v28, 16, v28
	v_lshrrev_b32_e32 v30, 16, v30
	v_add3_u32 v42, v50, v42, s25
	v_add3_u32 v40, v51, v40, s25
	v_add3_u32 v38, v54, v38, s25
	v_add3_u32 v36, v55, v36, s25
	v_lshrrev_b32_e32 v2, 16, v2
	v_lshrrev_b32_e32 v3, 16, v3
	v_lshrrev_b32_e32 v6, 16, v6
	v_lshrrev_b32_e32 v7, 16, v7
	v_and_or_b32 v51, v0, s1, v30
	v_and_or_b32 v50, v4, s1, v28
	v_and_or_b32 v49, v20, s1, v26
	v_and_or_b32 v48, v22, s1, v24
	v_and_or_b32 v55, v36, s1, v7
	v_and_or_b32 v54, v38, s1, v6
	v_and_or_b32 v53, v40, s1, v3
	v_and_or_b32 v52, v42, s1, v2
	global_store_dwordx4 v[16:17], v[48:51], off offset:-1024
	global_store_dwordx4 v[18:19], v[52:55], off offset:1024
	s_nop 1
	v_mov_b32_e32 v48, v216
	v_mov_b32_e32 v49, v217
	v_mov_b32_e32 v50, v218
	v_mov_b32_e32 v51, v219
	s_nop 0
	s_nop 1
	v_mov_b32_e32 v52, v220
	v_mov_b32_e32 v53, v221
	v_mov_b32_e32 v54, v222
	v_mov_b32_e32 v55, v223
	v_mov_b32_e32 v2, v48
	v_mov_b32_e32 v3, v50
	v_mov_b32_e32 v6, v52
	v_mov_b32_e32 v7, v54
	v_mov_b32_e32 v50, v49
	v_mov_b32_e32 v54, v53
	v_pk_mul_f32 v[48:49], v[96:97], v[2:3]
	v_pk_mul_f32 v[56:57], v[98:99], v[6:7]
	v_pk_mul_f32 v[52:53], v[92:93], v[50:51]
	v_pk_mul_f32 v[58:59], v[100:101], v[54:55]
	v_pk_mul_f32 v[2:3], v[106:107], v[2:3]
	v_pk_mul_f32 v[6:7], v[108:109], v[6:7]
	v_bfe_u32 v24, v48, 16, 1
	v_bfe_u32 v26, v49, 16, 1
	v_bfe_u32 v28, v56, 16, 1
	v_bfe_u32 v30, v57, 16, 1
	v_pk_mul_f32 v[50:51], v[64:65], v[50:51]
	v_pk_mul_f32 v[54:55], v[110:111], v[54:55]
	v_bfe_u32 v0, v59, 16, 1
	v_bfe_u32 v4, v58, 16, 1
	v_bfe_u32 v20, v53, 16, 1
	v_bfe_u32 v22, v52, 16, 1
	v_bfe_u32 v44, v2, 16, 1
	v_bfe_u32 v46, v3, 16, 1
	v_bfe_u32 v60, v6, 16, 1
	v_bfe_u32 v61, v7, 16, 1
	v_add3_u32 v30, v57, v30, s25
	v_add3_u32 v28, v56, v28, s25
	v_add3_u32 v26, v49, v26, s25
	v_add3_u32 v24, v48, v24, s25
	v_bfe_u32 v36, v55, 16, 1
	v_bfe_u32 v38, v54, 16, 1
	v_bfe_u32 v40, v51, 16, 1
	v_bfe_u32 v42, v50, 16, 1
	v_add3_u32 v22, v52, v22, s25
	v_add3_u32 v20, v53, v20, s25
	v_add3_u32 v4, v58, v4, s25
	v_add3_u32 v0, v59, v0, s25
	v_add3_u32 v7, v7, v61, s25
	v_add3_u32 v6, v6, v60, s25
	v_add3_u32 v3, v3, v46, s25
	v_add3_u32 v2, v2, v44, s25
	v_lshrrev_b32_e32 v24, 16, v24
	v_lshrrev_b32_e32 v26, 16, v26
	v_lshrrev_b32_e32 v28, 16, v28
	v_lshrrev_b32_e32 v30, 16, v30
	v_add3_u32 v42, v50, v42, s25
	v_add3_u32 v40, v51, v40, s25
	v_add3_u32 v38, v54, v38, s25
	v_add3_u32 v36, v55, v36, s25
	v_lshrrev_b32_e32 v2, 16, v2
	v_lshrrev_b32_e32 v3, 16, v3
	v_lshrrev_b32_e32 v6, 16, v6
	v_lshrrev_b32_e32 v7, 16, v7
	v_and_or_b32 v51, v0, s1, v30
	v_and_or_b32 v50, v4, s1, v28
	v_and_or_b32 v49, v20, s1, v26
	v_and_or_b32 v48, v22, s1, v24
	v_and_or_b32 v55, v36, s1, v7
	v_and_or_b32 v54, v38, s1, v6
	v_and_or_b32 v53, v40, s1, v3
	v_and_or_b32 v52, v42, s1, v2
	global_store_dwordx4 v[16:17], v[48:51], off
	global_store_dwordx4 v[18:19], v[52:55], off offset:2048
	s_nop 1
	v_mov_b32_e32 v48, v224
	v_mov_b32_e32 v49, v225
	v_mov_b32_e32 v50, v226
	v_mov_b32_e32 v51, v227
	s_nop 0
	s_nop 1
	v_mov_b32_e32 v52, v228
	v_mov_b32_e32 v53, v229
	v_mov_b32_e32 v54, v230
	v_mov_b32_e32 v55, v231
	v_mov_b32_e32 v30, v35
	v_mov_b32_e32 v28, v37
	v_mov_b32_e32 v26, v33
	v_mov_b32_e32 v22, v41
	v_mov_b32_e32 v24, v45
	v_mov_b32_e32 v0, v47
	v_mov_b32_e32 v4, v39
	v_pk_mul_f32 v[2:3], v[32:33], v[30:31] op_sel_hi:[0,1]
	v_pk_mul_f32 v[6:7], v[32:33], v[28:29] op_sel_hi:[0,1]
	v_pk_mul_f32 v[26:27], v[32:33], v[26:27] op_sel_hi:[0,1]
	v_mov_b32_e32 v20, v43
	v_pk_mul_f32 v[24:25], v[32:33], v[24:25] op_sel_hi:[0,1]
	v_pk_mul_f32 v[22:23], v[34:35], v[22:23] op_sel_hi:[0,1]
	v_pk_mul_f32 v[4:5], v[34:35], v[4:5] op_sel_hi:[0,1]
	v_pk_mul_f32 v[0:1], v[34:35], v[0:1] op_sel_hi:[0,1]
	v_pk_mul_f32 v[20:21], v[34:35], v[20:21] op_sel_hi:[0,1]
	v_mov_b32_e32 v28, v48
	v_mov_b32_e32 v29, v50
	v_mov_b32_e32 v30, v52
	v_mov_b32_e32 v31, v54
	v_mov_b32_e32 v50, v49
	v_mov_b32_e32 v54, v53
	v_pk_mul_f32 v[2:3], v[2:3], v[28:29]
	v_pk_mul_f32 v[26:27], v[26:27], v[30:31]
	v_pk_mul_f32 v[6:7], v[6:7], v[50:51]
	v_pk_mul_f32 v[24:25], v[24:25], v[54:55]
	v_pk_mul_f32 v[22:23], v[22:23], v[28:29]
	v_pk_mul_f32 v[4:5], v[4:5], v[30:31]
	v_pk_mul_f32 v[0:1], v[0:1], v[54:55]
	v_bfe_u32 v32, v2, 16, 1
	v_bfe_u32 v33, v3, 16, 1
	v_bfe_u32 v34, v26, 16, 1
	v_bfe_u32 v35, v27, 16, 1
	v_pk_mul_f32 v[20:21], v[20:21], v[50:51]
	v_bfe_u32 v28, v25, 16, 1
	v_bfe_u32 v29, v24, 16, 1
	v_bfe_u32 v30, v7, 16, 1
	v_bfe_u32 v31, v6, 16, 1
	v_bfe_u32 v36, v1, 16, 1
	v_bfe_u32 v37, v0, 16, 1
	v_bfe_u32 v40, v22, 16, 1
	v_bfe_u32 v41, v23, 16, 1
	v_bfe_u32 v42, v4, 16, 1
	v_bfe_u32 v43, v5, 16, 1
	v_add3_u32 v27, v27, v35, s25
	v_add3_u32 v26, v26, v34, s25
	v_add3_u32 v3, v3, v33, s25
	v_add3_u32 v2, v2, v32, s25
	v_bfe_u32 v38, v21, 16, 1
	v_bfe_u32 v39, v20, 16, 1
	v_add3_u32 v6, v6, v31, s25
	v_add3_u32 v7, v7, v30, s25
	v_add3_u32 v24, v24, v29, s25
	v_add3_u32 v25, v25, v28, s25
	v_add3_u32 v28, v0, v37, s25
	v_add3_u32 v29, v1, v36, s25
	v_add3_u32 v0, v5, v43, s25
	v_add3_u32 v1, v4, v42, s25
	v_add3_u32 v4, v23, v41, s25
	v_add3_u32 v5, v22, v40, s25
	v_lshrrev_b32_e32 v22, 16, v2
	v_lshrrev_b32_e32 v23, 16, v3
	v_lshrrev_b32_e32 v2, 16, v26
	v_lshrrev_b32_e32 v3, 16, v27
	v_add3_u32 v20, v20, v39, s25
	v_add3_u32 v21, v21, v38, s25
	v_lshrrev_b32_e32 v26, 16, v5
	v_lshrrev_b32_e32 v4, 16, v4
	v_lshrrev_b32_e32 v5, 16, v1
	v_lshrrev_b32_e32 v27, 16, v0
	v_and_or_b32 v3, v25, s1, v3
	v_and_or_b32 v2, v24, s1, v2
	v_and_or_b32 v1, v7, s1, v23
	v_and_or_b32 v0, v6, s1, v22
	v_and_or_b32 v7, v29, s1, v27
	v_and_or_b32 v6, v28, s1, v5
	v_and_or_b32 v5, v21, s1, v4
	v_and_or_b32 v4, v20, s1, v26
	global_store_dwordx4 v[16:17], v[0:3], off offset:1024
	global_store_dwordx4 v[18:19], v[4:7], off offset:3072
	s_cbranch_scc0 .LBB0_306

; __device__ __forceinline__ unsigned pk2(float lo, float hi) { return f2bf(lo) | (f2bf(hi) << 16); }
; __device__ __forceinline__ void rms_rows2_b2b(const bf16* x0, const bf16* x1, const float* g, bf16* o0, bf16* o1, int lane) {
;     const v4u* xr0 = (const v4u*)x0 + lane; const v4u* xr1 = (const v4u*)x1 + lane; const f32x4* gr = (const f32x4*)g + 2 * lane;
;     v4u v[4], w[4]; float s = 0.f, t = 0.f;
; #pragma unroll
;     for (int j = 0; j < 4; ++j) { v[j] = xr0[64 * j]; w[j] = xr1[64 * j]; }
; #pragma unroll
;     for (int j = 0; j < 4; ++j) {
;         s += (bflo(v[j].x) * bflo(v[j].x) + bfhi(v[j].x) * bfhi(v[j].x)) + (bflo(v[j].y) * bflo(v[j].y) + bfhi(v[j].y) * bfhi(v[j].y)) + (bflo(v[j].z) * bflo(v[j].z) + bfhi(v[j].z) * bfhi(v[j].z)) + (bflo(v[j].w) * bflo(v[j].w) + bfhi(v[j].w) * bfhi(v[j].w));
;         t += (bflo(w[j].x) * bflo(w[j].x) + bfhi(w[j].x) * bfhi(w[j].x)) + (bflo(w[j].y) * bflo(w[j].y) + bfhi(w[j].y) * bfhi(w[j].y)) + (bflo(w[j].z) * bflo(w[j].z) + bfhi(w[j].z) * bfhi(w[j].z)) + (bflo(w[j].w) * bflo(w[j].w) + bfhi(w[j].w) * bfhi(w[j].w)); }
;     const float rs = 1.f / sqrtf(wave_sum(s, lane) * (1.f / D) + NORM_EPS), rt = 1.f / sqrtf(wave_sum(t, lane) * (1.f / D) + NORM_EPS);
;     v4u* p0 = (v4u*)o0 + lane; v4u* p1 = (v4u*)o1 + lane;
; #pragma unroll
;     for (int j = 0; j < 4; ++j) { const f32x4 ga = gr[128 * j], gb = gr[128 * j + 1];
;         v4u a, b;
;         a.x = pk2(bflo(v[j].x) * rs * ga.x, bfhi(v[j].x) * rs * ga.y); a.y = pk2(bflo(v[j].y) * rs * ga.z, bfhi(v[j].y) * rs * ga.w); a.z = pk2(bflo(v[j].z) * rs * gb.x, bfhi(v[j].z) * rs * gb.y); a.w = pk2(bflo(v[j].w) * rs * gb.z, bfhi(v[j].w) * rs * gb.w);
;         b.x = pk2(bflo(w[j].x) * rt * ga.x, bfhi(w[j].x) * rt * ga.y); b.y = pk2(bflo(w[j].y) * rt * ga.z, bfhi(w[j].y) * rt * ga.w); b.z = pk2(bflo(w[j].z) * rt * gb.x, bfhi(w[j].z) * rt * gb.y); b.w = pk2(bflo(w[j].w) * rt * gb.z, bfhi(w[j].w) * rt * gb.w);
;         p0[64 * j] = a; p1[64 * j] = b; }
; __global__ void __launch_bounds__(NWAVES * 64, 2) mega_fwd(Args args) {
;     ...
;     { LOCAL_IDS(); for (int m = gw; m < M / 2; m += NGW) rms_rows2_b2b(HB + (size_t)m * D, HB + (size_t)(m + M / 2) * D, ln_mix + D, XN + (size_t)m * D, XN + (size_t)(m + M / 2) * D, lane); }
.LBB0_663:
	s_or_b64 exec, exec, s[6:7]
	s_waitcnt lgkmcnt(0)
	v_mov_b32_e32 v0, v248
	s_barrier
	s_nop 0
	v_readfirstlane_b32 s0, v0
	s_ashr_i32 s1, s0, 6
	v_readlane_b32 s0, v255, 1
	s_add_i32 s0, s1, s0
	s_cmpk_gt_i32 s0, 0x1fff
	s_cbranch_scc1 .LBB0_666
	v_and_b32_e32 v2, 63, v0
	v_lshlrev_b32_e32 v8, 5, v2
	v_mov_b32_e32 v9, 0
	v_lshl_add_u64 v[0:1], s[38:39], 0, v[8:9]
	s_mov_b64 s[4:5], 0x2000
	v_lshl_add_u64 v[10:11], v[0:1], 0, s[4:5]
	s_mov_b64 s[4:5], 0x3000
	v_lshl_add_u64 v[12:13], v[0:1], 0, s[4:5]
	s_mov_b64 s[4:5], 0x3800
	v_lshl_add_u64 v[14:15], v[0:1], 0, s[4:5]
	s_add_i32 s4, s0, 0x2000
	s_ashr_i32 s5, s4, 31
	s_lshl_b64 s[4:5], s[4:5], 12
	s_add_u32 s38, s54, s4
	s_addc_u32 s39, s55, s5
	s_ashr_i32 s35, s34, 31
	v_readlane_b32 s6, v255, 1
	s_lshl_b64 s[48:49], s[34:35], 12
	s_ashr_i32 s7, s1, 31
	s_ashr_i32 s8, s6, 31
	s_add_u32 s6, s1, s6
	s_addc_u32 s7, s7, s8
	s_lshl_b64 s[6:7], s[6:7], 12
	s_add_u32 s60, s52, s6
	s_addc_u32 s61, s53, s7
	s_add_u32 s62, s52, s4
	s_addc_u32 s63, s53, s5
	s_add_u32 s1, s54, s6
	s_addc_u32 s4, s55, s7
	v_lshlrev_b32_e32 v3, 2, v2
	s_add_u32 s64, s1, 0xc000800
	v_xor_b32_e32 v70, 4, v3
	v_xor_b32_e32 v71, 8, v3
	v_xor_b32_e32 v72, 16, v3
	v_xor_b32_e32 v73, 32, v3
	v_xor_b32_e32 v74, 64, v3
	v_xor_b32_e32 v75, 0x80, v3
	v_lshlrev_b32_e32 v8, 4, v2
	s_addc_u32 s65, s4, 0
	s_mov_b32 s1, 0xffff0000
	v_mov_b32_e32 v76, 0x358637bd
	s_mov_b32 s4, 0xf800000
	v_mov_b32_e32 v77, 0x260
	s_movk_i32 s5, 0x7fff
	s_brev_b32 s14, 48
	global_load_dwordx4 v[200:203], v[10:11], off offset:16
	global_load_dwordx4 v[204:207], v[10:11], off
	global_load_dwordx4 v[208:211], v[10:11], off offset:2048
	global_load_dwordx4 v[212:215], v[10:11], off offset:2064
	global_load_dwordx4 v[216:219], v[12:13], off
	global_load_dwordx4 v[220:223], v[12:13], off offset:16
	global_load_dwordx4 v[224:227], v[14:15], off
	global_load_dwordx4 v[228:231], v[14:15], off offset:16
	s_waitcnt vmcnt(0)
.LBB0_665:
	v_lshl_add_u64 v[18:19], s[60:61], 0, v[8:9]
	s_nop 1
	v_mov_b32_e32 v0, v200
	v_mov_b32_e32 v1, v201
	v_mov_b32_e32 v2, v202
	v_mov_b32_e32 v3, v203
	s_nop 1
	v_mov_b32_e32 v4, v204
	v_mov_b32_e32 v5, v205
	v_mov_b32_e32 v6, v206
	v_mov_b32_e32 v7, v207
	v_lshl_add_u64 v[20:21], s[62:63], 0, v[8:9]
	global_load_dwordx4 v[24:27], v[18:19], off offset:1024
	global_load_dwordx4 v[28:31], v[20:21], off offset:1024
	global_load_dwordx4 v[36:39], v[18:19], off offset:2048
	global_load_dwordx4 v[42:45], v[20:21], off offset:2048
	global_load_dwordx4 v[78:81], v[18:19], off offset:3072
	global_load_dwordx4 v[82:85], v[20:21], off offset:3072
	global_load_dwordx4 v[32:35], v[18:19], off
	global_load_dwordx4 v[86:89], v[20:21], off
	v_lshl_add_u64 v[22:23], s[38:39], 0, v[8:9]
	v_add_co_u32_e32 v18, vcc, s14, v22
	v_lshl_add_u64 v[16:17], s[64:65], 0, v[8:9]
	s_nop 0
	v_addc_co_u32_e32 v19, vcc, 0, v23, vcc
	s_add_i32 s0, s0, s34
	s_add_u32 s38, s38, s48
	s_addc_u32 s39, s39, s49
	s_add_u32 s60, s60, s48
	s_addc_u32 s61, s61, s49
	s_add_u32 s62, s62, s48
	s_addc_u32 s63, s63, s49
	s_add_u32 s64, s64, s48
	s_addc_u32 s65, s65, s49
	s_cmpk_gt_i32 s0, 0x1fff
	s_waitcnt vmcnt(7)
	v_and_b32_e32 v63, 0xffff0000, v25
	v_and_b32_e32 v62, 0xffff0000, v24
	s_waitcnt vmcnt(5)
	v_and_b32_e32 v91, 0xffff0000, v36
	v_lshlrev_b32_e32 v92, 16, v37
	v_and_b32_e32 v93, 0xffff0000, v37
	s_waitcnt vmcnt(4)
	v_and_b32_e32 v95, 0xffff0000, v42
	s_waitcnt vmcnt(1)
	v_and_b32_e32 v98, 0xffff0000, v32
	v_and_b32_e32 v102, 0xffff0000, v34
	v_and_b32_e32 v65, 0xffff0000, v43
	v_lshlrev_b32_e32 v97, 16, v33
	v_lshlrev_b32_e32 v96, 16, v32
	v_and_b32_e32 v99, 0xffff0000, v33
	v_lshlrev_b32_e32 v101, 16, v35
	v_lshlrev_b32_e32 v100, 16, v34
	v_and_b32_e32 v103, 0xffff0000, v35
	v_lshlrev_b32_e32 v35, 16, v78
	v_and_b32_e32 v37, 0xffff0000, v78
	v_pk_mov_b32 v[46:47], v[38:39], v[80:81] op_sel:[1,0]
	v_lshlrev_b32_e32 v33, 16, v80
	s_waitcnt vmcnt(0)
	v_lshlrev_b32_e32 v78, 16, v86
	v_and_b32_e32 v80, 0xffff0000, v86
	v_lshlrev_b32_e32 v86, 16, v88
	v_and_b32_e32 v88, 0xffff0000, v88
	v_mov_b32_e32 v114, v102
	v_mov_b32_e32 v115, v98
	v_mov_b32_e32 v48, v4
	v_mov_b32_e32 v49, v6
	v_mov_b32_e32 v6, v5
	v_mov_b32_e32 v50, v0
	v_mov_b32_e32 v51, v2
	v_mov_b32_e32 v2, v1
	v_lshlrev_b32_e32 v61, 16, v25
	v_lshlrev_b32_e32 v60, 16, v24
	v_lshlrev_b32_e32 v67, 16, v27
	v_lshlrev_b32_e32 v66, 16, v26
	v_and_b32_e32 v69, 0xffff0000, v27
	v_and_b32_e32 v68, 0xffff0000, v26
	v_lshlrev_b32_e32 v53, 16, v29
	v_lshlrev_b32_e32 v52, 16, v28
	v_and_b32_e32 v55, 0xffff0000, v29
	v_and_b32_e32 v54, 0xffff0000, v28
	v_lshlrev_b32_e32 v57, 16, v31
	v_and_b32_e32 v59, 0xffff0000, v31
	v_lshlrev_b32_e32 v90, 16, v36
	v_lshlrev_b32_e32 v94, 16, v42
	v_lshlrev_b32_e32 v64, 16, v43
	v_lshlrev_b32_e32 v31, 16, v79
	v_and_b32_e32 v29, 0xffff0000, v79
	v_lshlrev_b32_e32 v27, 16, v81
	v_and_b32_e32 v25, 0xffff0000, v81
	v_lshlrev_b32_e32 v23, 16, v83
	v_and_b32_e32 v21, 0xffff0000, v83
	v_lshlrev_b32_e32 v5, 16, v85
	v_and_b32_e32 v1, 0xffff0000, v85
	v_lshlrev_b32_e32 v32, 16, v39
	v_lshlrev_b32_e32 v79, 16, v87
	v_and_b32_e32 v81, 0xffff0000, v87
	v_lshlrev_b32_e32 v41, 16, v82
	v_and_b32_e32 v43, 0xffff0000, v82
	v_pk_mov_b32 v[82:83], v[44:45], v[84:85] op_sel:[1,0]
	v_lshlrev_b32_e32 v39, 16, v84
	v_pk_mul_f32 v[84:85], v[62:63], v[62:63]
	v_mov_b32_e32 v110, v97
	v_mov_b32_e32 v111, v99
	v_mul_f32_e32 v0, v99, v99
	v_mov_b32_e32 v112, v100
	v_mov_b32_e32 v113, v96
	v_mul_f32_e32 v4, v91, v91
	v_mul_f32_e32 v20, v93, v93
	v_mov_b32_e32 v126, v88
	v_mov_b32_e32 v127, v80
	v_mul_f32_e32 v26, v95, v95
	v_mul_f32_e32 v28, v65, v65
	v_pk_mul_f32 v[114:115], v[114:115], v[114:115]
; __device__ __forceinline__ void rms_rows2_b2b(const bf16* x0, const bf16* x1, const float* g, bf16* o0, bf16* o1, int lane) {
;     ...
;     for (int j = 0; j < 4; ++j) { v[j] = xr0[64 * j]; w[j] = xr1[64 * j]; }
; #pragma unroll
;     for (int j = 0; j < 4; ++j) {
;         s += (bflo(v[j].x) * bflo(v[j].x) + bfhi(v[j].x) * bfhi(v[j].x)) + (bflo(v[j].y) * bflo(v[j].y) + bfhi(v[j].y) * bfhi(v[j].y)) + (bflo(v[j].z) * bflo(v[j].z) + bfhi(v[j].z) * bfhi(v[j].z)) + (bflo(v[j].w) * bflo(v[j].w) + bfhi(v[j].w) * bfhi(v[j].w));
;         t += (bflo(w[j].x) * bflo(w[j].x) + bfhi(w[j].x) * bfhi(w[j].x)) + (bflo(w[j].y) * bflo(w[j].y) + bfhi(w[j].y) * bfhi(w[j].y)) + (bflo(w[j].z) * bflo(w[j].z) + bfhi(w[j].z) * bfhi(w[j].z)) + (bflo(w[j].w) * bflo(w[j].w) + bfhi(w[j].w) * bfhi(w[j].w)); }
;     const float rs = 1.f / sqrtf(wave_sum(s, lane) * (1.f / D) + NORM_EPS), rt = 1.f / sqrtf(wave_sum(t, lane) * (1.f / D) + NORM_EPS);
	v_and_b32_e32 v36, 0xffff0000, v38
	v_pk_mul_f32 v[104:105], v[68:69], v[68:69]
	v_mul_f32_e32 v120, v31, v31
	v_mul_f32_e32 v156, v29, v29
	v_mov_b32_e32 v122, v79
	v_mov_b32_e32 v123, v81
	v_mul_f32_e32 v24, v81, v81
	v_mov_b32_e32 v124, v86
	v_mov_b32_e32 v125, v78
	v_mov_b32_e32 v138, v94
	v_mov_b32_e32 v139, v64
	v_pk_fma_f32 v[84:85], v[60:61], v[60:61], v[84:85]
	v_pk_fma_f32 v[110:111], v[110:111], v[110:111], v[0:1] op_sel_hi:[1,1,0]
	v_pk_fma_f32 v[144:145], v[90:91], v[90:91], v[4:5] op_sel_hi:[1,1,0]
	v_pk_fma_f32 v[146:147], v[92:93], v[92:93], v[20:21] op_sel_hi:[1,1,0]
	v_pk_mul_f32 v[126:127], v[126:127], v[126:127]
	v_pk_fma_f32 v[150:151], v[94:95], v[94:95], v[26:27] op_sel_hi:[1,1,0]
	v_pk_fma_f32 v[152:153], v[64:65], v[64:65], v[28:29] op_sel_hi:[1,1,0]
	v_mov_b32_e32 v64, v95
	v_pk_fma_f32 v[94:95], v[112:113], v[112:113], v[114:115]
	v_and_b32_e32 v58, 0xffff0000, v30
	v_lshlrev_b32_e32 v34, 16, v38
	v_lshlrev_b32_e32 v87, 16, v89
	v_and_b32_e32 v89, 0xffff0000, v89
	v_lshlrev_b32_e32 v40, 16, v44
	v_and_b32_e32 v42, 0xffff0000, v44
	v_lshlrev_b32_e32 v38, 16, v45
	v_pk_mul_f32 v[106:107], v[54:55], v[54:55]
	v_mov_b32_e32 v116, v101
	v_mov_b32_e32 v117, v103
	v_pk_mul_f32 v[118:119], v[36:37], v[36:37]
	v_and_b32_e32 v45, 0xffff0000, v47
	v_and_b32_e32 v44, 0xffff0000, v46
	v_mul_f32_e32 v22, v103, v103
	v_pk_fma_f32 v[104:105], v[66:67], v[66:67], v[104:105]
	v_pk_fma_f32 v[122:123], v[122:123], v[122:123], v[24:25] op_sel_hi:[1,1,0]
	v_pk_add_f32 v[84:85], v[84:85], v[84:85] op_sel:[0,1] op_sel_hi:[1,0]
	v_mov_b32_e32 v145, v120
	v_mov_b32_e32 v147, v156
	v_pk_fma_f32 v[112:113], v[124:125], v[124:125], v[126:127]
	v_pk_add_f32 v[110:111], v[94:95], v[110:111] op_sel:[1,0] op_sel_hi:[0,1]
	v_lshlrev_b32_e32 v56, 16, v30
	v_pk_mul_f32 v[108:109], v[58:59], v[58:59]
	v_mov_b32_e32 v128, v87
	v_mov_b32_e32 v129, v89
	v_mul_f32_e32 v30, v89, v89
	v_pk_fma_f32 v[106:107], v[52:53], v[52:53], v[106:107]
	v_pk_fma_f32 v[118:119], v[34:35], v[34:35], v[118:119]
	v_pk_mul_f32 v[148:149], v[44:45], v[44:45]
	v_pk_fma_f32 v[116:117], v[116:117], v[116:117], v[22:23] op_sel_hi:[1,1,0]
	v_pk_add_f32 v[84:85], v[104:105], v[84:85]
	v_pk_add_f32 v[124:125], v[144:145], v[146:147]
	v_pk_add_f32 v[122:123], v[112:113], v[122:123] op_sel:[1,0] op_sel_hi:[0,1]
	v_pk_add_f32 v[94:95], v[94:95], v[110:111]
	v_mul_f32_e32 v158, v23, v23
	v_mul_f32_e32 v159, v21, v21
	v_mov_b32_e32 v121, v27
	v_mov_b32_e32 v132, v90
	v_mov_b32_e32 v133, v92
	v_pk_fma_f32 v[108:109], v[56:57], v[56:57], v[108:109]
	v_pk_fma_f32 v[128:129], v[128:129], v[128:129], v[30:31] op_sel_hi:[1,1,0]
	v_mov_b32_e32 v92, v91
	v_pk_add_f32 v[90:91], v[106:107], v[106:107] op_sel:[0,1] op_sel_hi:[1,0]
	v_pk_fma_f32 v[106:107], v[32:33], v[32:33], v[148:149]
	v_mov_b32_e32 v26, v116
	v_pk_add_f32 v[110:111], v[118:119], v[124:125]
	v_pk_add_f32 v[84:85], v[104:105], v[84:85] op_sel:[1,0] op_sel_hi:[0,1]
	v_pk_add_f32 v[104:105], v[112:113], v[122:123]
	v_mov_b32_e32 v120, v94
	v_mul_f32_e32 v157, v25, v25
	v_pk_mul_f32 v[130:131], v[42:43], v[42:43]
	v_and_b32_e32 v47, 0xffff0000, v83
	v_and_b32_e32 v46, 0xffff0000, v82
	v_mov_b32_e32 v83, v5
	v_mov_b32_e32 v151, v158
	v_mov_b32_e32 v153, v159
	v_mov_b32_e32 v4, v128
	v_pk_add_f32 v[90:91], v[108:109], v[90:91]
	v_pk_add_f32 v[106:107], v[106:107], v[110:111]
	v_pk_add_f32 v[94:95], v[116:117], v[94:95]
	v_mov_b32_e32 v82, v104
	v_pk_mul_f32 v[110:111], v[26:27], v[120:121]
	v_mul_f32_e32 v160, v1, v1
	v_pk_fma_f32 v[130:131], v[40:41], v[40:41], v[130:131]
	v_pk_mul_f32 v[154:155], v[46:47], v[46:47]
	v_pk_add_f32 v[126:127], v[150:151], v[152:153]
	v_pk_add_f32 v[90:91], v[108:109], v[90:91] op_sel:[1,0] op_sel_hi:[0,1]
	v_mov_b32_e32 v85, v157
	v_pk_add_f32 v[104:105], v[128:129], v[104:105]
	v_pk_mul_f32 v[82:83], v[4:5], v[82:83]
	v_mov_b32_e32 v95, v111
	v_pk_fma_f32 v[114:115], v[38:39], v[38:39], v[154:155]
	v_pk_add_f32 v[112:113], v[130:131], v[126:127]
	v_mov_b32_e32 v91, v160
	v_mov_b32_e32 v105, v83
	v_pk_add_f32 v[82:83], v[94:95], v[84:85]
	v_pk_add_f32 v[108:109], v[114:115], v[112:113]
	v_pk_add_f32 v[84:85], v[104:105], v[90:91]
	v_pk_add_f32 v[82:83], v[82:83], v[106:107]
	v_pk_add_f32 v[84:85], v[84:85], v[108:109]
	v_add_f32_e32 v0, v82, v83
	v_add_f32_e32 v4, v84, v85
	ds_bpermute_b32 v20, v70, v0
	ds_bpermute_b32 v22, v70, v4
	v_mov_b32_e32 v135, v32
	v_mov_b32_e32 v134, v34
	v_mov_b32_e32 v136, v36
	s_waitcnt lgkmcnt(1)
	v_add_f32_e32 v0, v0, v20
	s_waitcnt lgkmcnt(0)
	v_add_f32_e32 v4, v4, v22
	ds_bpermute_b32 v20, v71, v0
	ds_bpermute_b32 v22, v71, v4
	v_mov_b32_e32 v141, v38
	v_mov_b32_e32 v140, v40
	v_mov_b32_e32 v142, v42
	s_waitcnt lgkmcnt(1)
	v_add_f32_e32 v0, v0, v20
	s_waitcnt lgkmcnt(0)
	v_add_f32_e32 v4, v4, v22
	ds_bpermute_b32 v20, v72, v0
	ds_bpermute_b32 v22, v72, v4
	v_mov_b32_e32 v137, v44
	v_mov_b32_e32 v143, v46
	s_waitcnt lgkmcnt(1)
	v_add_f32_e32 v0, v0, v20
	s_waitcnt lgkmcnt(0)
	v_add_f32_e32 v4, v4, v22
	ds_bpermute_b32 v20, v73, v0
	ds_bpermute_b32 v22, v73, v4
	s_waitcnt lgkmcnt(1)
	v_add_f32_e32 v0, v0, v20
	s_waitcnt lgkmcnt(0)
	v_add_f32_e32 v4, v4, v22
	ds_bpermute_b32 v20, v74, v0
	ds_bpermute_b32 v22, v74, v4
	s_waitcnt lgkmcnt(1)
	v_add_f32_e32 v0, v0, v20
	s_waitcnt lgkmcnt(0)
	v_add_f32_e32 v4, v4, v22
	ds_bpermute_b32 v20, v75, v0
	ds_bpermute_b32 v22, v75, v4
	s_waitcnt lgkmcnt(1)
	v_add_f32_e32 v0, v0, v20
	s_waitcnt lgkmcnt(0)
; __device__ __forceinline__ unsigned pk2(float lo, float hi) { return f2bf(lo) | (f2bf(hi) << 16); }
; __device__ __forceinline__ void rms_rows2_b2b(const bf16* x0, const bf16* x1, const float* g, bf16* o0, bf16* o1, int lane) {
;     ...
;     const float rs = 1.f / sqrtf(wave_sum(s, lane) * (1.f / D) + NORM_EPS), rt = 1.f / sqrtf(wave_sum(t, lane) * (1.f / D) + NORM_EPS);
;     v4u* p0 = (v4u*)o0 + lane; v4u* p1 = (v4u*)o1 + lane;
; #pragma unroll
;     for (int j = 0; j < 4; ++j) { const f32x4 ga = gr[128 * j], gb = gr[128 * j + 1];
;         v4u a, b;
;         a.x = pk2(bflo(v[j].x) * rs * ga.x, bfhi(v[j].x) * rs * ga.y); a.y = pk2(bflo(v[j].y) * rs * ga.z, bfhi(v[j].y) * rs * ga.w); a.z = pk2(bflo(v[j].z) * rs * gb.x, bfhi(v[j].z) * rs * gb.y); a.w = pk2(bflo(v[j].w) * rs * gb.z, bfhi(v[j].w) * rs * gb.w);
;         b.x = pk2(bflo(w[j].x) * rt * ga.x, bfhi(w[j].x) * rt * ga.y); b.y = pk2(bflo(w[j].y) * rt * ga.z, bfhi(w[j].y) * rt * ga.w); b.z = pk2(bflo(w[j].z) * rt * gb.x, bfhi(w[j].z) * rt * gb.y); b.w = pk2(bflo(w[j].w) * rt * gb.z, bfhi(w[j].w) * rt * gb.w);
;         p0[64 * j] = a; p1[64 * j] = b; }
	v_add_f32_e32 v4, v4, v22
	v_fmamk_f32 v0, v0, 0x3a000000, v76
	v_fmamk_f32 v4, v4, 0x3a000000, v76
	v_mul_f32_e32 v20, 0x4f800000, v0
	v_cmp_gt_f32_e64 s[6:7], s4, v0
	v_mul_f32_e32 v22, 0x4f800000, v4
	v_cmp_gt_f32_e32 vcc, s4, v4
	v_cndmask_b32_e64 v0, v0, v20, s[6:7]
	v_sqrt_f32_e32 v20, v0
	v_cndmask_b32_e32 v4, v4, v22, vcc
	v_sqrt_f32_e32 v22, v4
	v_add_u32_e32 v24, -1, v20
	v_add_u32_e32 v26, 1, v20
	v_add_u32_e32 v28, -1, v22
	v_fma_f32 v32, -v24, v20, v0
	v_add_u32_e32 v30, 1, v22
	v_fma_f32 v34, -v26, v20, v0
	v_fma_f32 v36, -v28, v22, v4
	v_cmp_ge_f32_e64 s[8:9], 0, v32
	v_fma_f32 v38, -v30, v22, v4
	v_cmp_lt_f32_e64 s[10:11], 0, v34
	v_cndmask_b32_e64 v20, v20, v24, s[8:9]
	v_cmp_ge_f32_e64 s[8:9], 0, v36
	v_cndmask_b32_e64 v20, v20, v26, s[10:11]
	v_mul_f32_e32 v24, 0x37800000, v20
	v_cndmask_b32_e64 v22, v22, v28, s[8:9]
	v_cmp_lt_f32_e64 s[8:9], 0, v38
	v_cndmask_b32_e64 v20, v20, v24, s[6:7]
	v_cmp_class_f32_e64 s[6:7], v0, v77
	v_cndmask_b32_e64 v22, v22, v30, s[8:9]
	v_mul_f32_e32 v26, 0x37800000, v22
	v_cndmask_b32_e32 v22, v22, v26, vcc
	v_cmp_class_f32_e32 vcc, v4, v77
	v_cndmask_b32_e64 v0, v20, v0, s[6:7]
	v_div_scale_f32 v20, s[6:7], v0, v0, 1.0
	v_cndmask_b32_e32 v4, v22, v4, vcc
	v_div_scale_f32 v24, s[6:7], v4, v4, 1.0
	v_rcp_f32_e32 v28, v20
	v_rcp_f32_e32 v30, v24
	v_div_scale_f32 v22, vcc, 1.0, v0, 1.0
	v_fma_f32 v32, -v20, v28, 1.0
	v_fma_f32 v34, -v24, v30, 1.0
	v_fmac_f32_e32 v28, v32, v28
	v_div_scale_f32 v26, s[6:7], 1.0, v4, 1.0
	v_fmac_f32_e32 v30, v34, v30
	v_mul_f32_e32 v32, v22, v28
	v_mul_f32_e32 v34, v26, v30
	v_fma_f32 v36, -v20, v32, v22
	v_fma_f32 v38, -v24, v34, v26
	v_fmac_f32_e32 v32, v36, v28
	v_fmac_f32_e32 v34, v38, v30
	v_fma_f32 v20, -v20, v32, v22
	v_fma_f32 v22, -v24, v34, v26
	v_div_fmas_f32 v20, v20, v28, v32
	s_mov_b64 vcc, s[6:7]
	v_div_fixup_f32 v32, v20, v0, 1.0
	v_div_fmas_f32 v0, v22, v30, v34
	v_pk_mul_f32 v[82:83], v[32:33], v[96:97] op_sel_hi:[0,1]
	v_pk_mul_f32 v[90:91], v[32:33], v[100:101] op_sel_hi:[0,1]
	v_div_fixup_f32 v34, v0, v4, 1.0
	v_pk_mul_f32 v[84:85], v[32:33], v[98:99] op_sel_hi:[0,1]
	v_pk_mul_f32 v[94:95], v[32:33], v[102:103] op_sel_hi:[0,1]
	v_pk_mul_f32 v[82:83], v[48:49], v[82:83]
	v_pk_mul_f32 v[90:91], v[50:51], v[90:91]
	v_pk_mul_f32 v[78:79], v[34:35], v[78:79] op_sel_hi:[0,1]
	v_pk_mul_f32 v[80:81], v[34:35], v[80:81] op_sel_hi:[0,1]
	v_pk_mul_f32 v[86:87], v[34:35], v[86:87] op_sel_hi:[0,1]
	v_pk_mul_f32 v[88:89], v[34:35], v[88:89] op_sel_hi:[0,1]
	v_pk_mul_f32 v[84:85], v[6:7], v[84:85]
	v_pk_mul_f32 v[94:95], v[2:3], v[94:95]
	v_bfe_u32 v24, v82, 16, 1
	v_bfe_u32 v26, v83, 16, 1
	v_bfe_u32 v28, v90, 16, 1
	v_bfe_u32 v30, v91, 16, 1
	v_pk_mul_f32 v[48:49], v[48:49], v[78:79]
	v_pk_mul_f32 v[6:7], v[6:7], v[80:81]
	v_pk_mul_f32 v[50:51], v[50:51], v[86:87]
	v_pk_mul_f32 v[2:3], v[2:3], v[88:89]
	v_pk_mul_f32 v[102:103], v[34:35], v[52:53] op_sel_hi:[0,1]
	v_bfe_u32 v0, v95, 16, 1
	v_bfe_u32 v4, v94, 16, 1
	v_bfe_u32 v20, v85, 16, 1
	v_bfe_u32 v22, v84, 16, 1
	v_add3_u32 v30, v91, v30, s5
	v_add3_u32 v28, v90, v28, s5
	v_add3_u32 v26, v83, v26, s5
	v_add3_u32 v24, v82, v24, s5
	v_bfe_u32 v36, v3, 16, 1
	v_bfe_u32 v38, v2, 16, 1
	v_bfe_u32 v40, v7, 16, 1
	v_bfe_u32 v42, v6, 16, 1
	v_bfe_u32 v44, v48, 16, 1
	v_bfe_u32 v46, v49, 16, 1
	v_bfe_u32 v52, v50, 16, 1
	v_bfe_u32 v53, v51, 16, 1
	v_add3_u32 v22, v84, v22, s5
	v_add3_u32 v20, v85, v20, s5
	v_add3_u32 v4, v94, v4, s5
	v_add3_u32 v0, v95, v0, s5
	v_lshrrev_b32_e32 v24, 16, v24
	v_lshrrev_b32_e32 v26, 16, v26
	v_lshrrev_b32_e32 v28, 16, v28
	v_lshrrev_b32_e32 v30, 16, v30
	v_add3_u32 v6, v6, v42, s5
	v_add3_u32 v7, v7, v40, s5
	v_add3_u32 v2, v2, v38, s5
	v_add3_u32 v3, v3, v36, s5
	v_add3_u32 v36, v51, v53, s5
	v_add3_u32 v38, v50, v52, s5
	v_add3_u32 v40, v49, v46, s5
	v_add3_u32 v42, v48, v44, s5
	v_and_or_b32 v51, v0, s1, v30
	v_and_or_b32 v50, v4, s1, v28
	v_and_or_b32 v49, v20, s1, v26
	v_and_or_b32 v48, v22, s1, v24
	v_lshrrev_b32_e32 v0, 16, v42
	v_lshrrev_b32_e32 v4, 16, v40
	v_lshrrev_b32_e32 v20, 16, v38
	v_lshrrev_b32_e32 v22, 16, v36
	v_pk_mul_f32 v[104:105], v[34:35], v[54:55] op_sel_hi:[0,1]
	v_and_or_b32 v55, v3, s1, v22
	v_and_or_b32 v54, v2, s1, v20
	v_and_or_b32 v53, v7, s1, v4
	v_and_or_b32 v52, v6, s1, v0
	global_store_dwordx4 v[16:17], v[48:51], off offset:-2048
	global_store_dwordx4 v[18:19], v[52:55], off
	s_nop 1
	v_mov_b32_e32 v48, v208
	v_mov_b32_e32 v49, v209
	v_mov_b32_e32 v50, v210
	v_mov_b32_e32 v51, v211
	s_nop 0
	s_nop 1
	v_mov_b32_e32 v52, v212
	v_mov_b32_e32 v53, v213
	v_mov_b32_e32 v54, v214
	v_mov_b32_e32 v55, v215
	v_pk_mul_f32 v[60:61], v[32:33], v[60:61] op_sel_hi:[0,1]
	v_pk_mul_f32 v[66:67], v[32:33], v[66:67] op_sel_hi:[0,1]
	v_pk_mul_f32 v[62:63], v[32:33], v[62:63] op_sel_hi:[0,1]
	v_pk_mul_f32 v[68:69], v[32:33], v[68:69] op_sel_hi:[0,1]
	v_pk_mul_f32 v[56:57], v[34:35], v[56:57] op_sel_hi:[0,1]
	v_pk_mul_f32 v[58:59], v[34:35], v[58:59] op_sel_hi:[0,1]
	v_pk_mul_f32 v[96:97], v[32:33], v[132:133] op_sel_hi:[0,1]
	v_pk_mul_f32 v[98:99], v[32:33], v[134:135] op_sel_hi:[0,1]
	v_pk_mul_f32 v[92:93], v[32:33], v[92:93] op_sel_hi:[0,1]
	v_pk_mul_f32 v[100:101], v[32:33], v[136:137] op_sel_hi:[0,1]
	v_pk_mul_f32 v[106:107], v[34:35], v[138:139] op_sel_hi:[0,1]
	v_pk_mul_f32 v[108:109], v[34:35], v[140:141] op_sel_hi:[0,1]
	v_pk_mul_f32 v[64:65], v[34:35], v[64:65] op_sel_hi:[0,1]
	v_pk_mul_f32 v[110:111], v[34:35], v[142:143] op_sel_hi:[0,1]
	v_mov_b32_e32 v2, v48
	v_mov_b32_e32 v3, v50
	v_mov_b32_e32 v6, v52
	v_mov_b32_e32 v7, v54
	v_mov_b32_e32 v50, v49
	v_mov_b32_e32 v54, v53
	v_pk_mul_f32 v[48:49], v[2:3], v[60:61]
	v_pk_mul_f32 v[60:61], v[66:67], v[6:7]
; __device__ __forceinline__ unsigned pk2(float lo, float hi) { return f2bf(lo) | (f2bf(hi) << 16); }
; __device__ __forceinline__ void rms_rows2_b2b(const bf16* x0, const bf16* x1, const float* g, bf16* o0, bf16* o1, int lane) {
;     ...
;     for (int j = 0; j < 4; ++j) { const f32x4 ga = gr[128 * j], gb = gr[128 * j + 1];
;         v4u a, b;
;         a.x = pk2(bflo(v[j].x) * rs * ga.x, bfhi(v[j].x) * rs * ga.y); a.y = pk2(bflo(v[j].y) * rs * ga.z, bfhi(v[j].y) * rs * ga.w); a.z = pk2(bflo(v[j].z) * rs * gb.x, bfhi(v[j].z) * rs * gb.y); a.w = pk2(bflo(v[j].w) * rs * gb.z, bfhi(v[j].w) * rs * gb.w);
;         b.x = pk2(bflo(w[j].x) * rt * ga.x, bfhi(w[j].x) * rt * ga.y); b.y = pk2(bflo(w[j].y) * rt * ga.z, bfhi(w[j].y) * rt * ga.w); b.z = pk2(bflo(w[j].z) * rt * gb.x, bfhi(w[j].z) * rt * gb.y); b.w = pk2(bflo(w[j].w) * rt * gb.z, bfhi(w[j].w) * rt * gb.w);
;         p0[64 * j] = a; p1[64 * j] = b; }
	v_pk_mul_f32 v[52:53], v[50:51], v[62:63]
	v_pk_mul_f32 v[62:63], v[68:69], v[54:55]
	v_pk_mul_f32 v[2:3], v[2:3], v[102:103]
	v_pk_mul_f32 v[6:7], v[6:7], v[56:57]
	v_bfe_u32 v24, v48, 16, 1
	v_bfe_u32 v26, v49, 16, 1
	v_bfe_u32 v28, v60, 16, 1
	v_bfe_u32 v30, v61, 16, 1
	v_pk_mul_f32 v[50:51], v[50:51], v[104:105]
	v_pk_mul_f32 v[54:55], v[54:55], v[58:59]
	v_bfe_u32 v0, v63, 16, 1
	v_bfe_u32 v4, v62, 16, 1
	v_bfe_u32 v20, v53, 16, 1
	v_bfe_u32 v22, v52, 16, 1
	v_bfe_u32 v44, v2, 16, 1
	v_bfe_u32 v46, v3, 16, 1
	v_bfe_u32 v56, v6, 16, 1
	v_bfe_u32 v57, v7, 16, 1
	v_add3_u32 v30, v61, v30, s5
	v_add3_u32 v28, v60, v28, s5
	v_add3_u32 v26, v49, v26, s5
	v_add3_u32 v24, v48, v24, s5
	v_bfe_u32 v36, v55, 16, 1
	v_bfe_u32 v38, v54, 16, 1
	v_bfe_u32 v40, v51, 16, 1
	v_bfe_u32 v42, v50, 16, 1
	v_add3_u32 v22, v52, v22, s5
	v_add3_u32 v20, v53, v20, s5
	v_add3_u32 v4, v62, v4, s5
	v_add3_u32 v0, v63, v0, s5
	v_add3_u32 v7, v7, v57, s5
	v_add3_u32 v6, v6, v56, s5
	v_add3_u32 v3, v3, v46, s5
	v_add3_u32 v2, v2, v44, s5
	v_lshrrev_b32_e32 v24, 16, v24
	v_lshrrev_b32_e32 v26, 16, v26
	v_lshrrev_b32_e32 v28, 16, v28
	v_lshrrev_b32_e32 v30, 16, v30
	v_add3_u32 v42, v50, v42, s5
	v_add3_u32 v40, v51, v40, s5
	v_add3_u32 v38, v54, v38, s5
	v_add3_u32 v36, v55, v36, s5
	v_lshrrev_b32_e32 v2, 16, v2
	v_lshrrev_b32_e32 v3, 16, v3
	v_lshrrev_b32_e32 v6, 16, v6
	v_lshrrev_b32_e32 v7, 16, v7
	v_and_or_b32 v51, v0, s1, v30
	v_and_or_b32 v50, v4, s1, v28
	v_and_or_b32 v49, v20, s1, v26
	v_and_or_b32 v48, v22, s1, v24
	v_and_or_b32 v55, v36, s1, v7
	v_and_or_b32 v54, v38, s1, v6
	v_and_or_b32 v53, v40, s1, v3
	v_and_or_b32 v52, v42, s1, v2
	global_store_dwordx4 v[16:17], v[48:51], off offset:-1024
	global_store_dwordx4 v[18:19], v[52:55], off offset:1024
	s_nop 1
	v_mov_b32_e32 v48, v216
	v_mov_b32_e32 v49, v217
	v_mov_b32_e32 v50, v218
	v_mov_b32_e32 v51, v219
	s_nop 0
	s_nop 1
	v_mov_b32_e32 v52, v220
	v_mov_b32_e32 v53, v221
	v_mov_b32_e32 v54, v222
	v_mov_b32_e32 v55, v223
	v_mov_b32_e32 v2, v48
	v_mov_b32_e32 v3, v50
	v_mov_b32_e32 v6, v52
	v_mov_b32_e32 v7, v54
	v_mov_b32_e32 v50, v49
	v_mov_b32_e32 v54, v53
	v_pk_mul_f32 v[48:49], v[96:97], v[2:3]
	v_pk_mul_f32 v[56:57], v[98:99], v[6:7]
	v_pk_mul_f32 v[52:53], v[92:93], v[50:51]
	v_pk_mul_f32 v[58:59], v[100:101], v[54:55]
	v_pk_mul_f32 v[2:3], v[106:107], v[2:3]
	v_pk_mul_f32 v[6:7], v[108:109], v[6:7]
	v_bfe_u32 v24, v48, 16, 1
	v_bfe_u32 v26, v49, 16, 1
	v_bfe_u32 v28, v56, 16, 1
	v_bfe_u32 v30, v57, 16, 1
	v_pk_mul_f32 v[50:51], v[64:65], v[50:51]
	v_pk_mul_f32 v[54:55], v[110:111], v[54:55]
	v_bfe_u32 v0, v59, 16, 1
	v_bfe_u32 v4, v58, 16, 1
	v_bfe_u32 v20, v53, 16, 1
	v_bfe_u32 v22, v52, 16, 1
	v_bfe_u32 v44, v2, 16, 1
	v_bfe_u32 v46, v3, 16, 1
	v_bfe_u32 v60, v6, 16, 1
	v_bfe_u32 v61, v7, 16, 1
	v_add3_u32 v30, v57, v30, s5
	v_add3_u32 v28, v56, v28, s5
	v_add3_u32 v26, v49, v26, s5
	v_add3_u32 v24, v48, v24, s5
	v_bfe_u32 v36, v55, 16, 1
	v_bfe_u32 v38, v54, 16, 1
	v_bfe_u32 v40, v51, 16, 1
	v_bfe_u32 v42, v50, 16, 1
	v_add3_u32 v22, v52, v22, s5
	v_add3_u32 v20, v53, v20, s5
	v_add3_u32 v4, v58, v4, s5
	v_add3_u32 v0, v59, v0, s5
	v_add3_u32 v7, v7, v61, s5
	v_add3_u32 v6, v6, v60, s5
	v_add3_u32 v3, v3, v46, s5
	v_add3_u32 v2, v2, v44, s5
	v_lshrrev_b32_e32 v24, 16, v24
	v_lshrrev_b32_e32 v26, 16, v26
	v_lshrrev_b32_e32 v28, 16, v28
	v_lshrrev_b32_e32 v30, 16, v30
	v_add3_u32 v42, v50, v42, s5
	v_add3_u32 v40, v51, v40, s5
	v_add3_u32 v38, v54, v38, s5
	v_add3_u32 v36, v55, v36, s5
	v_lshrrev_b32_e32 v2, 16, v2
	v_lshrrev_b32_e32 v3, 16, v3
	v_lshrrev_b32_e32 v6, 16, v6
	v_lshrrev_b32_e32 v7, 16, v7
	v_and_or_b32 v51, v0, s1, v30
	v_and_or_b32 v50, v4, s1, v28
	v_and_or_b32 v49, v20, s1, v26
	v_and_or_b32 v48, v22, s1, v24
	v_and_or_b32 v55, v36, s1, v7
	v_and_or_b32 v54, v38, s1, v6
	v_and_or_b32 v53, v40, s1, v3
	v_and_or_b32 v52, v42, s1, v2
	global_store_dwordx4 v[16:17], v[48:51], off
	global_store_dwordx4 v[18:19], v[52:55], off offset:2048
	s_nop 1
	v_mov_b32_e32 v48, v224
	v_mov_b32_e32 v49, v225
	v_mov_b32_e32 v50, v226
	v_mov_b32_e32 v51, v227
	s_nop 0
	s_nop 1
	v_mov_b32_e32 v52, v228
	v_mov_b32_e32 v53, v229
	v_mov_b32_e32 v54, v230
	v_mov_b32_e32 v55, v231
	v_mov_b32_e32 v30, v35
	v_mov_b32_e32 v28, v37
	v_mov_b32_e32 v26, v33
	v_mov_b32_e32 v22, v41
	v_mov_b32_e32 v24, v45
	v_mov_b32_e32 v0, v47
	v_mov_b32_e32 v4, v39
	v_pk_mul_f32 v[2:3], v[32:33], v[30:31] op_sel_hi:[0,1]
	v_pk_mul_f32 v[6:7], v[32:33], v[28:29] op_sel_hi:[0,1]
	v_pk_mul_f32 v[26:27], v[32:33], v[26:27] op_sel_hi:[0,1]
	v_mov_b32_e32 v20, v43
	v_pk_mul_f32 v[24:25], v[32:33], v[24:25] op_sel_hi:[0,1]
	v_pk_mul_f32 v[22:23], v[34:35], v[22:23] op_sel_hi:[0,1]
	v_pk_mul_f32 v[4:5], v[34:35], v[4:5] op_sel_hi:[0,1]
	v_pk_mul_f32 v[0:1], v[34:35], v[0:1] op_sel_hi:[0,1]
	v_pk_mul_f32 v[20:21], v[34:35], v[20:21] op_sel_hi:[0,1]
	v_mov_b32_e32 v28, v48
	v_mov_b32_e32 v29, v50
	v_mov_b32_e32 v30, v52
	v_mov_b32_e32 v31, v54
	v_mov_b32_e32 v50, v49
	v_mov_b32_e32 v54, v53
	v_pk_mul_f32 v[2:3], v[2:3], v[28:29]
	v_pk_mul_f32 v[26:27], v[26:27], v[30:31]
	v_pk_mul_f32 v[6:7], v[6:7], v[50:51]
	v_pk_mul_f32 v[24:25], v[24:25], v[54:55]
	v_pk_mul_f32 v[22:23], v[22:23], v[28:29]
	v_pk_mul_f32 v[4:5], v[4:5], v[30:31]
	v_pk_mul_f32 v[0:1], v[0:1], v[54:55]
	v_bfe_u32 v32, v2, 16, 1
	v_bfe_u32 v33, v3, 16, 1
	v_bfe_u32 v34, v26, 16, 1
	v_bfe_u32 v35, v27, 16, 1
	v_pk_mul_f32 v[20:21], v[20:21], v[50:51]
	v_bfe_u32 v28, v25, 16, 1
	v_bfe_u32 v29, v24, 16, 1
	v_bfe_u32 v30, v7, 16, 1
	v_bfe_u32 v31, v6, 16, 1
	v_bfe_u32 v36, v1, 16, 1
	v_bfe_u32 v37, v0, 16, 1
	v_bfe_u32 v40, v22, 16, 1
	v_bfe_u32 v41, v23, 16, 1
	v_bfe_u32 v42, v4, 16, 1
	v_bfe_u32 v43, v5, 16, 1
	v_add3_u32 v27, v27, v35, s5
	v_add3_u32 v26, v26, v34, s5
	v_add3_u32 v3, v3, v33, s5
	v_add3_u32 v2, v2, v32, s5
	v_bfe_u32 v38, v21, 16, 1
	v_bfe_u32 v39, v20, 16, 1
	v_add3_u32 v6, v6, v31, s5
	v_add3_u32 v7, v7, v30, s5
	v_add3_u32 v24, v24, v29, s5
	v_add3_u32 v25, v25, v28, s5
	v_add3_u32 v28, v0, v37, s5
	v_add3_u32 v29, v1, v36, s5
	v_add3_u32 v0, v5, v43, s5
	v_add3_u32 v1, v4, v42, s5
	v_add3_u32 v4, v23, v41, s5
	v_add3_u32 v5, v22, v40, s5
	v_lshrrev_b32_e32 v22, 16, v2
	v_lshrrev_b32_e32 v23, 16, v3
	v_lshrrev_b32_e32 v2, 16, v26
	v_lshrrev_b32_e32 v3, 16, v27
	v_add3_u32 v20, v20, v39, s5
	v_add3_u32 v21, v21, v38, s5
	v_lshrrev_b32_e32 v26, 16, v5
	v_lshrrev_b32_e32 v4, 16, v4
	v_lshrrev_b32_e32 v5, 16, v1
	v_lshrrev_b32_e32 v27, 16, v0
	v_and_or_b32 v3, v25, s1, v3
	v_and_or_b32 v2, v24, s1, v2
	v_and_or_b32 v1, v7, s1, v23
	v_and_or_b32 v0, v6, s1, v22
	v_and_or_b32 v7, v29, s1, v27
	v_and_or_b32 v6, v28, s1, v5
	v_and_or_b32 v5, v21, s1, v4
	v_and_or_b32 v4, v20, s1, v26
	global_store_dwordx4 v[16:17], v[0:3], off offset:1024
	global_store_dwordx4 v[18:19], v[4:7], off offset:3072
	s_cbranch_scc0 .LBB0_665

; __device__ __forceinline__ unsigned pk2(float lo, float hi) { return f2bf(lo) | (f2bf(hi) << 16); }
; __device__ __forceinline__ void rms_rows2_b2b(const bf16* x0, const bf16* x1, const float* g, bf16* o0, bf16* o1, int lane) {
;     const v4u* xr0 = (const v4u*)x0 + lane; const v4u* xr1 = (const v4u*)x1 + lane; const f32x4* gr = (const f32x4*)g + 2 * lane;
;     v4u v[4], w[4]; float s = 0.f, t = 0.f;
; #pragma unroll
;     for (int j = 0; j < 4; ++j) { v[j] = xr0[64 * j]; w[j] = xr1[64 * j]; }
; #pragma unroll
;     for (int j = 0; j < 4; ++j) {
;         s += (bflo(v[j].x) * bflo(v[j].x) + bfhi(v[j].x) * bfhi(v[j].x)) + (bflo(v[j].y) * bflo(v[j].y) + bfhi(v[j].y) * bfhi(v[j].y)) + (bflo(v[j].z) * bflo(v[j].z) + bfhi(v[j].z) * bfhi(v[j].z)) + (bflo(v[j].w) * bflo(v[j].w) + bfhi(v[j].w) * bfhi(v[j].w));
;         t += (bflo(w[j].x) * bflo(w[j].x) + bfhi(w[j].x) * bfhi(w[j].x)) + (bflo(w[j].y) * bflo(w[j].y) + bfhi(w[j].y) * bfhi(w[j].y)) + (bflo(w[j].z) * bflo(w[j].z) + bfhi(w[j].z) * bfhi(w[j].z)) + (bflo(w[j].w) * bflo(w[j].w) + bfhi(w[j].w) * bfhi(w[j].w)); }
;     const float rs = 1.f / sqrtf(wave_sum(s, lane) * (1.f / D) + NORM_EPS), rt = 1.f / sqrtf(wave_sum(t, lane) * (1.f / D) + NORM_EPS);
;     v4u* p0 = (v4u*)o0 + lane; v4u* p1 = (v4u*)o1 + lane;
; #pragma unroll
;     for (int j = 0; j < 4; ++j) { const f32x4 ga = gr[128 * j], gb = gr[128 * j + 1];
;         v4u a, b;
;         a.x = pk2(bflo(v[j].x) * rs * ga.x, bfhi(v[j].x) * rs * ga.y); a.y = pk2(bflo(v[j].y) * rs * ga.z, bfhi(v[j].y) * rs * ga.w); a.z = pk2(bflo(v[j].z) * rs * gb.x, bfhi(v[j].z) * rs * gb.y); a.w = pk2(bflo(v[j].w) * rs * gb.z, bfhi(v[j].w) * rs * gb.w);
;         b.x = pk2(bflo(w[j].x) * rt * ga.x, bfhi(w[j].x) * rt * ga.y); b.y = pk2(bflo(w[j].y) * rt * ga.z, bfhi(w[j].y) * rt * ga.w); b.z = pk2(bflo(w[j].z) * rt * gb.x, bfhi(w[j].z) * rt * gb.y); b.w = pk2(bflo(w[j].w) * rt * gb.z, bfhi(w[j].w) * rt * gb.w);
;         p0[64 * j] = a; p1[64 * j] = b; }
.LBB0_1112:
	s_or_b64 exec, exec, s[6:7]
	s_waitcnt lgkmcnt(0)
	v_mov_b32_e32 v0, v248
	s_barrier
	s_nop 0
	v_readfirstlane_b32 s0, v0
	s_ashr_i32 s1, s0, 6
	v_readlane_b32 s0, v255, 1
	s_add_i32 s0, s1, s0
	s_cmpk_gt_i32 s0, 0x1fff
	s_cbranch_scc1 .LBB0_1115
	v_and_b32_e32 v2, 63, v0
	v_lshlrev_b32_e32 v8, 5, v2
	v_mov_b32_e32 v9, 0
	v_lshl_add_u64 v[0:1], s[40:41], 0, v[8:9]
	s_mov_b64 s[4:5], 0x2000
	v_lshl_add_u64 v[10:11], v[0:1], 0, s[4:5]
	s_mov_b64 s[4:5], 0x3000
	v_lshl_add_u64 v[12:13], v[0:1], 0, s[4:5]
	s_mov_b64 s[4:5], 0x3800
	v_lshl_add_u64 v[14:15], v[0:1], 0, s[4:5]
	s_add_i32 s4, s0, 0x2000
	s_ashr_i32 s5, s4, 31
	s_lshl_b64 s[4:5], s[4:5], 12
	s_add_u32 s12, s54, s4
	s_addc_u32 s13, s55, s5
	s_ashr_i32 s35, s34, 31
	v_readlane_b32 s6, v255, 1
	s_lshl_b64 s[16:17], s[34:35], 12
	s_ashr_i32 s3, s1, 31
	s_ashr_i32 s7, s6, 31
	s_add_u32 s6, s1, s6
	s_addc_u32 s7, s3, s7
	s_lshl_b64 s[6:7], s[6:7], 12
	s_add_u32 s18, s52, s6
	s_addc_u32 s19, s53, s7
	s_add_u32 s20, s52, s4
	s_addc_u32 s21, s53, s5
	s_add_u32 s1, s54, s6
	s_addc_u32 s3, s55, s7
	v_lshlrev_b32_e32 v3, 2, v2
	s_add_u32 s22, s1, 0xc000800
	v_xor_b32_e32 v70, 4, v3
	v_xor_b32_e32 v71, 8, v3
	v_xor_b32_e32 v72, 16, v3
	v_xor_b32_e32 v73, 32, v3
	v_xor_b32_e32 v74, 64, v3
	v_xor_b32_e32 v75, 0x80, v3
	v_lshlrev_b32_e32 v8, 4, v2
	s_addc_u32 s23, s3, 0
	s_mov_b32 s1, 0xffff0000
	v_mov_b32_e32 v76, 0x358637bd
	s_mov_b32 s3, 0xf800000
	v_mov_b32_e32 v77, 0x260
	s_movk_i32 s4, 0x7fff
	s_brev_b32 s5, 48
	global_load_dwordx4 v[200:203], v[10:11], off offset:16
	global_load_dwordx4 v[204:207], v[10:11], off
	global_load_dwordx4 v[208:211], v[10:11], off offset:2048
	global_load_dwordx4 v[212:215], v[10:11], off offset:2064
	global_load_dwordx4 v[216:219], v[12:13], off
	global_load_dwordx4 v[220:223], v[12:13], off offset:16
	global_load_dwordx4 v[224:227], v[14:15], off
	global_load_dwordx4 v[228:231], v[14:15], off offset:16
	s_waitcnt vmcnt(0)
.LBB0_1114:
	v_lshl_add_u64 v[18:19], s[18:19], 0, v[8:9]
	s_nop 1
	v_mov_b32_e32 v0, v200
	v_mov_b32_e32 v1, v201
	v_mov_b32_e32 v2, v202
	v_mov_b32_e32 v3, v203
	s_nop 1
	v_mov_b32_e32 v4, v204
	v_mov_b32_e32 v5, v205
	v_mov_b32_e32 v6, v206
	v_mov_b32_e32 v7, v207
	v_lshl_add_u64 v[22:23], s[20:21], 0, v[8:9]
	global_load_dwordx4 v[24:27], v[18:19], off offset:1024
	global_load_dwordx4 v[28:31], v[22:23], off offset:1024
	global_load_dwordx4 v[36:39], v[18:19], off offset:2048
	global_load_dwordx4 v[42:45], v[22:23], off offset:2048
	global_load_dwordx4 v[78:81], v[18:19], off offset:3072
	global_load_dwordx4 v[82:85], v[22:23], off offset:3072
	global_load_dwordx4 v[32:35], v[18:19], off
	global_load_dwordx4 v[86:89], v[22:23], off
	v_lshl_add_u64 v[20:21], s[12:13], 0, v[8:9]
	v_add_co_u32_e32 v18, vcc, s5, v20
	v_lshl_add_u64 v[16:17], s[22:23], 0, v[8:9]
	s_nop 0
	v_addc_co_u32_e32 v19, vcc, 0, v21, vcc
	s_add_i32 s0, s0, s34
	s_add_u32 s12, s12, s16
	s_addc_u32 s13, s13, s17
	s_add_u32 s18, s18, s16
	s_addc_u32 s19, s19, s17
	s_add_u32 s20, s20, s16
	s_addc_u32 s21, s21, s17
	s_add_u32 s22, s22, s16
	s_addc_u32 s23, s23, s17
	s_cmpk_gt_i32 s0, 0x1fff
	s_waitcnt vmcnt(7)
	v_and_b32_e32 v63, 0xffff0000, v25
	v_and_b32_e32 v62, 0xffff0000, v24
	s_waitcnt vmcnt(5)
	v_and_b32_e32 v91, 0xffff0000, v36
	v_lshlrev_b32_e32 v92, 16, v37
	v_and_b32_e32 v93, 0xffff0000, v37
	s_waitcnt vmcnt(4)
	v_and_b32_e32 v95, 0xffff0000, v42
	s_waitcnt vmcnt(1)
	v_and_b32_e32 v98, 0xffff0000, v32
	v_and_b32_e32 v102, 0xffff0000, v34
	v_and_b32_e32 v65, 0xffff0000, v43
	v_lshlrev_b32_e32 v97, 16, v33
	v_lshlrev_b32_e32 v96, 16, v32
	v_and_b32_e32 v99, 0xffff0000, v33
	v_lshlrev_b32_e32 v101, 16, v35
	v_lshlrev_b32_e32 v100, 16, v34
	v_and_b32_e32 v103, 0xffff0000, v35
	v_lshlrev_b32_e32 v35, 16, v78
	v_and_b32_e32 v37, 0xffff0000, v78
	v_pk_mov_b32 v[46:47], v[38:39], v[80:81] op_sel:[1,0]
	v_lshlrev_b32_e32 v33, 16, v80
	s_waitcnt vmcnt(0)
	v_lshlrev_b32_e32 v78, 16, v86
	v_and_b32_e32 v80, 0xffff0000, v86
	v_lshlrev_b32_e32 v86, 16, v88
	v_and_b32_e32 v88, 0xffff0000, v88
	v_mov_b32_e32 v114, v102
	v_mov_b32_e32 v115, v98
	v_mov_b32_e32 v48, v4
	v_mov_b32_e32 v49, v6
	v_mov_b32_e32 v6, v5
	v_mov_b32_e32 v50, v0
	v_mov_b32_e32 v51, v2
	v_mov_b32_e32 v2, v1
	v_lshlrev_b32_e32 v61, 16, v25
	v_lshlrev_b32_e32 v60, 16, v24
	v_lshlrev_b32_e32 v67, 16, v27
	v_lshlrev_b32_e32 v66, 16, v26
	v_and_b32_e32 v69, 0xffff0000, v27
	v_and_b32_e32 v68, 0xffff0000, v26
	v_lshlrev_b32_e32 v53, 16, v29
	v_lshlrev_b32_e32 v52, 16, v28
	v_and_b32_e32 v55, 0xffff0000, v29
	v_and_b32_e32 v54, 0xffff0000, v28
	v_lshlrev_b32_e32 v57, 16, v31
	v_and_b32_e32 v59, 0xffff0000, v31
	v_lshlrev_b32_e32 v90, 16, v36
	v_lshlrev_b32_e32 v94, 16, v42
	v_lshlrev_b32_e32 v64, 16, v43
	v_lshlrev_b32_e32 v31, 16, v79
	v_and_b32_e32 v29, 0xffff0000, v79
	v_lshlrev_b32_e32 v27, 16, v81
	v_and_b32_e32 v25, 0xffff0000, v81
	v_lshlrev_b32_e32 v23, 16, v83
	v_and_b32_e32 v21, 0xffff0000, v83
	v_lshlrev_b32_e32 v5, 16, v85
	v_and_b32_e32 v1, 0xffff0000, v85
	v_lshlrev_b32_e32 v32, 16, v39
	v_lshlrev_b32_e32 v79, 16, v87
	v_and_b32_e32 v81, 0xffff0000, v87
	v_lshlrev_b32_e32 v41, 16, v82
	v_and_b32_e32 v43, 0xffff0000, v82
	v_pk_mov_b32 v[82:83], v[44:45], v[84:85] op_sel:[1,0]
	v_lshlrev_b32_e32 v39, 16, v84
	v_pk_mul_f32 v[84:85], v[62:63], v[62:63]
	v_mov_b32_e32 v110, v97
	v_mov_b32_e32 v111, v99
	v_mul_f32_e32 v0, v99, v99
	v_mov_b32_e32 v112, v100
	v_mov_b32_e32 v113, v96
	v_mul_f32_e32 v4, v91, v91
	v_mul_f32_e32 v20, v93, v93
	v_mov_b32_e32 v126, v88
	v_mov_b32_e32 v127, v80
	v_mul_f32_e32 v26, v95, v95
	v_mul_f32_e32 v28, v65, v65
	v_pk_mul_f32 v[114:115], v[114:115], v[114:115]
; __device__ __forceinline__ void rms_rows2_b2b(const bf16* x0, const bf16* x1, const float* g, bf16* o0, bf16* o1, int lane) {
;     ...
;     for (int j = 0; j < 4; ++j) { v[j] = xr0[64 * j]; w[j] = xr1[64 * j]; }
; #pragma unroll
;     for (int j = 0; j < 4; ++j) {
;         s += (bflo(v[j].x) * bflo(v[j].x) + bfhi(v[j].x) * bfhi(v[j].x)) + (bflo(v[j].y) * bflo(v[j].y) + bfhi(v[j].y) * bfhi(v[j].y)) + (bflo(v[j].z) * bflo(v[j].z) + bfhi(v[j].z) * bfhi(v[j].z)) + (bflo(v[j].w) * bflo(v[j].w) + bfhi(v[j].w) * bfhi(v[j].w));
;         t += (bflo(w[j].x) * bflo(w[j].x) + bfhi(w[j].x) * bfhi(w[j].x)) + (bflo(w[j].y) * bflo(w[j].y) + bfhi(w[j].y) * bfhi(w[j].y)) + (bflo(w[j].z) * bflo(w[j].z) + bfhi(w[j].z) * bfhi(w[j].z)) + (bflo(w[j].w) * bflo(w[j].w) + bfhi(w[j].w) * bfhi(w[j].w)); }
;     const float rs = 1.f / sqrtf(wave_sum(s, lane) * (1.f / D) + NORM_EPS), rt = 1.f / sqrtf(wave_sum(t, lane) * (1.f / D) + NORM_EPS);
	v_and_b32_e32 v36, 0xffff0000, v38
	v_pk_mul_f32 v[104:105], v[68:69], v[68:69]
	v_mul_f32_e32 v120, v31, v31
	v_mul_f32_e32 v156, v29, v29
	v_mov_b32_e32 v122, v79
	v_mov_b32_e32 v123, v81
	v_mul_f32_e32 v24, v81, v81
	v_mov_b32_e32 v124, v86
	v_mov_b32_e32 v125, v78
	v_mov_b32_e32 v138, v94
	v_mov_b32_e32 v139, v64
	v_pk_fma_f32 v[84:85], v[60:61], v[60:61], v[84:85]
	v_pk_fma_f32 v[110:111], v[110:111], v[110:111], v[0:1] op_sel_hi:[1,1,0]
	v_pk_fma_f32 v[144:145], v[90:91], v[90:91], v[4:5] op_sel_hi:[1,1,0]
	v_pk_fma_f32 v[146:147], v[92:93], v[92:93], v[20:21] op_sel_hi:[1,1,0]
	v_pk_mul_f32 v[126:127], v[126:127], v[126:127]
	v_pk_fma_f32 v[150:151], v[94:95], v[94:95], v[26:27] op_sel_hi:[1,1,0]
	v_pk_fma_f32 v[152:153], v[64:65], v[64:65], v[28:29] op_sel_hi:[1,1,0]
	v_mov_b32_e32 v64, v95
	v_pk_fma_f32 v[94:95], v[112:113], v[112:113], v[114:115]
	v_and_b32_e32 v58, 0xffff0000, v30
	v_lshlrev_b32_e32 v34, 16, v38
	v_lshlrev_b32_e32 v87, 16, v89
	v_and_b32_e32 v89, 0xffff0000, v89
	v_lshlrev_b32_e32 v40, 16, v44
	v_and_b32_e32 v42, 0xffff0000, v44
	v_lshlrev_b32_e32 v38, 16, v45
	v_pk_mul_f32 v[106:107], v[54:55], v[54:55]
	v_mov_b32_e32 v116, v101
	v_mov_b32_e32 v117, v103
	v_pk_mul_f32 v[118:119], v[36:37], v[36:37]
	v_and_b32_e32 v45, 0xffff0000, v47
	v_and_b32_e32 v44, 0xffff0000, v46
	v_mul_f32_e32 v22, v103, v103
	v_pk_fma_f32 v[104:105], v[66:67], v[66:67], v[104:105]
	v_pk_fma_f32 v[122:123], v[122:123], v[122:123], v[24:25] op_sel_hi:[1,1,0]
	v_pk_add_f32 v[84:85], v[84:85], v[84:85] op_sel:[0,1] op_sel_hi:[1,0]
	v_mov_b32_e32 v145, v120
	v_mov_b32_e32 v147, v156
	v_pk_fma_f32 v[112:113], v[124:125], v[124:125], v[126:127]
	v_pk_add_f32 v[110:111], v[94:95], v[110:111] op_sel:[1,0] op_sel_hi:[0,1]
	v_lshlrev_b32_e32 v56, 16, v30
	v_pk_mul_f32 v[108:109], v[58:59], v[58:59]
	v_mov_b32_e32 v128, v87
	v_mov_b32_e32 v129, v89
	v_mul_f32_e32 v30, v89, v89
	v_pk_fma_f32 v[106:107], v[52:53], v[52:53], v[106:107]
	v_pk_fma_f32 v[118:119], v[34:35], v[34:35], v[118:119]
	v_pk_mul_f32 v[148:149], v[44:45], v[44:45]
	v_pk_fma_f32 v[116:117], v[116:117], v[116:117], v[22:23] op_sel_hi:[1,1,0]
	v_pk_add_f32 v[84:85], v[104:105], v[84:85]
	v_pk_add_f32 v[124:125], v[144:145], v[146:147]
	v_pk_add_f32 v[122:123], v[112:113], v[122:123] op_sel:[1,0] op_sel_hi:[0,1]
	v_pk_add_f32 v[94:95], v[94:95], v[110:111]
	v_mul_f32_e32 v158, v23, v23
	v_mul_f32_e32 v159, v21, v21
	v_mov_b32_e32 v121, v27
	v_mov_b32_e32 v132, v90
	v_mov_b32_e32 v133, v92
	v_pk_fma_f32 v[108:109], v[56:57], v[56:57], v[108:109]
	v_pk_fma_f32 v[128:129], v[128:129], v[128:129], v[30:31] op_sel_hi:[1,1,0]
	v_mov_b32_e32 v92, v91
	v_pk_add_f32 v[90:91], v[106:107], v[106:107] op_sel:[0,1] op_sel_hi:[1,0]
	v_pk_fma_f32 v[106:107], v[32:33], v[32:33], v[148:149]
	v_mov_b32_e32 v26, v116
	v_pk_add_f32 v[110:111], v[118:119], v[124:125]
	v_pk_add_f32 v[84:85], v[104:105], v[84:85] op_sel:[1,0] op_sel_hi:[0,1]
	v_pk_add_f32 v[104:105], v[112:113], v[122:123]
	v_mov_b32_e32 v120, v94
	v_mul_f32_e32 v157, v25, v25
	v_pk_mul_f32 v[130:131], v[42:43], v[42:43]
	v_and_b32_e32 v47, 0xffff0000, v83
	v_and_b32_e32 v46, 0xffff0000, v82
	v_mov_b32_e32 v83, v5
	v_mov_b32_e32 v151, v158
	v_mov_b32_e32 v153, v159
	v_mov_b32_e32 v4, v128
	v_pk_add_f32 v[90:91], v[108:109], v[90:91]
	v_pk_add_f32 v[106:107], v[106:107], v[110:111]
	v_pk_add_f32 v[94:95], v[116:117], v[94:95]
	v_mov_b32_e32 v82, v104
	v_pk_mul_f32 v[110:111], v[26:27], v[120:121]
	v_mul_f32_e32 v160, v1, v1
	v_pk_fma_f32 v[130:131], v[40:41], v[40:41], v[130:131]
	v_pk_mul_f32 v[154:155], v[46:47], v[46:47]
	v_pk_add_f32 v[126:127], v[150:151], v[152:153]
	v_pk_add_f32 v[90:91], v[108:109], v[90:91] op_sel:[1,0] op_sel_hi:[0,1]
	v_mov_b32_e32 v85, v157
	v_pk_add_f32 v[104:105], v[128:129], v[104:105]
	v_pk_mul_f32 v[82:83], v[4:5], v[82:83]
	v_mov_b32_e32 v95, v111
	v_pk_fma_f32 v[114:115], v[38:39], v[38:39], v[154:155]
	v_pk_add_f32 v[112:113], v[130:131], v[126:127]
	v_mov_b32_e32 v91, v160
	v_mov_b32_e32 v105, v83
	v_pk_add_f32 v[82:83], v[94:95], v[84:85]
	v_pk_add_f32 v[108:109], v[114:115], v[112:113]
	v_pk_add_f32 v[84:85], v[104:105], v[90:91]
	v_pk_add_f32 v[82:83], v[82:83], v[106:107]
	v_pk_add_f32 v[84:85], v[84:85], v[108:109]
	v_add_f32_e32 v0, v82, v83
	v_add_f32_e32 v4, v84, v85
	ds_bpermute_b32 v20, v70, v0
	ds_bpermute_b32 v22, v70, v4
	v_mov_b32_e32 v135, v32
	v_mov_b32_e32 v134, v34
	v_mov_b32_e32 v136, v36
	s_waitcnt lgkmcnt(1)
	v_add_f32_e32 v0, v0, v20
	s_waitcnt lgkmcnt(0)
	v_add_f32_e32 v4, v4, v22
	ds_bpermute_b32 v20, v71, v0
	ds_bpermute_b32 v22, v71, v4
	v_mov_b32_e32 v141, v38
	v_mov_b32_e32 v140, v40
	v_mov_b32_e32 v142, v42
	s_waitcnt lgkmcnt(1)
	v_add_f32_e32 v0, v0, v20
	s_waitcnt lgkmcnt(0)
	v_add_f32_e32 v4, v4, v22
	ds_bpermute_b32 v20, v72, v0
	ds_bpermute_b32 v22, v72, v4
	v_mov_b32_e32 v137, v44
	v_mov_b32_e32 v143, v46
	s_waitcnt lgkmcnt(1)
	v_add_f32_e32 v0, v0, v20
	s_waitcnt lgkmcnt(0)
	v_add_f32_e32 v4, v4, v22
	ds_bpermute_b32 v20, v73, v0
	ds_bpermute_b32 v22, v73, v4
	s_waitcnt lgkmcnt(1)
	v_add_f32_e32 v0, v0, v20
	s_waitcnt lgkmcnt(0)
	v_add_f32_e32 v4, v4, v22
	ds_bpermute_b32 v20, v74, v0
	ds_bpermute_b32 v22, v74, v4
	s_waitcnt lgkmcnt(1)
	v_add_f32_e32 v0, v0, v20
	s_waitcnt lgkmcnt(0)
	v_add_f32_e32 v4, v4, v22
	ds_bpermute_b32 v20, v75, v0
	ds_bpermute_b32 v22, v75, v4
	s_waitcnt lgkmcnt(1)
	v_add_f32_e32 v0, v0, v20
	s_waitcnt lgkmcnt(0)
; __device__ __forceinline__ unsigned pk2(float lo, float hi) { return f2bf(lo) | (f2bf(hi) << 16); }
; __device__ __forceinline__ void rms_rows2_b2b(const bf16* x0, const bf16* x1, const float* g, bf16* o0, bf16* o1, int lane) {
;     ...
;     const float rs = 1.f / sqrtf(wave_sum(s, lane) * (1.f / D) + NORM_EPS), rt = 1.f / sqrtf(wave_sum(t, lane) * (1.f / D) + NORM_EPS);
;     v4u* p0 = (v4u*)o0 + lane; v4u* p1 = (v4u*)o1 + lane;
; #pragma unroll
;     for (int j = 0; j < 4; ++j) { const f32x4 ga = gr[128 * j], gb = gr[128 * j + 1];
;         v4u a, b;
;         a.x = pk2(bflo(v[j].x) * rs * ga.x, bfhi(v[j].x) * rs * ga.y); a.y = pk2(bflo(v[j].y) * rs * ga.z, bfhi(v[j].y) * rs * ga.w); a.z = pk2(bflo(v[j].z) * rs * gb.x, bfhi(v[j].z) * rs * gb.y); a.w = pk2(bflo(v[j].w) * rs * gb.z, bfhi(v[j].w) * rs * gb.w);
;         b.x = pk2(bflo(w[j].x) * rt * ga.x, bfhi(w[j].x) * rt * ga.y); b.y = pk2(bflo(w[j].y) * rt * ga.z, bfhi(w[j].y) * rt * ga.w); b.z = pk2(bflo(w[j].z) * rt * gb.x, bfhi(w[j].z) * rt * gb.y); b.w = pk2(bflo(w[j].w) * rt * gb.z, bfhi(w[j].w) * rt * gb.w);
;         p0[64 * j] = a; p1[64 * j] = b; }
	v_add_f32_e32 v4, v4, v22
	v_fmamk_f32 v0, v0, 0x3a000000, v76
	v_fmamk_f32 v4, v4, 0x3a000000, v76
	v_mul_f32_e32 v20, 0x4f800000, v0
	v_cmp_gt_f32_e64 s[6:7], s3, v0
	v_mul_f32_e32 v22, 0x4f800000, v4
	v_cmp_gt_f32_e32 vcc, s3, v4
	v_cndmask_b32_e64 v0, v0, v20, s[6:7]
	v_sqrt_f32_e32 v20, v0
	v_cndmask_b32_e32 v4, v4, v22, vcc
	v_sqrt_f32_e32 v22, v4
	v_add_u32_e32 v24, -1, v20
	v_add_u32_e32 v26, 1, v20
	v_add_u32_e32 v28, -1, v22
	v_fma_f32 v32, -v24, v20, v0
	v_add_u32_e32 v30, 1, v22
	v_fma_f32 v34, -v26, v20, v0
	v_fma_f32 v36, -v28, v22, v4
	v_cmp_ge_f32_e64 s[8:9], 0, v32
	v_fma_f32 v38, -v30, v22, v4
	v_cmp_lt_f32_e64 s[10:11], 0, v34
	v_cndmask_b32_e64 v20, v20, v24, s[8:9]
	v_cmp_ge_f32_e64 s[8:9], 0, v36
	v_cndmask_b32_e64 v20, v20, v26, s[10:11]
	v_mul_f32_e32 v24, 0x37800000, v20
	v_cndmask_b32_e64 v22, v22, v28, s[8:9]
	v_cmp_lt_f32_e64 s[8:9], 0, v38
	v_cndmask_b32_e64 v20, v20, v24, s[6:7]
	v_cmp_class_f32_e64 s[6:7], v0, v77
	v_cndmask_b32_e64 v22, v22, v30, s[8:9]
	v_mul_f32_e32 v26, 0x37800000, v22
	v_cndmask_b32_e32 v22, v22, v26, vcc
	v_cmp_class_f32_e32 vcc, v4, v77
	v_cndmask_b32_e64 v0, v20, v0, s[6:7]
	v_div_scale_f32 v20, s[6:7], v0, v0, 1.0
	v_cndmask_b32_e32 v4, v22, v4, vcc
	v_div_scale_f32 v24, s[6:7], v4, v4, 1.0
	v_rcp_f32_e32 v28, v20
	v_rcp_f32_e32 v30, v24
	v_div_scale_f32 v22, vcc, 1.0, v0, 1.0
	v_fma_f32 v32, -v20, v28, 1.0
	v_fma_f32 v34, -v24, v30, 1.0
	v_fmac_f32_e32 v28, v32, v28
	v_div_scale_f32 v26, s[6:7], 1.0, v4, 1.0
	v_fmac_f32_e32 v30, v34, v30
	v_mul_f32_e32 v32, v22, v28
	v_mul_f32_e32 v34, v26, v30
	v_fma_f32 v36, -v20, v32, v22
	v_fma_f32 v38, -v24, v34, v26
	v_fmac_f32_e32 v32, v36, v28
	v_fmac_f32_e32 v34, v38, v30
	v_fma_f32 v20, -v20, v32, v22
	v_fma_f32 v22, -v24, v34, v26
	v_div_fmas_f32 v20, v20, v28, v32
	s_mov_b64 vcc, s[6:7]
	v_div_fixup_f32 v32, v20, v0, 1.0
	v_div_fmas_f32 v0, v22, v30, v34
	v_pk_mul_f32 v[82:83], v[32:33], v[96:97] op_sel_hi:[0,1]
	v_pk_mul_f32 v[90:91], v[32:33], v[100:101] op_sel_hi:[0,1]
	v_div_fixup_f32 v34, v0, v4, 1.0
	v_pk_mul_f32 v[84:85], v[32:33], v[98:99] op_sel_hi:[0,1]
	v_pk_mul_f32 v[94:95], v[32:33], v[102:103] op_sel_hi:[0,1]
	v_pk_mul_f32 v[82:83], v[48:49], v[82:83]
	v_pk_mul_f32 v[90:91], v[50:51], v[90:91]
	v_pk_mul_f32 v[78:79], v[34:35], v[78:79] op_sel_hi:[0,1]
	v_pk_mul_f32 v[80:81], v[34:35], v[80:81] op_sel_hi:[0,1]
	v_pk_mul_f32 v[86:87], v[34:35], v[86:87] op_sel_hi:[0,1]
	v_pk_mul_f32 v[88:89], v[34:35], v[88:89] op_sel_hi:[0,1]
	v_pk_mul_f32 v[84:85], v[6:7], v[84:85]
	v_pk_mul_f32 v[94:95], v[2:3], v[94:95]
	v_bfe_u32 v24, v82, 16, 1
	v_bfe_u32 v26, v83, 16, 1
	v_bfe_u32 v28, v90, 16, 1
	v_bfe_u32 v30, v91, 16, 1
	v_pk_mul_f32 v[48:49], v[48:49], v[78:79]
	v_pk_mul_f32 v[6:7], v[6:7], v[80:81]
	v_pk_mul_f32 v[50:51], v[50:51], v[86:87]
	v_pk_mul_f32 v[2:3], v[2:3], v[88:89]
	v_pk_mul_f32 v[102:103], v[34:35], v[52:53] op_sel_hi:[0,1]
	v_bfe_u32 v0, v95, 16, 1
	v_bfe_u32 v4, v94, 16, 1
	v_bfe_u32 v20, v85, 16, 1
	v_bfe_u32 v22, v84, 16, 1
	v_add3_u32 v30, v91, v30, s4
	v_add3_u32 v28, v90, v28, s4
	v_add3_u32 v26, v83, v26, s4
	v_add3_u32 v24, v82, v24, s4
	v_bfe_u32 v36, v3, 16, 1
	v_bfe_u32 v38, v2, 16, 1
	v_bfe_u32 v40, v7, 16, 1
	v_bfe_u32 v42, v6, 16, 1
	v_bfe_u32 v44, v48, 16, 1
	v_bfe_u32 v46, v49, 16, 1
	v_bfe_u32 v52, v50, 16, 1
	v_bfe_u32 v53, v51, 16, 1
	v_add3_u32 v22, v84, v22, s4
	v_add3_u32 v20, v85, v20, s4
	v_add3_u32 v4, v94, v4, s4
	v_add3_u32 v0, v95, v0, s4
	v_lshrrev_b32_e32 v24, 16, v24
	v_lshrrev_b32_e32 v26, 16, v26
	v_lshrrev_b32_e32 v28, 16, v28
	v_lshrrev_b32_e32 v30, 16, v30
	v_add3_u32 v6, v6, v42, s4
	v_add3_u32 v7, v7, v40, s4
	v_add3_u32 v2, v2, v38, s4
	v_add3_u32 v3, v3, v36, s4
	v_add3_u32 v36, v51, v53, s4
	v_add3_u32 v38, v50, v52, s4
	v_add3_u32 v40, v49, v46, s4
	v_add3_u32 v42, v48, v44, s4
	v_and_or_b32 v51, v0, s1, v30
	v_and_or_b32 v50, v4, s1, v28
	v_and_or_b32 v49, v20, s1, v26
	v_and_or_b32 v48, v22, s1, v24
	v_lshrrev_b32_e32 v0, 16, v42
	v_lshrrev_b32_e32 v4, 16, v40
	v_lshrrev_b32_e32 v20, 16, v38
	v_lshrrev_b32_e32 v22, 16, v36
	v_pk_mul_f32 v[104:105], v[34:35], v[54:55] op_sel_hi:[0,1]
	v_and_or_b32 v55, v3, s1, v22
	v_and_or_b32 v54, v2, s1, v20
	v_and_or_b32 v53, v7, s1, v4
	v_and_or_b32 v52, v6, s1, v0
	global_store_dwordx4 v[16:17], v[48:51], off offset:-2048
	global_store_dwordx4 v[18:19], v[52:55], off
	s_nop 1
	v_mov_b32_e32 v48, v208
	v_mov_b32_e32 v49, v209
	v_mov_b32_e32 v50, v210
	v_mov_b32_e32 v51, v211
	s_nop 0
	s_nop 1
	v_mov_b32_e32 v52, v212
	v_mov_b32_e32 v53, v213
	v_mov_b32_e32 v54, v214
	v_mov_b32_e32 v55, v215
	v_pk_mul_f32 v[60:61], v[32:33], v[60:61] op_sel_hi:[0,1]
	v_pk_mul_f32 v[66:67], v[32:33], v[66:67] op_sel_hi:[0,1]
	v_pk_mul_f32 v[62:63], v[32:33], v[62:63] op_sel_hi:[0,1]
	v_pk_mul_f32 v[68:69], v[32:33], v[68:69] op_sel_hi:[0,1]
	v_pk_mul_f32 v[56:57], v[34:35], v[56:57] op_sel_hi:[0,1]
	v_pk_mul_f32 v[58:59], v[34:35], v[58:59] op_sel_hi:[0,1]
	v_pk_mul_f32 v[96:97], v[32:33], v[132:133] op_sel_hi:[0,1]
	v_pk_mul_f32 v[98:99], v[32:33], v[134:135] op_sel_hi:[0,1]
	v_pk_mul_f32 v[92:93], v[32:33], v[92:93] op_sel_hi:[0,1]
	v_pk_mul_f32 v[100:101], v[32:33], v[136:137] op_sel_hi:[0,1]
	v_pk_mul_f32 v[106:107], v[34:35], v[138:139] op_sel_hi:[0,1]
	v_pk_mul_f32 v[108:109], v[34:35], v[140:141] op_sel_hi:[0,1]
	v_pk_mul_f32 v[64:65], v[34:35], v[64:65] op_sel_hi:[0,1]
	v_pk_mul_f32 v[110:111], v[34:35], v[142:143] op_sel_hi:[0,1]
	v_mov_b32_e32 v2, v48
	v_mov_b32_e32 v3, v50
	v_mov_b32_e32 v6, v52
	v_mov_b32_e32 v7, v54
	v_mov_b32_e32 v50, v49
	v_mov_b32_e32 v54, v53
	v_pk_mul_f32 v[48:49], v[2:3], v[60:61]
	v_pk_mul_f32 v[60:61], v[66:67], v[6:7]
; __device__ __forceinline__ unsigned pk2(float lo, float hi) { return f2bf(lo) | (f2bf(hi) << 16); }
; __device__ __forceinline__ void rms_rows2_b2b(const bf16* x0, const bf16* x1, const float* g, bf16* o0, bf16* o1, int lane) {
;     ...
;     for (int j = 0; j < 4; ++j) { const f32x4 ga = gr[128 * j], gb = gr[128 * j + 1];
;         v4u a, b;
;         a.x = pk2(bflo(v[j].x) * rs * ga.x, bfhi(v[j].x) * rs * ga.y); a.y = pk2(bflo(v[j].y) * rs * ga.z, bfhi(v[j].y) * rs * ga.w); a.z = pk2(bflo(v[j].z) * rs * gb.x, bfhi(v[j].z) * rs * gb.y); a.w = pk2(bflo(v[j].w) * rs * gb.z, bfhi(v[j].w) * rs * gb.w);
;         b.x = pk2(bflo(w[j].x) * rt * ga.x, bfhi(w[j].x) * rt * ga.y); b.y = pk2(bflo(w[j].y) * rt * ga.z, bfhi(w[j].y) * rt * ga.w); b.z = pk2(bflo(w[j].z) * rt * gb.x, bfhi(w[j].z) * rt * gb.y); b.w = pk2(bflo(w[j].w) * rt * gb.z, bfhi(w[j].w) * rt * gb.w);
;         p0[64 * j] = a; p1[64 * j] = b; }
	v_pk_mul_f32 v[52:53], v[50:51], v[62:63]
	v_pk_mul_f32 v[62:63], v[68:69], v[54:55]
	v_pk_mul_f32 v[2:3], v[2:3], v[102:103]
	v_pk_mul_f32 v[6:7], v[6:7], v[56:57]
	v_bfe_u32 v24, v48, 16, 1
	v_bfe_u32 v26, v49, 16, 1
	v_bfe_u32 v28, v60, 16, 1
	v_bfe_u32 v30, v61, 16, 1
	v_pk_mul_f32 v[50:51], v[50:51], v[104:105]
	v_pk_mul_f32 v[54:55], v[54:55], v[58:59]
	v_bfe_u32 v0, v63, 16, 1
	v_bfe_u32 v4, v62, 16, 1
	v_bfe_u32 v20, v53, 16, 1
	v_bfe_u32 v22, v52, 16, 1
	v_bfe_u32 v44, v2, 16, 1
	v_bfe_u32 v46, v3, 16, 1
	v_bfe_u32 v56, v6, 16, 1
	v_bfe_u32 v57, v7, 16, 1
	v_add3_u32 v30, v61, v30, s4
	v_add3_u32 v28, v60, v28, s4
	v_add3_u32 v26, v49, v26, s4
	v_add3_u32 v24, v48, v24, s4
	v_bfe_u32 v36, v55, 16, 1
	v_bfe_u32 v38, v54, 16, 1
	v_bfe_u32 v40, v51, 16, 1
	v_bfe_u32 v42, v50, 16, 1
	v_add3_u32 v22, v52, v22, s4
	v_add3_u32 v20, v53, v20, s4
	v_add3_u32 v4, v62, v4, s4
	v_add3_u32 v0, v63, v0, s4
	v_add3_u32 v7, v7, v57, s4
	v_add3_u32 v6, v6, v56, s4
	v_add3_u32 v3, v3, v46, s4
	v_add3_u32 v2, v2, v44, s4
	v_lshrrev_b32_e32 v24, 16, v24
	v_lshrrev_b32_e32 v26, 16, v26
	v_lshrrev_b32_e32 v28, 16, v28
	v_lshrrev_b32_e32 v30, 16, v30
	v_add3_u32 v42, v50, v42, s4
	v_add3_u32 v40, v51, v40, s4
	v_add3_u32 v38, v54, v38, s4
	v_add3_u32 v36, v55, v36, s4
	v_lshrrev_b32_e32 v2, 16, v2
	v_lshrrev_b32_e32 v3, 16, v3
	v_lshrrev_b32_e32 v6, 16, v6
	v_lshrrev_b32_e32 v7, 16, v7
	v_and_or_b32 v51, v0, s1, v30
	v_and_or_b32 v50, v4, s1, v28
	v_and_or_b32 v49, v20, s1, v26
	v_and_or_b32 v48, v22, s1, v24
	v_and_or_b32 v55, v36, s1, v7
	v_and_or_b32 v54, v38, s1, v6
	v_and_or_b32 v53, v40, s1, v3
	v_and_or_b32 v52, v42, s1, v2
	global_store_dwordx4 v[16:17], v[48:51], off offset:-1024
	global_store_dwordx4 v[18:19], v[52:55], off offset:1024
	s_nop 1
	v_mov_b32_e32 v48, v216
	v_mov_b32_e32 v49, v217
	v_mov_b32_e32 v50, v218
	v_mov_b32_e32 v51, v219
	s_nop 0
	s_nop 1
	v_mov_b32_e32 v52, v220
	v_mov_b32_e32 v53, v221
	v_mov_b32_e32 v54, v222
	v_mov_b32_e32 v55, v223
	v_mov_b32_e32 v2, v48
	v_mov_b32_e32 v3, v50
	v_mov_b32_e32 v6, v52
	v_mov_b32_e32 v7, v54
	v_mov_b32_e32 v50, v49
	v_mov_b32_e32 v54, v53
	v_pk_mul_f32 v[48:49], v[96:97], v[2:3]
	v_pk_mul_f32 v[56:57], v[98:99], v[6:7]
	v_pk_mul_f32 v[52:53], v[92:93], v[50:51]
	v_pk_mul_f32 v[58:59], v[100:101], v[54:55]
	v_pk_mul_f32 v[2:3], v[106:107], v[2:3]
	v_pk_mul_f32 v[6:7], v[108:109], v[6:7]
	v_bfe_u32 v24, v48, 16, 1
	v_bfe_u32 v26, v49, 16, 1
	v_bfe_u32 v28, v56, 16, 1
	v_bfe_u32 v30, v57, 16, 1
	v_pk_mul_f32 v[50:51], v[64:65], v[50:51]
	v_pk_mul_f32 v[54:55], v[110:111], v[54:55]
	v_bfe_u32 v0, v59, 16, 1
	v_bfe_u32 v4, v58, 16, 1
	v_bfe_u32 v20, v53, 16, 1
	v_bfe_u32 v22, v52, 16, 1
	v_bfe_u32 v44, v2, 16, 1
	v_bfe_u32 v46, v3, 16, 1
	v_bfe_u32 v60, v6, 16, 1
	v_bfe_u32 v61, v7, 16, 1
	v_add3_u32 v30, v57, v30, s4
	v_add3_u32 v28, v56, v28, s4
	v_add3_u32 v26, v49, v26, s4
	v_add3_u32 v24, v48, v24, s4
	v_bfe_u32 v36, v55, 16, 1
	v_bfe_u32 v38, v54, 16, 1
	v_bfe_u32 v40, v51, 16, 1
	v_bfe_u32 v42, v50, 16, 1
	v_add3_u32 v22, v52, v22, s4
	v_add3_u32 v20, v53, v20, s4
	v_add3_u32 v4, v58, v4, s4
	v_add3_u32 v0, v59, v0, s4
	v_add3_u32 v7, v7, v61, s4
	v_add3_u32 v6, v6, v60, s4
	v_add3_u32 v3, v3, v46, s4
	v_add3_u32 v2, v2, v44, s4
	v_lshrrev_b32_e32 v24, 16, v24
	v_lshrrev_b32_e32 v26, 16, v26
	v_lshrrev_b32_e32 v28, 16, v28
	v_lshrrev_b32_e32 v30, 16, v30
	v_add3_u32 v42, v50, v42, s4
	v_add3_u32 v40, v51, v40, s4
	v_add3_u32 v38, v54, v38, s4
	v_add3_u32 v36, v55, v36, s4
	v_lshrrev_b32_e32 v2, 16, v2
	v_lshrrev_b32_e32 v3, 16, v3
	v_lshrrev_b32_e32 v6, 16, v6
	v_lshrrev_b32_e32 v7, 16, v7
	v_and_or_b32 v51, v0, s1, v30
	v_and_or_b32 v50, v4, s1, v28
	v_and_or_b32 v49, v20, s1, v26
	v_and_or_b32 v48, v22, s1, v24
	v_and_or_b32 v55, v36, s1, v7
	v_and_or_b32 v54, v38, s1, v6
	v_and_or_b32 v53, v40, s1, v3
	v_and_or_b32 v52, v42, s1, v2
	global_store_dwordx4 v[16:17], v[48:51], off
	global_store_dwordx4 v[18:19], v[52:55], off offset:2048
	s_nop 1
	v_mov_b32_e32 v48, v224
	v_mov_b32_e32 v49, v225
	v_mov_b32_e32 v50, v226
	v_mov_b32_e32 v51, v227
	s_nop 0
	s_nop 1
	v_mov_b32_e32 v52, v228
	v_mov_b32_e32 v53, v229
	v_mov_b32_e32 v54, v230
	v_mov_b32_e32 v55, v231
	v_mov_b32_e32 v30, v35
	v_mov_b32_e32 v28, v37
	v_mov_b32_e32 v26, v33
	v_mov_b32_e32 v22, v41
	v_mov_b32_e32 v24, v45
	v_mov_b32_e32 v0, v47
	v_mov_b32_e32 v4, v39
	v_pk_mul_f32 v[2:3], v[32:33], v[30:31] op_sel_hi:[0,1]
	v_pk_mul_f32 v[6:7], v[32:33], v[28:29] op_sel_hi:[0,1]
	v_pk_mul_f32 v[26:27], v[32:33], v[26:27] op_sel_hi:[0,1]
	v_mov_b32_e32 v20, v43
	v_pk_mul_f32 v[24:25], v[32:33], v[24:25] op_sel_hi:[0,1]
	v_pk_mul_f32 v[22:23], v[34:35], v[22:23] op_sel_hi:[0,1]
	v_pk_mul_f32 v[4:5], v[34:35], v[4:5] op_sel_hi:[0,1]
	v_pk_mul_f32 v[0:1], v[34:35], v[0:1] op_sel_hi:[0,1]
	v_pk_mul_f32 v[20:21], v[34:35], v[20:21] op_sel_hi:[0,1]
	v_mov_b32_e32 v28, v48
	v_mov_b32_e32 v29, v50
	v_mov_b32_e32 v30, v52
	v_mov_b32_e32 v31, v54
	v_mov_b32_e32 v50, v49
	v_mov_b32_e32 v54, v53
	v_pk_mul_f32 v[2:3], v[2:3], v[28:29]
	v_pk_mul_f32 v[26:27], v[26:27], v[30:31]
	v_pk_mul_f32 v[6:7], v[6:7], v[50:51]
	v_pk_mul_f32 v[24:25], v[24:25], v[54:55]
	v_pk_mul_f32 v[22:23], v[22:23], v[28:29]
	v_pk_mul_f32 v[4:5], v[4:5], v[30:31]
	v_pk_mul_f32 v[0:1], v[0:1], v[54:55]
	v_bfe_u32 v32, v2, 16, 1
	v_bfe_u32 v33, v3, 16, 1
	v_bfe_u32 v34, v26, 16, 1
	v_bfe_u32 v35, v27, 16, 1
	v_pk_mul_f32 v[20:21], v[20:21], v[50:51]
	v_bfe_u32 v28, v25, 16, 1
	v_bfe_u32 v29, v24, 16, 1
	v_bfe_u32 v30, v7, 16, 1
	v_bfe_u32 v31, v6, 16, 1
	v_bfe_u32 v36, v1, 16, 1
	v_bfe_u32 v37, v0, 16, 1
	v_bfe_u32 v40, v22, 16, 1
	v_bfe_u32 v41, v23, 16, 1
	v_bfe_u32 v42, v4, 16, 1
	v_bfe_u32 v43, v5, 16, 1
	v_add3_u32 v27, v27, v35, s4
	v_add3_u32 v26, v26, v34, s4
	v_add3_u32 v3, v3, v33, s4
	v_add3_u32 v2, v2, v32, s4
	v_bfe_u32 v38, v21, 16, 1
	v_bfe_u32 v39, v20, 16, 1
	v_add3_u32 v6, v6, v31, s4
	v_add3_u32 v7, v7, v30, s4
	v_add3_u32 v24, v24, v29, s4
	v_add3_u32 v25, v25, v28, s4
	v_add3_u32 v28, v0, v37, s4
	v_add3_u32 v29, v1, v36, s4
	v_add3_u32 v0, v5, v43, s4
	v_add3_u32 v1, v4, v42, s4
	v_add3_u32 v4, v23, v41, s4
	v_add3_u32 v5, v22, v40, s4
	v_lshrrev_b32_e32 v22, 16, v2
	v_lshrrev_b32_e32 v23, 16, v3
	v_lshrrev_b32_e32 v2, 16, v26
	v_lshrrev_b32_e32 v3, 16, v27
	v_add3_u32 v20, v20, v39, s4
	v_add3_u32 v21, v21, v38, s4
	v_lshrrev_b32_e32 v26, 16, v5
	v_lshrrev_b32_e32 v4, 16, v4
	v_lshrrev_b32_e32 v5, 16, v1
	v_lshrrev_b32_e32 v27, 16, v0
	v_and_or_b32 v3, v25, s1, v3
	v_and_or_b32 v2, v24, s1, v2
	v_and_or_b32 v1, v7, s1, v23
	v_and_or_b32 v0, v6, s1, v22
	v_and_or_b32 v7, v29, s1, v27
	v_and_or_b32 v6, v28, s1, v5
	v_and_or_b32 v5, v21, s1, v4
	v_and_or_b32 v4, v20, s1, v26
	global_store_dwordx4 v[16:17], v[0:3], off offset:1024
	global_store_dwordx4 v[18:19], v[4:7], off offset:3072
	s_cbranch_scc0 .LBB0_1114

; #define LOCAL_IDS() int tid = threadIdx.x; asm volatile("" : "+v"(tid)); const int lane = tid & 63, wave = __builtin_amdgcn_readfirstlane(tid >> 6), gw = vcu * NWAVES + wave; (void)lane; (void)gw
; __device__ __forceinline__ void rms_rows2_b2f(const bf16* x0, const bf16* x1, const float* g, float* o0, float* o1, int lane) {
;     const v4u* xr0 = (const v4u*)x0 + lane; const v4u* xr1 = (const v4u*)x1 + lane; const f32x4* gr = (const f32x4*)g + 2 * lane;
;     v4u v[4], w[4]; float s = 0.f, t = 0.f;
; #pragma unroll
;     for (int j = 0; j < 4; ++j) { v[j] = xr0[64 * j]; w[j] = xr1[64 * j]; }
; #pragma unroll
;     for (int j = 0; j < 4; ++j) {
;         s += (bflo(v[j].x) * bflo(v[j].x) + bfhi(v[j].x) * bfhi(v[j].x)) + (bflo(v[j].y) * bflo(v[j].y) + bfhi(v[j].y) * bfhi(v[j].y)) + (bflo(v[j].z) * bflo(v[j].z) + bfhi(v[j].z) * bfhi(v[j].z)) + (bflo(v[j].w) * bflo(v[j].w) + bfhi(v[j].w) * bfhi(v[j].w));
;         t += (bflo(w[j].x) * bflo(w[j].x) + bfhi(w[j].x) * bfhi(w[j].x)) + (bflo(w[j].y) * bflo(w[j].y) + bfhi(w[j].y) * bfhi(w[j].y)) + (bflo(w[j].z) * bflo(w[j].z) + bfhi(w[j].z) * bfhi(w[j].z)) + (bflo(w[j].w) * bflo(w[j].w) + bfhi(w[j].w) * bfhi(w[j].w)); }
;     const float rs = 1.f / sqrtf(wave_sum(s, lane) * (1.f / D) + NORM_EPS), rt = 1.f / sqrtf(wave_sum(t, lane) * (1.f / D) + NORM_EPS);
;     f32x4* p0 = (f32x4*)o0 + 2 * lane; f32x4* p1 = (f32x4*)o1 + 2 * lane;
; #pragma unroll
;     for (int j = 0; j < 4; ++j) { const f32x4 ga = gr[128 * j], gb = gr[128 * j + 1];
;         p0[128 * j]     = (f32x4){bflo(v[j].x), bfhi(v[j].x), bflo(v[j].y), bfhi(v[j].y)} * rs * ga; p0[128 * j + 1] = (f32x4){bflo(v[j].z), bfhi(v[j].z), bflo(v[j].w), bfhi(v[j].w)} * rs * gb;
;         p1[128 * j]     = (f32x4){bflo(w[j].x), bfhi(w[j].x), bflo(w[j].y), bfhi(w[j].y)} * rt * ga; p1[128 * j + 1] = (f32x4){bflo(w[j].z), bfhi(w[j].z), bflo(w[j].w), bfhi(w[j].w)} * rt * gb; }
; __global__ void __launch_bounds__(NWAVES * 64, 2) mega_fwd(Args args) {
;     ...
;     { LOCAL_IDS(); for (int m = gw; m < M / 2; m += NGW) rms_rows2_b2f(XN + (size_t)m * D, XN + (size_t)(m + M / 2) * D, ln_f, out + (size_t)m * D, out + (size_t)(m + M / 2) * D, lane); }
.LBB0_1471:
	s_or_b64 exec, exec, s[2:3]
	s_waitcnt lgkmcnt(0)
	s_barrier
	v_readlane_b32 s9, v255, 1
	v_readfirstlane_b32 s0, v248
	s_ashr_i32 s0, s0, 6
	s_add_i32 s16, s0, s9
	s_cmpk_gt_i32 s16, 0x1fff
	s_cbranch_scc1 .LBB0_1474
	v_and_b32_e32 v0, 63, v248
	v_lshlrev_b32_e32 v8, 5, v0
	v_mov_b32_e32 v9, 0
	v_lshl_add_u64 v[10:11], s[30:31], 0, v[8:9]
	s_mov_b64 s[2:3], 0x1000
	v_lshl_add_u64 v[12:13], v[10:11], 0, s[2:3]
	s_mov_b64 s[2:3], 0x1800
	v_lshl_add_u64 v[14:15], v[10:11], 0, s[2:3]
	s_add_i32 s2, s16, 0x2000
	s_ashr_i32 s3, s2, 31
	s_lshl_b64 s[4:5], s[2:3], 13
	s_add_u32 s4, s52, s4
	s_addc_u32 s5, s53, s5
	s_ashr_i32 s35, s34, 31
	s_lshl_b64 s[6:7], s[34:35], 13
	s_ashr_i32 s1, s0, 31
	s_ashr_i32 s8, s9, 31
	s_add_u32 s0, s0, s9
	s_addc_u32 s1, s1, s8
	s_lshl_b64 s[8:9], s[0:1], 12
	s_add_u32 s8, s54, s8
	s_addc_u32 s9, s55, s9
	s_add_u32 s8, s8, 0xc000800
	s_addc_u32 s9, s9, 0
	s_lshl_b64 s[10:11], s[34:35], 12
	s_lshl_b64 s[0:1], s[0:1], 13
	s_add_u32 s12, s52, s0
	s_addc_u32 s13, s53, s1
	s_lshl_b64 s[0:1], s[2:3], 12
	v_lshlrev_b32_e32 v1, 2, v0
	s_add_u32 s14, s54, s0
	v_xor_b32_e32 v80, 4, v1
	v_xor_b32_e32 v81, 8, v1
	v_xor_b32_e32 v82, 16, v1
	v_xor_b32_e32 v83, 32, v1
	v_xor_b32_e32 v84, 64, v1
	v_xor_b32_e32 v85, 0x80, v1
	v_lshlrev_b32_e32 v16, 4, v0
	v_mov_b32_e32 v17, v9
	s_addc_u32 s15, s55, s1
	v_mov_b32_e32 v86, 0x358637bd
	s_mov_b32 s17, 0xf800000
	v_mov_b32_e32 v87, 0x260
	s_movk_i32 s18, 0x1000
	global_load_dwordx4 v[200:203], v[10:11], off offset:16
	global_load_dwordx4 v[204:207], v[10:11], off
	global_load_dwordx4 v[208:211], v[10:11], off offset:2048
	global_load_dwordx4 v[212:215], v[10:11], off offset:2064
	global_load_dwordx4 v[216:219], v[12:13], off
	global_load_dwordx4 v[220:223], v[12:13], off offset:16
	global_load_dwordx4 v[224:227], v[14:15], off
	global_load_dwordx4 v[228:231], v[14:15], off offset:16
	s_waitcnt vmcnt(0)
.LBB0_1473:
	v_lshl_add_u64 v[18:19], s[14:15], 0, v[16:17]
	v_lshl_add_u64 v[20:21], s[8:9], 0, v[16:17]
	s_nop 1
	v_mov_b32_e32 v0, v200
	v_mov_b32_e32 v1, v201
	v_mov_b32_e32 v2, v202
	v_mov_b32_e32 v3, v203
	s_nop 1
	v_mov_b32_e32 v4, v204
	v_mov_b32_e32 v5, v205
	v_mov_b32_e32 v6, v206
	v_mov_b32_e32 v7, v207
	global_load_dwordx4 v[22:25], v[20:21], off offset:-2048
	global_load_dwordx4 v[26:29], v[20:21], off offset:-1024
	global_load_dwordx4 v[30:33], v[20:21], off
	global_load_dwordx4 v[34:37], v[20:21], off offset:1024
	v_add_co_u32_e32 v18, vcc, 0xc000000, v18
	v_lshl_add_u64 v[52:53], s[12:13], 0, v[8:9]
	s_nop 0
	v_addc_co_u32_e32 v19, vcc, 0, v19, vcc
	global_load_dwordx4 v[38:41], v[18:19], off
	global_load_dwordx4 v[54:57], v[18:19], off offset:1024
	global_load_dwordx4 v[88:91], v[18:19], off offset:2048
	global_load_dwordx4 v[92:95], v[18:19], off offset:3072
	v_lshl_add_u64 v[44:45], s[4:5], 0, v[8:9]
	s_add_i32 s16, s16, s34
	s_add_u32 s4, s4, s6
	s_addc_u32 s5, s5, s7
	s_add_u32 s8, s8, s10
	s_addc_u32 s9, s9, s11
	s_add_u32 s12, s12, s6
	s_addc_u32 s13, s13, s7
	s_add_u32 s14, s14, s10
	s_addc_u32 s15, s15, s11
	s_cmpk_gt_i32 s16, 0x1fff
	s_waitcnt vmcnt(7)
	v_and_b32_e32 v75, 0xffff0000, v23
	v_and_b32_e32 v47, 0xffff0000, v22
	v_and_b32_e32 v46, 0xffff0000, v24
	v_lshlrev_b32_e32 v74, 16, v23
	v_lshlrev_b32_e32 v77, 16, v22
	v_lshlrev_b32_e32 v76, 16, v24
	s_waitcnt vmcnt(6)
	v_lshlrev_b32_e32 v58, 16, v26
	v_and_b32_e32 v63, 0xffff0000, v27
	v_and_b32_e32 v62, 0xffff0000, v26
	v_lshlrev_b32_e32 v60, 16, v28
	v_and_b32_e32 v65, 0xffff0000, v29
	v_and_b32_e32 v64, 0xffff0000, v28
	s_waitcnt vmcnt(5)
	v_lshlrev_b32_e32 v48, 16, v30
	v_and_b32_e32 v49, 0xffff0000, v30
	v_lshlrev_b32_e32 v50, 16, v31
	v_and_b32_e32 v51, 0xffff0000, v31
	s_waitcnt vmcnt(4)
	v_and_b32_e32 v21, 0xffff0000, v37
	v_lshlrev_b32_e32 v26, 16, v32
	v_and_b32_e32 v23, 0xffff0000, v34
	v_and_b32_e32 v22, 0xffff0000, v32
	v_pk_mov_b32 v[30:31], v[32:33], v[36:37] op_sel:[1,0]
	v_lshlrev_b32_e32 v28, 16, v33
	v_mul_f32_e32 v20, v75, v75
	v_pk_mul_f32 v[32:33], v[46:47], v[46:47]
	v_lshlrev_b32_e32 v78, 16, v25
	v_and_b32_e32 v79, 0xffff0000, v25
	v_lshlrev_b32_e32 v59, 16, v27
	v_lshlrev_b32_e32 v61, 16, v29
	v_lshlrev_b32_e32 v18, 16, v35
	v_and_b32_e32 v19, 0xffff0000, v35
	v_lshlrev_b32_e32 v25, 16, v37
	v_lshlrev_b32_e32 v27, 16, v34
	v_lshlrev_b32_e32 v29, 16, v36
	v_pk_mul_f32 v[34:35], v[62:63], v[62:63]
	v_pk_mul_f32 v[36:37], v[64:65], v[64:65]
	v_pk_mul_f32 v[42:43], v[22:23], v[22:23]
	v_pk_fma_f32 v[102:103], v[74:75], v[74:75], v[20:21] op_sel_hi:[1,1,0]
	v_pk_fma_f32 v[104:105], v[76:77], v[76:77], v[32:33]
	v_mul_f32_e32 v24, v49, v49
	v_mul_f32_e32 v96, v51, v51
	v_mul_f32_e32 v98, v79, v79
	v_mov_b32_e32 v97, v25
	s_waitcnt vmcnt(3)
	v_and_b32_e32 v107, 0xffff0000, v39
	v_lshlrev_b32_e32 v108, 16, v40
	v_and_b32_e32 v111, 0xffff0000, v38
	v_and_b32_e32 v110, 0xffff0000, v40
	v_lshlrev_b32_e32 v112, 16, v41
	v_and_b32_e32 v113, 0xffff0000, v41
	v_pk_fma_f32 v[114:115], v[58:59], v[58:59], v[34:35]
	v_pk_fma_f32 v[116:117], v[60:61], v[60:61], v[36:37]
	s_waitcnt vmcnt(2)
	v_lshlrev_b32_e32 v67, 16, v55
	v_lshlrev_b32_e32 v66, 16, v54
	v_and_b32_e32 v71, 0xffff0000, v55
	v_and_b32_e32 v70, 0xffff0000, v54
	v_lshlrev_b32_e32 v69, 16, v57
	v_lshlrev_b32_e32 v68, 16, v56
	v_and_b32_e32 v73, 0xffff0000, v57
	v_and_b32_e32 v72, 0xffff0000, v56
	s_waitcnt vmcnt(1)
	v_lshlrev_b32_e32 v54, 16, v88
	v_and_b32_e32 v55, 0xffff0000, v88
	v_lshlrev_b32_e32 v56, 16, v89
	v_and_b32_e32 v57, 0xffff0000, v89
	v_pk_fma_f32 v[88:89], v[26:27], v[26:27], v[42:43]
	s_waitcnt vmcnt(0)
; __device__ __forceinline__ void rms_rows2_b2f(const bf16* x0, const bf16* x1, const float* g, float* o0, float* o1, int lane) {
;     ...
;     for (int j = 0; j < 4; ++j) { v[j] = xr0[64 * j]; w[j] = xr1[64 * j]; }
; #pragma unroll
;     for (int j = 0; j < 4; ++j) {
;         s += (bflo(v[j].x) * bflo(v[j].x) + bfhi(v[j].x) * bfhi(v[j].x)) + (bflo(v[j].y) * bflo(v[j].y) + bfhi(v[j].y) * bfhi(v[j].y)) + (bflo(v[j].z) * bflo(v[j].z) + bfhi(v[j].z) * bfhi(v[j].z)) + (bflo(v[j].w) * bflo(v[j].w) + bfhi(v[j].w) * bfhi(v[j].w));
;         t += (bflo(w[j].x) * bflo(w[j].x) + bfhi(w[j].x) * bfhi(w[j].x)) + (bflo(w[j].y) * bflo(w[j].y) + bfhi(w[j].y) * bfhi(w[j].y)) + (bflo(w[j].z) * bflo(w[j].z) + bfhi(w[j].z) * bfhi(w[j].z)) + (bflo(w[j].w) * bflo(w[j].w) + bfhi(w[j].w) * bfhi(w[j].w)); }
;     const float rs = 1.f / sqrtf(wave_sum(s, lane) * (1.f / D) + NORM_EPS), rt = 1.f / sqrtf(wave_sum(t, lane) * (1.f / D) + NORM_EPS);
	v_lshlrev_b32_e32 v32, 16, v93
	v_and_b32_e32 v33, 0xffff0000, v93
	v_lshlrev_b32_e32 v41, 16, v92
	v_lshlrev_b32_e32 v40, 16, v90
	v_and_b32_e32 v37, 0xffff0000, v92
	v_and_b32_e32 v36, 0xffff0000, v90
	v_pk_mov_b32 v[92:93], v[90:91], v[94:95] op_sel:[1,0]
	v_lshlrev_b32_e32 v42, 16, v91
	v_pk_add_f32 v[90:91], v[104:105], v[102:103] op_sel:[1,0] op_sel_hi:[0,1]
	v_mul_f32_e32 v126, v18, v18
	v_mul_f32_e32 v127, v19, v19
	v_lshlrev_b32_e32 v106, 16, v39
	v_lshlrev_b32_e32 v109, 16, v38
	v_pk_fma_f32 v[118:119], v[48:49], v[48:49], v[24:25] op_sel_hi:[1,1,0]
	v_pk_fma_f32 v[120:121], v[50:51], v[50:51], v[96:97] op_sel_hi:[1,1,0]
	v_pk_fma_f32 v[98:99], v[78:79], v[78:79], v[98:99] op_sel_hi:[1,1,0]
	v_lshlrev_b32_e32 v39, 16, v95
	v_and_b32_e32 v35, 0xffff0000, v95
	v_lshlrev_b32_e32 v43, 16, v94
	v_mul_f32_e32 v20, v107, v107
	v_pk_mul_f32 v[94:95], v[110:111], v[110:111]
	v_pk_add_f32 v[102:103], v[114:115], v[114:115] op_sel:[0,1] op_sel_hi:[1,0]
	v_pk_add_f32 v[90:91], v[104:105], v[90:91]
	v_and_b32_e32 v31, 0xffff0000, v31
	v_and_b32_e32 v30, 0xffff0000, v30
	v_pk_mul_f32 v[114:115], v[70:71], v[70:71]
	v_mov_b32_e32 v119, v126
	v_mov_b32_e32 v121, v127
	v_mov_b32_e32 v24, v98
	v_pk_fma_f32 v[104:105], v[106:107], v[106:107], v[20:21] op_sel_hi:[1,1,0]
	v_pk_fma_f32 v[94:95], v[108:109], v[108:109], v[94:95]
	v_pk_add_f32 v[102:103], v[116:117], v[102:103]
	v_mov_b32_e32 v96, v90
	v_mul_f32_e32 v136, v21, v21
	v_mov_b32_e32 v100, v77
	v_mov_b32_e32 v101, v47
	v_pk_mul_f32 v[122:123], v[30:31], v[30:31]
	v_mov_b32_e32 v77, v46
	v_pk_mul_f32 v[124:125], v[72:73], v[72:73]
	v_pk_mul_f32 v[126:127], v[36:37], v[36:37]
	v_mul_f32_e32 v34, v55, v55
	v_mul_f32_e32 v38, v57, v57
	v_and_b32_e32 v47, 0xffff0000, v93
	v_and_b32_e32 v46, 0xffff0000, v92
	v_mul_f32_e32 v92, v113, v113
	v_mov_b32_e32 v93, v39
	v_pk_fma_f32 v[114:115], v[66:67], v[66:67], v[114:115]
	v_pk_add_f32 v[118:119], v[118:119], v[120:121]
	v_pk_add_f32 v[104:105], v[94:95], v[104:105] op_sel:[1,0] op_sel_hi:[0,1]
	v_pk_add_f32 v[90:91], v[98:99], v[90:91]
	v_pk_add_f32 v[98:99], v[116:117], v[102:103] op_sel:[1,0] op_sel_hi:[0,1]
	v_pk_mul_f32 v[96:97], v[24:25], v[96:97]
	v_pk_fma_f32 v[122:123], v[28:29], v[28:29], v[122:123]
	v_mul_f32_e32 v137, v32, v32
	v_mul_f32_e32 v138, v33, v33
	v_mov_b32_e32 v128, v109
	v_mov_b32_e32 v129, v111
	v_pk_fma_f32 v[124:125], v[68:69], v[68:69], v[124:125]
	v_pk_fma_f32 v[120:121], v[40:41], v[40:41], v[126:127]
	v_pk_fma_f32 v[126:127], v[54:55], v[54:55], v[34:35] op_sel_hi:[1,1,0]
	v_pk_fma_f32 v[130:131], v[56:57], v[56:57], v[38:39] op_sel_hi:[1,1,0]
	v_pk_fma_f32 v[134:135], v[112:113], v[112:113], v[92:93] op_sel_hi:[1,1,0]
	v_mov_b32_e32 v109, v110
	v_pk_add_f32 v[110:111], v[114:115], v[114:115] op_sel:[0,1] op_sel_hi:[1,0]
	v_pk_add_f32 v[88:89], v[88:89], v[118:119]
	v_pk_add_f32 v[94:95], v[94:95], v[104:105]
	v_mov_b32_e32 v99, v136
	v_mov_b32_e32 v91, v97
	v_mov_b32_e32 v127, v137
	v_mov_b32_e32 v131, v138
	v_mov_b32_e32 v38, v134
	v_pk_add_f32 v[104:105], v[124:125], v[110:111]
	v_pk_add_f32 v[88:89], v[122:123], v[88:89]
	v_mov_b32_e32 v92, v94
	v_pk_add_f32 v[90:91], v[90:91], v[98:99]
	v_mul_f32_e32 v139, v35, v35
	v_pk_mul_f32 v[132:133], v[46:47], v[46:47]
	v_pk_add_f32 v[110:111], v[126:127], v[130:131]
	v_pk_add_f32 v[94:95], v[134:135], v[94:95]
	v_pk_add_f32 v[104:105], v[124:125], v[104:105] op_sel:[1,0] op_sel_hi:[0,1]
	v_pk_mul_f32 v[92:93], v[38:39], v[92:93]
	v_pk_add_f32 v[88:89], v[90:91], v[88:89]
	v_pk_fma_f32 v[102:103], v[42:43], v[42:43], v[132:133]
	v_pk_add_f32 v[96:97], v[120:121], v[110:111]
	v_mov_b32_e32 v105, v139
	v_mov_b32_e32 v95, v93
	v_add_f32_e32 v20, v88, v89
	v_pk_add_f32 v[96:97], v[102:103], v[96:97]
	v_pk_add_f32 v[88:89], v[94:95], v[104:105]
	ds_bpermute_b32 v24, v80, v20
	v_pk_add_f32 v[88:89], v[88:89], v[96:97]
	s_waitcnt lgkmcnt(0)
	v_add_f32_e32 v20, v20, v24
	v_add_f32_e32 v34, v88, v89
	ds_bpermute_b32 v38, v80, v34
	ds_bpermute_b32 v24, v81, v20
	s_waitcnt lgkmcnt(1)
	v_add_f32_e32 v34, v34, v38
	ds_bpermute_b32 v38, v81, v34
	s_waitcnt lgkmcnt(1)
	v_add_f32_e32 v20, v20, v24
	ds_bpermute_b32 v24, v82, v20
	s_waitcnt lgkmcnt(1)
	v_add_f32_e32 v34, v34, v38
	ds_bpermute_b32 v38, v82, v34
	s_waitcnt lgkmcnt(1)
	v_add_f32_e32 v20, v20, v24
	ds_bpermute_b32 v24, v83, v20
	s_waitcnt lgkmcnt(1)
	v_add_f32_e32 v34, v34, v38
	ds_bpermute_b32 v38, v83, v34
	s_waitcnt lgkmcnt(1)
	v_add_f32_e32 v20, v20, v24
	ds_bpermute_b32 v24, v84, v20
	s_waitcnt lgkmcnt(1)
	v_add_f32_e32 v34, v34, v38
	ds_bpermute_b32 v38, v84, v34
	s_waitcnt lgkmcnt(1)
	v_add_f32_e32 v20, v20, v24
	ds_bpermute_b32 v24, v85, v20
	s_waitcnt lgkmcnt(1)
	v_add_f32_e32 v34, v34, v38
	ds_bpermute_b32 v38, v85, v34
	s_waitcnt lgkmcnt(1)
	v_add_f32_e32 v20, v20, v24
	v_fmamk_f32 v20, v20, 0x3a000000, v86
	v_mul_f32_e32 v24, 0x4f800000, v20
	v_cmp_gt_f32_e32 vcc, s17, v20
	s_waitcnt lgkmcnt(0)
; __device__ __forceinline__ void rms_rows2_b2f(const bf16* x0, const bf16* x1, const float* g, float* o0, float* o1, int lane) {
;     ...
;     const float rs = 1.f / sqrtf(wave_sum(s, lane) * (1.f / D) + NORM_EPS), rt = 1.f / sqrtf(wave_sum(t, lane) * (1.f / D) + NORM_EPS);
;     f32x4* p0 = (f32x4*)o0 + 2 * lane; f32x4* p1 = (f32x4*)o1 + 2 * lane;
; #pragma unroll
;     for (int j = 0; j < 4; ++j) { const f32x4 ga = gr[128 * j], gb = gr[128 * j + 1];
;         p0[128 * j]     = (f32x4){bflo(v[j].x), bfhi(v[j].x), bflo(v[j].y), bfhi(v[j].y)} * rs * ga; p0[128 * j + 1] = (f32x4){bflo(v[j].z), bfhi(v[j].z), bflo(v[j].w), bfhi(v[j].w)} * rs * gb;
;         p1[128 * j]     = (f32x4){bflo(w[j].x), bfhi(w[j].x), bflo(w[j].y), bfhi(w[j].y)} * rt * ga; p1[128 * j + 1] = (f32x4){bflo(w[j].z), bfhi(w[j].z), bflo(w[j].w), bfhi(w[j].w)} * rt * gb; }
	v_add_f32_e32 v34, v34, v38
	v_cndmask_b32_e32 v20, v20, v24, vcc
	v_fmamk_f32 v24, v34, 0x3a000000, v86
	v_sqrt_f32_e32 v34, v20
	v_mul_f32_e32 v38, 0x4f800000, v24
	v_cmp_gt_f32_e64 s[0:1], s17, v24
	v_add_u32_e32 v88, -1, v34
	s_nop 0
	v_cndmask_b32_e64 v24, v24, v38, s[0:1]
	v_sqrt_f32_e32 v38, v24
	v_add_u32_e32 v89, 1, v34
	v_fma_f32 v90, -v88, v34, v20
	v_fma_f32 v91, -v89, v34, v20
	v_cmp_ge_f32_e64 s[2:3], 0, v90
	v_add_u32_e32 v90, 1, v38
	s_nop 0
	v_cndmask_b32_e64 v34, v34, v88, s[2:3]
	v_add_u32_e32 v88, -1, v38
	v_cmp_lt_f32_e64 s[2:3], 0, v91
	v_fma_f32 v91, -v90, v38, v24
	s_nop 0
	v_cndmask_b32_e64 v34, v34, v89, s[2:3]
	v_fma_f32 v89, -v88, v38, v24
	v_cmp_ge_f32_e64 s[2:3], 0, v89
	v_mul_f32_e32 v92, 0x37800000, v34
	v_cndmask_b32_e32 v34, v34, v92, vcc
	v_cndmask_b32_e64 v38, v38, v88, s[2:3]
	v_cmp_lt_f32_e64 s[2:3], 0, v91
	v_cmp_class_f32_e32 vcc, v20, v87
	s_nop 0
	v_cndmask_b32_e64 v38, v38, v90, s[2:3]
	v_cndmask_b32_e32 v20, v34, v20, vcc
	v_mul_f32_e32 v34, 0x37800000, v38
	v_div_scale_f32 v88, s[2:3], v20, v20, 1.0
	v_cndmask_b32_e64 v34, v38, v34, s[0:1]
	v_cmp_class_f32_e64 s[0:1], v24, v87
	v_rcp_f32_e32 v38, v88
	v_div_scale_f32 v89, vcc, 1.0, v20, 1.0
	v_cndmask_b32_e64 v34, v34, v24, s[0:1]
	v_div_scale_f32 v90, s[0:1], v34, v34, 1.0
	v_rcp_f32_e32 v92, v90
	v_fma_f32 v24, -v88, v38, 1.0
	v_fmac_f32_e32 v38, v24, v38
	v_mul_f32_e32 v24, v89, v38
	v_fma_f32 v93, -v90, v92, 1.0
	v_div_scale_f32 v91, s[0:1], 1.0, v34, 1.0
	v_fma_f32 v94, -v88, v24, v89
	v_fmac_f32_e32 v92, v93, v92
	v_fmac_f32_e32 v24, v94, v38
	v_mul_f32_e32 v93, v91, v92
	v_fma_f32 v88, -v88, v24, v89
	v_fma_f32 v89, -v90, v93, v91
	v_div_fmas_f32 v24, v88, v38, v24
	v_fmac_f32_e32 v93, v89, v92
	v_div_fixup_f32 v24, v24, v20, 1.0
	v_fma_f32 v20, -v90, v93, v91
	s_mov_b64 vcc, s[0:1]
	v_div_fmas_f32 v20, v20, v92, v93
	v_pk_mul_f32 v[88:89], v[24:25], v[100:101] op_sel_hi:[0,1]
	v_pk_mul_f32 v[74:75], v[24:25], v[74:75] op_sel_hi:[0,1]
	v_pk_mul_f32 v[92:93], v[24:25], v[76:77] op_sel_hi:[0,1]
	v_pk_mul_f32 v[78:79], v[24:25], v[78:79] op_sel_hi:[0,1]
	v_div_fixup_f32 v38, v20, v34, 1.0
	v_pk_mul_f32 v[76:77], v[6:7], v[74:75]
	v_pk_mul_f32 v[74:75], v[4:5], v[88:89]
	v_pk_mul_f32 v[90:91], v[2:3], v[78:79]
	v_pk_mul_f32 v[88:89], v[0:1], v[92:93]
	global_store_dwordx4 v[52:53], v[74:77], off
	global_store_dwordx4 v[52:53], v[88:91], off offset:16
	v_pk_mul_f32 v[78:79], v[38:39], v[108:109] op_sel_hi:[0,1]
	v_pk_mul_f32 v[74:75], v[38:39], v[128:129] op_sel_hi:[0,1]
	v_pk_mul_f32 v[76:77], v[38:39], v[106:107] op_sel_hi:[0,1]
	v_pk_mul_f32 v[88:89], v[38:39], v[112:113] op_sel_hi:[0,1]
	v_pk_mul_f32 v[6:7], v[6:7], v[76:77]
	v_pk_mul_f32 v[4:5], v[4:5], v[74:75]
	v_pk_mul_f32 v[2:3], v[2:3], v[88:89]
	v_pk_mul_f32 v[0:1], v[0:1], v[78:79]
	global_store_dwordx4 v[44:45], v[4:7], off
	global_store_dwordx4 v[44:45], v[0:3], off offset:16
	s_nop 1
	v_mov_b32_e32 v0, v208
	v_mov_b32_e32 v1, v209
	v_mov_b32_e32 v2, v210
	v_mov_b32_e32 v3, v211
	s_nop 0
	s_nop 1
	v_mov_b32_e32 v4, v212
	v_mov_b32_e32 v5, v213
	v_mov_b32_e32 v6, v214
	v_mov_b32_e32 v7, v215
	v_mov_b32_e32 v74, v59
	v_mov_b32_e32 v75, v63
	v_mov_b32_e32 v59, v62
	v_mov_b32_e32 v76, v61
	v_mov_b32_e32 v77, v65
	v_mov_b32_e32 v61, v64
	v_mov_b32_e32 v62, v67
	v_mov_b32_e32 v63, v71
	v_mov_b32_e32 v64, v69
	v_mov_b32_e32 v65, v73
	v_mov_b32_e32 v67, v70
	v_mov_b32_e32 v69, v72
	v_pk_mul_f32 v[70:71], v[24:25], v[74:75] op_sel_hi:[0,1]
	v_pk_mul_f32 v[58:59], v[24:25], v[58:59] op_sel_hi:[0,1]
	v_pk_mul_f32 v[72:73], v[24:25], v[76:77] op_sel_hi:[0,1]
	v_pk_mul_f32 v[74:75], v[24:25], v[60:61] op_sel_hi:[0,1]
	v_pk_mul_f32 v[76:77], v[38:39], v[62:63] op_sel_hi:[0,1]
; __device__ __forceinline__ void rms_rows2_b2f(const bf16* x0, const bf16* x1, const float* g, float* o0, float* o1, int lane) {
;     ...
;     for (int j = 0; j < 4; ++j) { const f32x4 ga = gr[128 * j], gb = gr[128 * j + 1];
;         p0[128 * j]     = (f32x4){bflo(v[j].x), bfhi(v[j].x), bflo(v[j].y), bfhi(v[j].y)} * rs * ga; p0[128 * j + 1] = (f32x4){bflo(v[j].z), bfhi(v[j].z), bflo(v[j].w), bfhi(v[j].w)} * rs * gb;
;         p1[128 * j]     = (f32x4){bflo(w[j].x), bfhi(w[j].x), bflo(w[j].y), bfhi(w[j].y)} * rt * ga; p1[128 * j + 1] = (f32x4){bflo(w[j].z), bfhi(w[j].z), bflo(w[j].w), bfhi(w[j].w)} * rt * gb; }
	v_pk_mul_f32 v[66:67], v[38:39], v[66:67] op_sel_hi:[0,1]
	v_pk_mul_f32 v[78:79], v[38:39], v[64:65] op_sel_hi:[0,1]
	v_pk_mul_f32 v[68:69], v[38:39], v[68:69] op_sel_hi:[0,1]
	v_pk_mul_f32 v[50:51], v[24:25], v[50:51] op_sel_hi:[0,1]
	v_pk_mul_f32 v[48:49], v[24:25], v[48:49] op_sel_hi:[0,1]
	v_pk_mul_f32 v[56:57], v[38:39], v[56:57] op_sel_hi:[0,1]
	v_mov_b32_e32 v20, v25
	v_mov_b32_e32 v34, v39
	v_pk_mul_f32 v[34:35], v[38:39], v[34:35] op_sel_hi:[0,1]
	v_pk_mul_f32 v[58:59], v[0:1], v[58:59]
	v_pk_mul_f32 v[60:61], v[2:3], v[70:71]
	v_pk_mul_f32 v[62:63], v[4:5], v[74:75]
	v_pk_mul_f32 v[64:65], v[6:7], v[72:73]
	v_pk_mul_f32 v[0:1], v[0:1], v[66:67]
	v_pk_mul_f32 v[2:3], v[2:3], v[76:77]
	v_pk_mul_f32 v[4:5], v[4:5], v[68:69]
	v_pk_mul_f32 v[6:7], v[6:7], v[78:79]
	global_store_dwordx4 v[52:53], v[58:61], off offset:2048
	global_store_dwordx4 v[52:53], v[62:65], off offset:2064
	global_store_dwordx4 v[44:45], v[0:3], off offset:2048
	global_store_dwordx4 v[44:45], v[4:7], off offset:2064
	s_nop 1
	v_mov_b32_e32 v0, v216
	v_mov_b32_e32 v1, v217
	v_mov_b32_e32 v2, v218
	v_mov_b32_e32 v3, v219
	s_nop 0
	s_nop 1
	v_mov_b32_e32 v4, v220
	v_mov_b32_e32 v5, v221
	v_mov_b32_e32 v6, v222
	v_mov_b32_e32 v7, v223
	v_add_co_u32_e32 v58, vcc, s18, v52
	v_mov_b32_e32 v52, v28
	s_nop 0
	v_addc_co_u32_e32 v59, vcc, 0, v53, vcc
	v_mov_b32_e32 v60, v26
	v_mov_b32_e32 v61, v22
	v_mov_b32_e32 v53, v30
	v_mov_b32_e32 v62, v42
	v_mov_b32_e32 v64, v40
	v_mov_b32_e32 v65, v36
	v_mov_b32_e32 v63, v46
	v_add_co_u32_e32 v44, vcc, s18, v44
	v_pk_mul_f32 v[66:67], v[24:25], v[52:53] op_sel_hi:[0,1]
	v_pk_mul_f32 v[52:53], v[24:25], v[60:61] op_sel_hi:[0,1]
	v_pk_mul_f32 v[60:61], v[38:39], v[54:55] op_sel_hi:[0,1]
	v_pk_mul_f32 v[62:63], v[38:39], v[62:63] op_sel_hi:[0,1]
	v_pk_mul_f32 v[64:65], v[38:39], v[64:65] op_sel_hi:[0,1]
	v_addc_co_u32_e32 v45, vcc, 0, v45, vcc
	v_mov_b32_e32 v22, v27
	v_mov_b32_e32 v30, v29
	v_mov_b32_e32 v36, v41
	v_mov_b32_e32 v46, v43
	v_pk_mul_f32 v[26:27], v[24:25], v[18:19] op_sel_hi:[0,1]
	v_pk_mul_f32 v[18:19], v[24:25], v[22:23] op_sel_hi:[0,1]
	v_pk_mul_f32 v[28:29], v[24:25], v[20:21] op_sel_hi:[0,1]
	v_pk_mul_f32 v[22:23], v[24:25], v[30:31] op_sel_hi:[0,1]
	v_pk_mul_f32 v[30:31], v[38:39], v[32:33] op_sel_hi:[0,1]
	v_pk_mul_f32 v[32:33], v[38:39], v[36:37] op_sel_hi:[0,1]
	v_pk_mul_f32 v[36:37], v[38:39], v[46:47] op_sel_hi:[0,1]
	v_pk_mul_f32 v[48:49], v[48:49], v[0:1]
	v_pk_mul_f32 v[50:51], v[50:51], v[2:3]
	v_pk_mul_f32 v[52:53], v[52:53], v[4:5]
	v_pk_mul_f32 v[54:55], v[66:67], v[6:7]
	v_pk_mul_f32 v[0:1], v[60:61], v[0:1]
	v_pk_mul_f32 v[2:3], v[56:57], v[2:3]
	v_pk_mul_f32 v[4:5], v[64:65], v[4:5]
	v_pk_mul_f32 v[6:7], v[62:63], v[6:7]
	global_store_dwordx4 v[58:59], v[48:51], off
	global_store_dwordx4 v[58:59], v[52:55], off offset:16
	global_store_dwordx4 v[44:45], v[0:3], off
	global_store_dwordx4 v[44:45], v[4:7], off offset:16
	s_nop 1
	v_mov_b32_e32 v0, v224
	v_mov_b32_e32 v1, v225
	v_mov_b32_e32 v2, v226
	v_mov_b32_e32 v3, v227
	s_nop 0
	s_nop 1
	v_mov_b32_e32 v4, v228
	v_mov_b32_e32 v5, v229
	v_mov_b32_e32 v6, v230
	v_mov_b32_e32 v7, v231
	v_pk_mul_f32 v[18:19], v[18:19], v[0:1]
	v_pk_mul_f32 v[20:21], v[26:27], v[2:3]
	v_pk_mul_f32 v[22:23], v[22:23], v[4:5]
	v_pk_mul_f32 v[24:25], v[28:29], v[6:7]
	v_pk_mul_f32 v[0:1], v[32:33], v[0:1]
	v_pk_mul_f32 v[2:3], v[30:31], v[2:3]
	v_pk_mul_f32 v[4:5], v[36:37], v[4:5]
	v_pk_mul_f32 v[6:7], v[34:35], v[6:7]
	global_store_dwordx4 v[58:59], v[18:21], off offset:2048
	global_store_dwordx4 v[58:59], v[22:25], off offset:2064
	global_store_dwordx4 v[44:45], v[0:3], off offset:2048
	global_store_dwordx4 v[44:45], v[4:7], off offset:2064
	s_cbranch_scc0 .LBB0_1473
